# GEMM unit loop (6 instances): the trailing half's per-unit offset barrier is taken after the unit-scheduler header, so it computes the next unit's coordinates while waiting for the leading half
# baseline (speedup 1.0000x reference)
.LBB0_353:
	s_lshl_b64 s[2:3], s[14:15], 1
	v_readlane_b32 s20, v253, 52
	v_readlane_b32 s21, v253, 53
	s_add_u32 s20, s20, s2
	s_addc_u32 s21, s21, s3
	s_and_b64 s[2:3], s[18:19], exec
	s_cselect_b32 s11, s21, s27
	s_cselect_b32 s13, s20, s26
	s_lshl_b64 s[2:3], s[16:17], 1
	s_add_u32 s22, s48, s2
	s_addc_u32 s23, s49, s3
	s_and_b64 s[2:3], s[18:19], exec
	s_cselect_b32 s44, s23, s29
	s_cselect_b32 s45, s22, s28
	s_add_u32 s26, s26, 0x40080
	s_addc_u32 s27, s27, 0
	s_add_u32 s46, s28, 0x100
	s_addc_u32 s47, s29, 0
	s_mov_b32 s52, -2
	s_cmp_lt_u32 s37, 2
	s_cbranch_scc1 .Lz1s354
	s_andn2_b64 vcc, exec, s[0:1]
	s_cbranch_vccnz .Lz1s354
	s_barrier
.Lz1s354:
.Lpk354_peel:
	ds_read_b128 v[166:169], v139
	ds_read_b128 v[170:173], v139 offset:1024
	ds_read_b128 v[178:181], v139 offset:2048
	ds_read_b128 v[182:185], v139 offset:3072
	ds_read_b128 v[186:189], v164
	ds_read_b128 v[190:193], v164 offset:1024
	ds_read_b128 v[194:197], v164 offset:2048
	ds_read_b128 v[198:201], v164 offset:3072
	s_add_u32 s2, s26, 0xfffc0080
	s_addc_u32 s3, s27, -1
	s_cmp_eq_u32 s52, 12
	s_cselect_b32 s3, s11, s3
	s_cselect_b32 s2, s13, s2
	s_cselect_b32 s29, s44, s47
	s_cselect_b32 s28, s45, s46
	v_lshl_add_u64 v[148:149], s[26:27], 0, v[142:143]
	s_add_i32 m0, s34, 0xc000
	ds_read_b128 v[202:205], v165
	ds_read_b128 v[206:209], v165 offset:1024
	ds_read_b128 v[210:213], v165 offset:2048
	ds_read_b128 v[214:217], v165 offset:3072
	ds_read_b128 v[218:221], v165 offset:4096
	ds_read_b128 v[222:225], v165 offset:5120
	ds_read_b128 v[226:229], v165 offset:6144
	ds_read_b128 v[230:233], v165 offset:7168
	global_load_lds_dwordx4 v[148:149], off
	v_lshl_add_u64 v[148:149], s[26:27], 0, v[144:145]
	s_add_i32 m0, s34, 0xe000
	s_nop 0
	global_load_lds_dwordx4 v[148:149], off
	s_waitcnt vmcnt(8)
	s_waitcnt lgkmcnt(0)
	s_setprio 1
	s_barrier
	v_mfma_f32_16x16x32_bf16 v[126:129], v[166:169], v[202:205], 0
	v_mfma_f32_16x16x32_bf16 v[122:125], v[178:181], v[202:205], 0
	v_mfma_f32_16x16x32_bf16 v[110:113], v[166:169], v[210:213], 0
	v_mfma_f32_16x16x32_bf16 v[106:109], v[178:181], v[210:213], 0
	v_mfma_f32_16x16x32_bf16 v[94:97], v[166:169], v[218:221], 0
	v_mfma_f32_16x16x32_bf16 v[90:93], v[178:181], v[218:221], 0
	v_mfma_f32_16x16x32_bf16 v[78:81], v[166:169], v[226:229], 0
	v_mfma_f32_16x16x32_bf16 v[74:77], v[178:181], v[226:229], 0
	v_mfma_f32_16x16x32_bf16 v[126:129], v[170:173], v[206:209], v[126:129]
	v_mfma_f32_16x16x32_bf16 v[122:125], v[182:185], v[206:209], v[122:125]
	v_mfma_f32_16x16x32_bf16 v[110:113], v[170:173], v[214:217], v[110:113]
	v_mfma_f32_16x16x32_bf16 v[106:109], v[182:185], v[214:217], v[106:109]
	v_mfma_f32_16x16x32_bf16 v[94:97], v[170:173], v[222:225], v[94:97]
	v_mfma_f32_16x16x32_bf16 v[90:93], v[182:185], v[222:225], v[90:93]
	v_mfma_f32_16x16x32_bf16 v[78:81], v[170:173], v[230:233], v[78:81]
	v_mfma_f32_16x16x32_bf16 v[74:77], v[182:185], v[230:233], v[74:77]
	v_mfma_f32_16x16x32_bf16 v[118:121], v[186:189], v[202:205], 0
	v_mfma_f32_16x16x32_bf16 v[114:117], v[194:197], v[202:205], 0
	v_mfma_f32_16x16x32_bf16 v[102:105], v[186:189], v[210:213], 0
	v_mfma_f32_16x16x32_bf16 v[98:101], v[194:197], v[210:213], 0
	v_mfma_f32_16x16x32_bf16 v[86:89], v[186:189], v[218:221], 0
	v_mfma_f32_16x16x32_bf16 v[82:85], v[194:197], v[218:221], 0
	v_mfma_f32_16x16x32_bf16 v[70:73], v[186:189], v[226:229], 0
	v_mfma_f32_16x16x32_bf16 v[66:69], v[194:197], v[226:229], 0
	v_mfma_f32_16x16x32_bf16 v[118:121], v[190:193], v[206:209], v[118:121]
	v_mfma_f32_16x16x32_bf16 v[114:117], v[198:201], v[206:209], v[114:117]
	v_mfma_f32_16x16x32_bf16 v[102:105], v[190:193], v[214:217], v[102:105]
	v_mfma_f32_16x16x32_bf16 v[98:101], v[198:201], v[214:217], v[98:101]
	v_mfma_f32_16x16x32_bf16 v[86:89], v[190:193], v[222:225], v[86:89]
	v_mfma_f32_16x16x32_bf16 v[82:85], v[198:201], v[222:225], v[82:85]
	v_mfma_f32_16x16x32_bf16 v[70:73], v[190:193], v[230:233], v[70:73]
	v_mfma_f32_16x16x32_bf16 v[66:69], v[198:201], v[230:233], v[66:69]
	s_barrier
	s_setprio 0
	s_add_i32 s53, s41, s30
	v_lshl_add_u64 v[148:149], s[28:29], 0, v[132:133]
	s_mov_b32 m0, s53
	ds_read_b128 v[202:205], v165 offset:16384
	ds_read_b128 v[206:209], v165 offset:17408
	ds_read_b128 v[210:213], v165 offset:18432
	ds_read_b128 v[214:217], v165 offset:19456
	ds_read_b128 v[218:221], v165 offset:20480
	ds_read_b128 v[222:225], v165 offset:21504
	ds_read_b128 v[226:229], v165 offset:22528
	ds_read_b128 v[230:233], v165 offset:23552
	global_load_lds_dwordx4 v[148:149], off
	s_add_i32 m0, s53, 0x2000
	s_add_u32 s54, s28, 0x40000
	v_lshl_add_u64 v[174:175], s[28:29], 0, v[136:137]
	s_addc_u32 s55, s29, 0
	s_add_i32 s53, s42, s30
	global_load_lds_dwordx4 v[174:175], off
	v_lshl_add_u64 v[234:235], s[54:55], 0, v[132:133]
	s_mov_b32 m0, s53
	v_lshl_add_u64 v[236:237], s[2:3], 0, v[134:135]
	global_load_lds_dwordx4 v[234:235], off
	v_lshl_add_u64 v[234:235], s[54:55], 0, v[136:137]
	s_add_i32 m0, s53, 0x2000
	s_nop 0
	global_load_lds_dwordx4 v[234:235], off
	v_lshl_add_u64 v[234:235], s[2:3], 0, v[130:131]
	s_mov_b32 m0, s34
	s_nop 0
	global_load_lds_dwordx4 v[234:235], off
	s_mov_b32 m0, s25
	s_nop 0
	global_load_lds_dwordx4 v[236:237], off
	s_waitcnt vmcnt(8)
	s_waitcnt lgkmcnt(0)
	s_setprio 1
	s_barrier
	v_mfma_f32_16x16x32_bf16 v[62:65], v[166:169], v[202:205], 0
	v_mfma_f32_16x16x32_bf16 v[58:61], v[178:181], v[202:205], 0
	v_mfma_f32_16x16x32_bf16 v[46:49], v[166:169], v[210:213], 0
	v_mfma_f32_16x16x32_bf16 v[42:45], v[178:181], v[210:213], 0
	v_mfma_f32_16x16x32_bf16 v[30:33], v[166:169], v[218:221], 0
	v_mfma_f32_16x16x32_bf16 v[26:29], v[178:181], v[218:221], 0
	v_mfma_f32_16x16x32_bf16 v[14:17], v[166:169], v[226:229], 0
	v_mfma_f32_16x16x32_bf16 v[10:13], v[178:181], v[226:229], 0
	v_mfma_f32_16x16x32_bf16 v[62:65], v[170:173], v[206:209], v[62:65]
	v_mfma_f32_16x16x32_bf16 v[58:61], v[182:185], v[206:209], v[58:61]
	v_mfma_f32_16x16x32_bf16 v[46:49], v[170:173], v[214:217], v[46:49]
	v_mfma_f32_16x16x32_bf16 v[42:45], v[182:185], v[214:217], v[42:45]
	v_mfma_f32_16x16x32_bf16 v[30:33], v[170:173], v[222:225], v[30:33]
	v_mfma_f32_16x16x32_bf16 v[26:29], v[182:185], v[222:225], v[26:29]
	v_mfma_f32_16x16x32_bf16 v[14:17], v[170:173], v[230:233], v[14:17]
	v_mfma_f32_16x16x32_bf16 v[10:13], v[182:185], v[230:233], v[10:13]
	v_mfma_f32_16x16x32_bf16 v[54:57], v[186:189], v[202:205], 0
	v_mfma_f32_16x16x32_bf16 v[50:53], v[194:197], v[202:205], 0
	v_mfma_f32_16x16x32_bf16 v[38:41], v[186:189], v[210:213], 0
	v_mfma_f32_16x16x32_bf16 v[34:37], v[194:197], v[210:213], 0
	v_mfma_f32_16x16x32_bf16 v[22:25], v[186:189], v[218:221], 0
	v_mfma_f32_16x16x32_bf16 v[18:21], v[194:197], v[218:221], 0
	v_mfma_f32_16x16x32_bf16 v[6:9], v[186:189], v[226:229], 0
	v_mfma_f32_16x16x32_bf16 v[2:5], v[194:197], v[226:229], 0
	v_mfma_f32_16x16x32_bf16 v[54:57], v[190:193], v[206:209], v[54:57]
	v_mfma_f32_16x16x32_bf16 v[50:53], v[198:201], v[206:209], v[50:53]
	v_mfma_f32_16x16x32_bf16 v[38:41], v[190:193], v[214:217], v[38:41]
	v_mfma_f32_16x16x32_bf16 v[34:37], v[198:201], v[214:217], v[34:37]
	v_mfma_f32_16x16x32_bf16 v[22:25], v[190:193], v[222:225], v[22:25]
	v_mfma_f32_16x16x32_bf16 v[18:21], v[198:201], v[222:225], v[18:21]
	v_mfma_f32_16x16x32_bf16 v[6:9], v[190:193], v[230:233], v[6:9]
	v_mfma_f32_16x16x32_bf16 v[2:5], v[198:201], v[230:233], v[2:5]
	s_barrier
	s_setprio 0
	s_add_i32 s53, 0, 0x18000
	v_add_u32_e32 v176, s53, v163
	s_add_i32 s54, 0, 0x1c000
	ds_read_b128 v[166:169], v176
	ds_read_b128 v[170:173], v176 offset:1024
	ds_read_b128 v[178:181], v176 offset:2048
	ds_read_b128 v[182:185], v176 offset:3072
	v_add_u32_e32 v176, s54, v163
	ds_read_b128 v[186:189], v176
	ds_read_b128 v[190:193], v176 offset:1024
	ds_read_b128 v[194:197], v176 offset:2048
	ds_read_b128 v[198:201], v176 offset:3072
	s_add_u32 s2, s2, 0x40000
	s_addc_u32 s3, s3, 0
	s_mov_b32 m0, s35
	v_lshl_add_u64 v[238:239], s[2:3], 0, v[130:131]
	ds_read_b128 v[202:205], v165 offset:32768
	ds_read_b128 v[206:209], v165 offset:33792
	ds_read_b128 v[210:213], v165 offset:34816
	ds_read_b128 v[214:217], v165 offset:35840
	ds_read_b128 v[218:221], v165 offset:36864
	ds_read_b128 v[222:225], v165 offset:37888
	ds_read_b128 v[226:229], v165 offset:38912
	ds_read_b128 v[230:233], v165 offset:39936
	global_load_lds_dwordx4 v[238:239], off
	v_lshl_add_u64 v[238:239], s[2:3], 0, v[134:135]
	s_mov_b32 m0, s36
	s_nop 0
	global_load_lds_dwordx4 v[238:239], off
	s_waitcnt vmcnt(8)
	s_waitcnt lgkmcnt(0)
	s_setprio 1
	s_barrier
	v_mfma_f32_16x16x32_bf16 v[126:129], v[166:169], v[202:205], v[126:129]
	v_mfma_f32_16x16x32_bf16 v[122:125], v[178:181], v[202:205], v[122:125]
	v_mfma_f32_16x16x32_bf16 v[110:113], v[166:169], v[210:213], v[110:113]
	v_mfma_f32_16x16x32_bf16 v[106:109], v[178:181], v[210:213], v[106:109]
	v_mfma_f32_16x16x32_bf16 v[94:97], v[166:169], v[218:221], v[94:97]
	v_mfma_f32_16x16x32_bf16 v[90:93], v[178:181], v[218:221], v[90:93]
	v_mfma_f32_16x16x32_bf16 v[78:81], v[166:169], v[226:229], v[78:81]
	v_mfma_f32_16x16x32_bf16 v[74:77], v[178:181], v[226:229], v[74:77]
	v_mfma_f32_16x16x32_bf16 v[126:129], v[170:173], v[206:209], v[126:129]
	v_mfma_f32_16x16x32_bf16 v[122:125], v[182:185], v[206:209], v[122:125]
	v_mfma_f32_16x16x32_bf16 v[110:113], v[170:173], v[214:217], v[110:113]
	v_mfma_f32_16x16x32_bf16 v[106:109], v[182:185], v[214:217], v[106:109]
	v_mfma_f32_16x16x32_bf16 v[94:97], v[170:173], v[222:225], v[94:97]
	v_mfma_f32_16x16x32_bf16 v[90:93], v[182:185], v[222:225], v[90:93]
	v_mfma_f32_16x16x32_bf16 v[78:81], v[170:173], v[230:233], v[78:81]
	v_mfma_f32_16x16x32_bf16 v[74:77], v[182:185], v[230:233], v[74:77]
	v_mfma_f32_16x16x32_bf16 v[118:121], v[186:189], v[202:205], v[118:121]
	v_mfma_f32_16x16x32_bf16 v[114:117], v[194:197], v[202:205], v[114:117]
	v_mfma_f32_16x16x32_bf16 v[102:105], v[186:189], v[210:213], v[102:105]
	v_mfma_f32_16x16x32_bf16 v[98:101], v[194:197], v[210:213], v[98:101]
	v_mfma_f32_16x16x32_bf16 v[86:89], v[186:189], v[218:221], v[86:89]
	v_mfma_f32_16x16x32_bf16 v[82:85], v[194:197], v[218:221], v[82:85]
	v_mfma_f32_16x16x32_bf16 v[70:73], v[186:189], v[226:229], v[70:73]
	v_mfma_f32_16x16x32_bf16 v[66:69], v[194:197], v[226:229], v[66:69]
	v_mfma_f32_16x16x32_bf16 v[118:121], v[190:193], v[206:209], v[118:121]
	v_mfma_f32_16x16x32_bf16 v[114:117], v[198:201], v[206:209], v[114:117]
	v_mfma_f32_16x16x32_bf16 v[102:105], v[190:193], v[214:217], v[102:105]
	v_mfma_f32_16x16x32_bf16 v[98:101], v[198:201], v[214:217], v[98:101]
	v_mfma_f32_16x16x32_bf16 v[86:89], v[190:193], v[222:225], v[86:89]
	v_mfma_f32_16x16x32_bf16 v[82:85], v[198:201], v[222:225], v[82:85]
	v_mfma_f32_16x16x32_bf16 v[70:73], v[190:193], v[230:233], v[70:73]
	v_mfma_f32_16x16x32_bf16 v[66:69], v[198:201], v[230:233], v[66:69]
	s_barrier
	s_setprio 0
	s_add_i32 s2, s53, s30
	v_lshl_add_u64 v[148:149], v[148:149], 0, s[6:7]
	s_mov_b32 m0, s2
	ds_read_b128 v[202:205], v165 offset:49152
	ds_read_b128 v[206:209], v165 offset:50176
	ds_read_b128 v[210:213], v165 offset:51200
	ds_read_b128 v[214:217], v165 offset:52224
	ds_read_b128 v[218:221], v165 offset:53248
	ds_read_b128 v[222:225], v165 offset:54272
	ds_read_b128 v[226:229], v165 offset:55296
	ds_read_b128 v[230:233], v165 offset:56320
	global_load_lds_dwordx4 v[148:149], off
	s_add_i32 m0, s2, 0x2000
	s_add_u32 s2, s28, 0x40080
	v_lshl_add_u64 v[148:149], v[174:175], 0, s[6:7]
	s_addc_u32 s3, s29, 0
	s_add_i32 s28, s54, s30
	global_load_lds_dwordx4 v[148:149], off
	v_lshl_add_u64 v[148:149], s[2:3], 0, v[132:133]
	s_mov_b32 m0, s28
	s_nop 0
	global_load_lds_dwordx4 v[148:149], off
	v_lshl_add_u64 v[148:149], s[2:3], 0, v[136:137]
	s_add_i32 m0, s28, 0x2000
	s_nop 0
	global_load_lds_dwordx4 v[148:149], off
	v_lshl_add_u64 v[148:149], v[234:235], 0, s[6:7]
	s_mov_b32 m0, s38
	s_nop 0
	global_load_lds_dwordx4 v[148:149], off
	v_lshl_add_u64 v[148:149], v[236:237], 0, s[6:7]
	s_mov_b32 m0, s39
	s_nop 0
	global_load_lds_dwordx4 v[148:149], off
	s_waitcnt vmcnt(8)
	s_waitcnt lgkmcnt(0)
	s_setprio 1
	s_barrier
	v_mfma_f32_16x16x32_bf16 v[62:65], v[166:169], v[202:205], v[62:65]
	v_mfma_f32_16x16x32_bf16 v[58:61], v[178:181], v[202:205], v[58:61]
	v_mfma_f32_16x16x32_bf16 v[46:49], v[166:169], v[210:213], v[46:49]
	v_mfma_f32_16x16x32_bf16 v[42:45], v[178:181], v[210:213], v[42:45]
	v_mfma_f32_16x16x32_bf16 v[30:33], v[166:169], v[218:221], v[30:33]
	v_mfma_f32_16x16x32_bf16 v[26:29], v[178:181], v[218:221], v[26:29]
	v_mfma_f32_16x16x32_bf16 v[14:17], v[166:169], v[226:229], v[14:17]
	v_mfma_f32_16x16x32_bf16 v[10:13], v[178:181], v[226:229], v[10:13]
	v_mfma_f32_16x16x32_bf16 v[62:65], v[170:173], v[206:209], v[62:65]
	v_mfma_f32_16x16x32_bf16 v[58:61], v[182:185], v[206:209], v[58:61]
	v_mfma_f32_16x16x32_bf16 v[46:49], v[170:173], v[214:217], v[46:49]
	v_mfma_f32_16x16x32_bf16 v[42:45], v[182:185], v[214:217], v[42:45]
	v_mfma_f32_16x16x32_bf16 v[30:33], v[170:173], v[222:225], v[30:33]
	v_mfma_f32_16x16x32_bf16 v[26:29], v[182:185], v[222:225], v[26:29]
	v_mfma_f32_16x16x32_bf16 v[14:17], v[170:173], v[230:233], v[14:17]
	v_mfma_f32_16x16x32_bf16 v[10:13], v[182:185], v[230:233], v[10:13]
	v_mfma_f32_16x16x32_bf16 v[54:57], v[186:189], v[202:205], v[54:57]
	v_mfma_f32_16x16x32_bf16 v[50:53], v[194:197], v[202:205], v[50:53]
	v_mfma_f32_16x16x32_bf16 v[38:41], v[186:189], v[210:213], v[38:41]
	v_mfma_f32_16x16x32_bf16 v[34:37], v[194:197], v[210:213], v[34:37]
	v_mfma_f32_16x16x32_bf16 v[22:25], v[186:189], v[218:221], v[22:25]
	v_mfma_f32_16x16x32_bf16 v[18:21], v[194:197], v[218:221], v[18:21]
	v_mfma_f32_16x16x32_bf16 v[6:9], v[186:189], v[226:229], v[6:9]
	v_mfma_f32_16x16x32_bf16 v[2:5], v[194:197], v[226:229], v[2:5]
	v_mfma_f32_16x16x32_bf16 v[54:57], v[190:193], v[206:209], v[54:57]
	v_mfma_f32_16x16x32_bf16 v[50:53], v[198:201], v[206:209], v[50:53]
	v_mfma_f32_16x16x32_bf16 v[38:41], v[190:193], v[214:217], v[38:41]
	v_mfma_f32_16x16x32_bf16 v[34:37], v[198:201], v[214:217], v[34:37]
	v_mfma_f32_16x16x32_bf16 v[22:25], v[190:193], v[222:225], v[22:25]
	v_mfma_f32_16x16x32_bf16 v[18:21], v[198:201], v[222:225], v[18:21]
	v_mfma_f32_16x16x32_bf16 v[6:9], v[190:193], v[230:233], v[6:9]
	v_mfma_f32_16x16x32_bf16 v[2:5], v[198:201], v[230:233], v[2:5]
	s_barrier
	s_setprio 0
	s_add_i32 s52, s52, 2
	s_add_u32 s26, s26, 0x100
	s_addc_u32 s27, s27, 0
	s_add_u32 s46, s46, 0x100
	s_addc_u32 s47, s47, 0
	s_cmp_gt_u32 s52, 13
	s_cbranch_scc0 .LBB0_354
	s_branch .Lpk354_exit

.LBB0_357:
	s_mov_b32 s100, 0xbfb8aa3b
	v_pk_mul_f32 v[166:167], v[126:127], s[100:101] op_sel_hi:[1,0]
	v_pk_mul_f32 v[168:169], v[128:129], s[100:101] op_sel_hi:[1,0]
	v_pk_mul_f32 v[170:171], v[122:123], s[100:101] op_sel_hi:[1,0]
	v_pk_mul_f32 v[172:173], v[124:125], s[100:101] op_sel_hi:[1,0]
	v_exp_f32_e32 v166, v166
	v_exp_f32_e32 v167, v167
	v_exp_f32_e32 v168, v168
	v_exp_f32_e32 v169, v169
	v_exp_f32_e32 v170, v170
	v_exp_f32_e32 v171, v171
	v_exp_f32_e32 v172, v172
	v_exp_f32_e32 v173, v173
	v_pk_add_f32 v[166:167], v[166:167], 1.0 op_sel_hi:[1,0]
	v_pk_add_f32 v[168:169], v[168:169], 1.0 op_sel_hi:[1,0]
	v_pk_add_f32 v[170:171], v[170:171], 1.0 op_sel_hi:[1,0]
	v_pk_add_f32 v[172:173], v[172:173], 1.0 op_sel_hi:[1,0]
	v_rcp_f32_e32 v166, v166
	v_rcp_f32_e32 v167, v167
	v_rcp_f32_e32 v168, v168
	v_rcp_f32_e32 v169, v169
	v_rcp_f32_e32 v170, v170
	v_rcp_f32_e32 v171, v171
	v_rcp_f32_e32 v172, v172
	v_rcp_f32_e32 v173, v173
	v_pk_mul_f32 v[166:167], v[126:127], v[166:167]
	v_pk_mul_f32 v[168:169], v[128:129], v[168:169]
	v_pk_mul_f32 v[170:171], v[122:123], v[170:171]
	v_pk_mul_f32 v[172:173], v[124:125], v[172:173]
	v_pk_mul_f32 v[166:167], v[166:167], v[118:119]
	v_pk_mul_f32 v[168:169], v[168:169], v[120:121]
	v_pk_mul_f32 v[170:171], v[170:171], v[114:115]
	v_pk_mul_f32 v[172:173], v[172:173], v[116:117]
	s_lshl_b32 s3, s43, 1
	s_mul_i32 s2, s24, 44
	s_or_b32 s3, s3, s40
	s_add_i32 s2, s3, s2
	s_ashr_i32 s3, s2, 31
	s_lshl_b64 s[2:3], s[2:3], 15
	v_lshl_add_u64 v[148:149], v[140:141], 0, s[2:3]
	v_cvt_pk_bf16_f32 v114, v166, v167
	v_cvt_pk_bf16_f32 v115, v168, v169
	v_cvt_pk_bf16_f32 v116, v170, v171
	v_cvt_pk_bf16_f32 v117, v172, v173
	global_store_dwordx4 v[148:149], v[114:117], off
	v_pk_mul_f32 v[166:167], v[110:111], s[100:101] op_sel_hi:[1,0]
	v_pk_mul_f32 v[168:169], v[112:113], s[100:101] op_sel_hi:[1,0]
	v_pk_mul_f32 v[170:171], v[106:107], s[100:101] op_sel_hi:[1,0]
	v_pk_mul_f32 v[172:173], v[108:109], s[100:101] op_sel_hi:[1,0]
	v_exp_f32_e32 v166, v166
	v_exp_f32_e32 v167, v167
	v_exp_f32_e32 v168, v168
	v_exp_f32_e32 v169, v169
	v_exp_f32_e32 v170, v170
	v_exp_f32_e32 v171, v171
	v_exp_f32_e32 v172, v172
	v_exp_f32_e32 v173, v173
	v_pk_add_f32 v[166:167], v[166:167], 1.0 op_sel_hi:[1,0]
	v_pk_add_f32 v[168:169], v[168:169], 1.0 op_sel_hi:[1,0]
	v_pk_add_f32 v[170:171], v[170:171], 1.0 op_sel_hi:[1,0]
	v_pk_add_f32 v[172:173], v[172:173], 1.0 op_sel_hi:[1,0]
	v_rcp_f32_e32 v166, v166
	v_rcp_f32_e32 v167, v167
	v_rcp_f32_e32 v168, v168
	v_rcp_f32_e32 v169, v169
	v_rcp_f32_e32 v170, v170
	v_rcp_f32_e32 v171, v171
	v_rcp_f32_e32 v172, v172
	v_rcp_f32_e32 v173, v173
	v_pk_mul_f32 v[166:167], v[110:111], v[166:167]
	v_pk_mul_f32 v[168:169], v[112:113], v[168:169]
	v_pk_mul_f32 v[170:171], v[106:107], v[170:171]
	v_pk_mul_f32 v[172:173], v[108:109], v[172:173]
	v_pk_mul_f32 v[166:167], v[166:167], v[102:103]
	v_pk_mul_f32 v[168:169], v[168:169], v[104:105]
	v_pk_mul_f32 v[170:171], v[170:171], v[98:99]
	v_pk_mul_f32 v[172:173], v[172:173], v[100:101]
	s_movk_i32 s2, 0x1000
	v_cvt_pk_bf16_f32 v98, v166, v167
	v_cvt_pk_bf16_f32 v99, v168, v169
	v_cvt_pk_bf16_f32 v100, v170, v171
	v_cvt_pk_bf16_f32 v101, v172, v173
	global_store_dwordx4 v[148:149], v[98:101], off offset:2048
	v_pk_mul_f32 v[166:167], v[94:95], s[100:101] op_sel_hi:[1,0]
	v_pk_mul_f32 v[168:169], v[96:97], s[100:101] op_sel_hi:[1,0]
	v_pk_mul_f32 v[170:171], v[90:91], s[100:101] op_sel_hi:[1,0]
	v_pk_mul_f32 v[172:173], v[92:93], s[100:101] op_sel_hi:[1,0]
	v_exp_f32_e32 v166, v166
	v_exp_f32_e32 v167, v167
	v_exp_f32_e32 v168, v168
	v_exp_f32_e32 v169, v169
	v_exp_f32_e32 v170, v170
	v_exp_f32_e32 v171, v171
	v_exp_f32_e32 v172, v172
	v_exp_f32_e32 v173, v173
	v_pk_add_f32 v[166:167], v[166:167], 1.0 op_sel_hi:[1,0]
	v_pk_add_f32 v[168:169], v[168:169], 1.0 op_sel_hi:[1,0]
	v_pk_add_f32 v[170:171], v[170:171], 1.0 op_sel_hi:[1,0]
	v_pk_add_f32 v[172:173], v[172:173], 1.0 op_sel_hi:[1,0]
	v_rcp_f32_e32 v166, v166
	v_rcp_f32_e32 v167, v167
	v_rcp_f32_e32 v168, v168
	v_rcp_f32_e32 v169, v169
	v_rcp_f32_e32 v170, v170
	v_rcp_f32_e32 v171, v171
	v_rcp_f32_e32 v172, v172
	v_rcp_f32_e32 v173, v173
	v_pk_mul_f32 v[166:167], v[94:95], v[166:167]
	v_pk_mul_f32 v[168:169], v[96:97], v[168:169]
	v_pk_mul_f32 v[170:171], v[90:91], v[170:171]
	v_pk_mul_f32 v[172:173], v[92:93], v[172:173]
	v_pk_mul_f32 v[166:167], v[166:167], v[86:87]
	v_pk_mul_f32 v[168:169], v[168:169], v[88:89]
	v_pk_mul_f32 v[170:171], v[170:171], v[82:83]
	v_pk_mul_f32 v[172:173], v[172:173], v[84:85]
	v_add_co_u32_e32 v86, vcc, s2, v148
	s_nop 1
	v_addc_co_u32_e32 v87, vcc, 0, v149, vcc
	v_cvt_pk_bf16_f32 v82, v166, v167
	v_cvt_pk_bf16_f32 v83, v168, v169
	v_cvt_pk_bf16_f32 v84, v170, v171
	v_cvt_pk_bf16_f32 v85, v172, v173
	global_store_dwordx4 v[86:87], v[82:85], off
	v_pk_mul_f32 v[166:167], v[78:79], s[100:101] op_sel_hi:[1,0]
	v_pk_mul_f32 v[168:169], v[80:81], s[100:101] op_sel_hi:[1,0]
	v_pk_mul_f32 v[170:171], v[74:75], s[100:101] op_sel_hi:[1,0]
	v_pk_mul_f32 v[172:173], v[76:77], s[100:101] op_sel_hi:[1,0]
	v_exp_f32_e32 v166, v166
	v_exp_f32_e32 v167, v167
	v_exp_f32_e32 v168, v168
	v_exp_f32_e32 v169, v169
	v_exp_f32_e32 v170, v170
	v_exp_f32_e32 v171, v171
	v_exp_f32_e32 v172, v172
	v_exp_f32_e32 v173, v173
	v_pk_add_f32 v[166:167], v[166:167], 1.0 op_sel_hi:[1,0]
	v_pk_add_f32 v[168:169], v[168:169], 1.0 op_sel_hi:[1,0]
	v_pk_add_f32 v[170:171], v[170:171], 1.0 op_sel_hi:[1,0]
	v_pk_add_f32 v[172:173], v[172:173], 1.0 op_sel_hi:[1,0]
	v_rcp_f32_e32 v166, v166
	v_rcp_f32_e32 v167, v167
	v_rcp_f32_e32 v168, v168
	v_rcp_f32_e32 v169, v169
	v_rcp_f32_e32 v170, v170
	v_rcp_f32_e32 v171, v171
	v_rcp_f32_e32 v172, v172
	v_rcp_f32_e32 v173, v173
	v_pk_mul_f32 v[166:167], v[78:79], v[166:167]
	v_pk_mul_f32 v[168:169], v[80:81], v[168:169]
	v_pk_mul_f32 v[170:171], v[74:75], v[170:171]
	v_pk_mul_f32 v[172:173], v[76:77], v[172:173]
	v_pk_mul_f32 v[166:167], v[166:167], v[70:71]
	v_pk_mul_f32 v[168:169], v[168:169], v[72:73]
	v_pk_mul_f32 v[170:171], v[170:171], v[66:67]
	v_pk_mul_f32 v[172:173], v[172:173], v[68:69]
	s_movk_i32 s2, 0x4000
	v_cvt_pk_bf16_f32 v66, v166, v167
	v_cvt_pk_bf16_f32 v67, v168, v169
	v_cvt_pk_bf16_f32 v68, v170, v171
	v_cvt_pk_bf16_f32 v69, v172, v173
	global_store_dwordx4 v[86:87], v[66:69], off offset:2048
	v_pk_mul_f32 v[166:167], v[62:63], s[100:101] op_sel_hi:[1,0]
	v_pk_mul_f32 v[168:169], v[64:65], s[100:101] op_sel_hi:[1,0]
	v_pk_mul_f32 v[170:171], v[58:59], s[100:101] op_sel_hi:[1,0]
	v_pk_mul_f32 v[172:173], v[60:61], s[100:101] op_sel_hi:[1,0]
	v_exp_f32_e32 v166, v166
	v_exp_f32_e32 v167, v167
	v_exp_f32_e32 v168, v168
	v_exp_f32_e32 v169, v169
	v_exp_f32_e32 v170, v170
	v_exp_f32_e32 v171, v171
	v_exp_f32_e32 v172, v172
	v_exp_f32_e32 v173, v173
	v_pk_add_f32 v[166:167], v[166:167], 1.0 op_sel_hi:[1,0]
	v_pk_add_f32 v[168:169], v[168:169], 1.0 op_sel_hi:[1,0]
	v_pk_add_f32 v[170:171], v[170:171], 1.0 op_sel_hi:[1,0]
	v_pk_add_f32 v[172:173], v[172:173], 1.0 op_sel_hi:[1,0]
	v_rcp_f32_e32 v166, v166
	v_rcp_f32_e32 v167, v167
	v_rcp_f32_e32 v168, v168
	v_rcp_f32_e32 v169, v169
	v_rcp_f32_e32 v170, v170
	v_rcp_f32_e32 v171, v171
	v_rcp_f32_e32 v172, v172
	v_rcp_f32_e32 v173, v173
	v_pk_mul_f32 v[166:167], v[62:63], v[166:167]
	v_pk_mul_f32 v[168:169], v[64:65], v[168:169]
	v_pk_mul_f32 v[170:171], v[58:59], v[170:171]
	v_pk_mul_f32 v[172:173], v[60:61], v[172:173]
	v_pk_mul_f32 v[166:167], v[166:167], v[54:55]
	v_pk_mul_f32 v[168:169], v[168:169], v[56:57]
	v_pk_mul_f32 v[170:171], v[170:171], v[50:51]
	v_pk_mul_f32 v[172:173], v[172:173], v[52:53]
	v_add_co_u32_e32 v54, vcc, s2, v148
	s_nop 1
	v_addc_co_u32_e32 v55, vcc, 0, v149, vcc
	s_movk_i32 s2, 0x5000
	v_add_co_u32_e32 v56, vcc, s2, v148
	s_nop 0
	s_nop 1
	v_addc_co_u32_e32 v57, vcc, 0, v149, vcc
	v_cvt_pk_bf16_f32 v50, v166, v167
	v_cvt_pk_bf16_f32 v51, v168, v169
	v_cvt_pk_bf16_f32 v52, v170, v171
	v_cvt_pk_bf16_f32 v53, v172, v173
	global_store_dwordx4 v[56:57], v[50:53], off offset:-4096
	v_pk_mul_f32 v[166:167], v[46:47], s[100:101] op_sel_hi:[1,0]
	v_pk_mul_f32 v[168:169], v[48:49], s[100:101] op_sel_hi:[1,0]
	v_pk_mul_f32 v[170:171], v[42:43], s[100:101] op_sel_hi:[1,0]
	v_pk_mul_f32 v[172:173], v[44:45], s[100:101] op_sel_hi:[1,0]
	v_exp_f32_e32 v166, v166
	v_exp_f32_e32 v167, v167
	v_exp_f32_e32 v168, v168
	v_exp_f32_e32 v169, v169
	v_exp_f32_e32 v170, v170
	v_exp_f32_e32 v171, v171
	v_exp_f32_e32 v172, v172
	v_exp_f32_e32 v173, v173
	v_pk_add_f32 v[166:167], v[166:167], 1.0 op_sel_hi:[1,0]
	v_pk_add_f32 v[168:169], v[168:169], 1.0 op_sel_hi:[1,0]
	v_pk_add_f32 v[170:171], v[170:171], 1.0 op_sel_hi:[1,0]
	v_pk_add_f32 v[172:173], v[172:173], 1.0 op_sel_hi:[1,0]
	v_rcp_f32_e32 v166, v166
	v_rcp_f32_e32 v167, v167
	v_rcp_f32_e32 v168, v168
	v_rcp_f32_e32 v169, v169
	v_rcp_f32_e32 v170, v170
	v_rcp_f32_e32 v171, v171
	v_rcp_f32_e32 v172, v172
	v_rcp_f32_e32 v173, v173
	v_pk_mul_f32 v[166:167], v[46:47], v[166:167]
	v_pk_mul_f32 v[168:169], v[48:49], v[168:169]
	v_pk_mul_f32 v[170:171], v[42:43], v[170:171]
	v_pk_mul_f32 v[172:173], v[44:45], v[172:173]
	v_pk_mul_f32 v[166:167], v[166:167], v[38:39]
	v_pk_mul_f32 v[168:169], v[168:169], v[40:41]
	v_pk_mul_f32 v[170:171], v[170:171], v[34:35]
	v_pk_mul_f32 v[172:173], v[172:173], v[36:37]
	s_andn2_b64 vcc, exec, s[18:19]
	v_cvt_pk_bf16_f32 v34, v166, v167
	v_cvt_pk_bf16_f32 v35, v168, v169
	v_cvt_pk_bf16_f32 v36, v170, v171
	v_cvt_pk_bf16_f32 v37, v172, v173
	global_store_dwordx4 v[54:55], v[34:37], off offset:2048
	v_pk_mul_f32 v[166:167], v[30:31], s[100:101] op_sel_hi:[1,0]
	v_pk_mul_f32 v[168:169], v[32:33], s[100:101] op_sel_hi:[1,0]
	v_pk_mul_f32 v[170:171], v[26:27], s[100:101] op_sel_hi:[1,0]
	v_pk_mul_f32 v[172:173], v[28:29], s[100:101] op_sel_hi:[1,0]
	v_exp_f32_e32 v166, v166
	v_exp_f32_e32 v167, v167
	v_exp_f32_e32 v168, v168
	v_exp_f32_e32 v169, v169
	v_exp_f32_e32 v170, v170
	v_exp_f32_e32 v171, v171
	v_exp_f32_e32 v172, v172
	v_exp_f32_e32 v173, v173
	v_pk_add_f32 v[166:167], v[166:167], 1.0 op_sel_hi:[1,0]
	v_pk_add_f32 v[168:169], v[168:169], 1.0 op_sel_hi:[1,0]
	v_pk_add_f32 v[170:171], v[170:171], 1.0 op_sel_hi:[1,0]
	v_pk_add_f32 v[172:173], v[172:173], 1.0 op_sel_hi:[1,0]
	v_rcp_f32_e32 v166, v166
	v_rcp_f32_e32 v167, v167
	v_rcp_f32_e32 v168, v168
	v_rcp_f32_e32 v169, v169
	v_rcp_f32_e32 v170, v170
	v_rcp_f32_e32 v171, v171
	v_rcp_f32_e32 v172, v172
	v_rcp_f32_e32 v173, v173
	v_pk_mul_f32 v[166:167], v[30:31], v[166:167]
	v_pk_mul_f32 v[168:169], v[32:33], v[168:169]
	v_pk_mul_f32 v[170:171], v[26:27], v[170:171]
	v_pk_mul_f32 v[172:173], v[28:29], v[172:173]
	v_pk_mul_f32 v[166:167], v[166:167], v[22:23]
	v_pk_mul_f32 v[168:169], v[168:169], v[24:25]
	v_pk_mul_f32 v[170:171], v[170:171], v[18:19]
	v_pk_mul_f32 v[172:173], v[172:173], v[20:21]
	s_mov_b64 s[2:3], -1
	v_cvt_pk_bf16_f32 v18, v166, v167
	v_cvt_pk_bf16_f32 v19, v168, v169
	v_cvt_pk_bf16_f32 v20, v170, v171
	v_cvt_pk_bf16_f32 v21, v172, v173
	global_store_dwordx4 v[56:57], v[18:21], off
	v_pk_mul_f32 v[166:167], v[14:15], s[100:101] op_sel_hi:[1,0]
	v_pk_mul_f32 v[168:169], v[16:17], s[100:101] op_sel_hi:[1,0]
	v_pk_mul_f32 v[170:171], v[10:11], s[100:101] op_sel_hi:[1,0]
	v_pk_mul_f32 v[172:173], v[12:13], s[100:101] op_sel_hi:[1,0]
	v_exp_f32_e32 v166, v166
	v_exp_f32_e32 v167, v167
	v_exp_f32_e32 v168, v168
	v_exp_f32_e32 v169, v169
	v_exp_f32_e32 v170, v170
	v_exp_f32_e32 v171, v171
	v_exp_f32_e32 v172, v172
	v_exp_f32_e32 v173, v173
	v_pk_add_f32 v[166:167], v[166:167], 1.0 op_sel_hi:[1,0]
	v_pk_add_f32 v[168:169], v[168:169], 1.0 op_sel_hi:[1,0]
	v_pk_add_f32 v[170:171], v[170:171], 1.0 op_sel_hi:[1,0]
	v_pk_add_f32 v[172:173], v[172:173], 1.0 op_sel_hi:[1,0]
	v_rcp_f32_e32 v166, v166
	v_rcp_f32_e32 v167, v167
	v_rcp_f32_e32 v168, v168
	v_rcp_f32_e32 v169, v169
	v_rcp_f32_e32 v170, v170
	v_rcp_f32_e32 v171, v171
	v_rcp_f32_e32 v172, v172
	v_rcp_f32_e32 v173, v173
	v_pk_mul_f32 v[166:167], v[14:15], v[166:167]
	v_pk_mul_f32 v[168:169], v[16:17], v[168:169]
	v_pk_mul_f32 v[170:171], v[10:11], v[170:171]
	v_pk_mul_f32 v[172:173], v[12:13], v[172:173]
	v_pk_mul_f32 v[166:167], v[166:167], v[6:7]
	v_pk_mul_f32 v[168:169], v[168:169], v[8:9]
	v_pk_mul_f32 v[170:171], v[170:171], v[2:3]
	v_pk_mul_f32 v[172:173], v[172:173], v[4:5]
	v_cvt_pk_bf16_f32 v2, v166, v167
	v_cvt_pk_bf16_f32 v3, v168, v169
	v_cvt_pk_bf16_f32 v4, v170, v171
	v_cvt_pk_bf16_f32 v5, v172, v173
	global_store_dwordx4 v[56:57], v[2:5], off offset:2048
	s_cbranch_vccnz .LBB0_349
	s_andn2_b64 vcc, exec, s[0:1]
	s_cbranch_vccnz .LBB0_348
	s_branch .LBB0_348

.LBB0_554:
	s_lshl_b64 s[2:3], s[14:15], 1
	v_readlane_b32 s20, v253, 52
	v_readlane_b32 s21, v253, 53
	s_add_u32 s20, s20, s2
	s_addc_u32 s21, s21, s3
	s_and_b64 s[2:3], s[18:19], exec
	s_cselect_b32 s11, s21, s27
	s_cselect_b32 s13, s20, s26
	s_lshl_b64 s[2:3], s[16:17], 1
	s_add_u32 s22, s30, s2
	s_addc_u32 s23, s31, s3
	s_and_b64 s[2:3], s[18:19], exec
	s_cselect_b32 s48, s23, s29
	s_cselect_b32 s49, s22, s28
	s_add_u32 s26, s26, 0x40080
	s_addc_u32 s27, s27, 0
	s_add_u32 s50, s28, 0x100
	s_addc_u32 s51, s29, 0
	s_mov_b32 s52, -2
	s_cmp_lt_u32 s40, 2
	s_cbranch_scc1 .Lz1s555
	s_andn2_b64 vcc, exec, s[0:1]
	s_cbranch_vccnz .Lz1s555
	s_barrier
.Lz1s555:
.Lpk555_peel:
	ds_read_b128 v[154:157], v151
	ds_read_b128 v[158:161], v151 offset:1024
	ds_read_b128 v[162:165], v151 offset:2048
	ds_read_b128 v[166:169], v151 offset:3072
	ds_read_b128 v[170:173], v152
	ds_read_b128 v[178:181], v152 offset:1024
	ds_read_b128 v[182:185], v152 offset:2048
	ds_read_b128 v[186:189], v152 offset:3072
	s_add_u32 s2, s26, 0xfffc0080
	s_addc_u32 s3, s27, -1
	s_cmp_eq_u32 s52, 12
	s_cselect_b32 s3, s11, s3
	s_cselect_b32 s2, s13, s2
	s_cselect_b32 s29, s48, s51
	s_cselect_b32 s28, s49, s50
	v_lshl_add_u64 v[144:145], s[26:27], 0, v[138:139]
	s_add_i32 m0, s37, 0xc000
	ds_read_b128 v[190:193], v153
	ds_read_b128 v[194:197], v153 offset:1024
	ds_read_b128 v[198:201], v153 offset:2048
	ds_read_b128 v[202:205], v153 offset:3072
	ds_read_b128 v[206:209], v153 offset:4096
	ds_read_b128 v[210:213], v153 offset:5120
	ds_read_b128 v[214:217], v153 offset:6144
	ds_read_b128 v[218:221], v153 offset:7168
	global_load_lds_dwordx4 v[144:145], off
	v_lshl_add_u64 v[144:145], s[26:27], 0, v[140:141]
	s_add_i32 m0, s37, 0xe000
	s_nop 0
	global_load_lds_dwordx4 v[144:145], off
	s_waitcnt vmcnt(8)
	s_waitcnt lgkmcnt(0)
	s_setprio 1
	s_barrier
	v_mfma_f32_16x16x32_bf16 v[126:129], v[154:157], v[190:193], 0
	v_mfma_f32_16x16x32_bf16 v[122:125], v[162:165], v[190:193], 0
	v_mfma_f32_16x16x32_bf16 v[114:117], v[154:157], v[198:201], 0
	v_mfma_f32_16x16x32_bf16 v[106:109], v[162:165], v[198:201], 0
	v_mfma_f32_16x16x32_bf16 v[98:101], v[154:157], v[206:209], 0
	v_mfma_f32_16x16x32_bf16 v[90:93], v[162:165], v[206:209], 0
	v_mfma_f32_16x16x32_bf16 v[82:85], v[154:157], v[214:217], 0
	v_mfma_f32_16x16x32_bf16 v[74:77], v[162:165], v[214:217], 0
	v_mfma_f32_16x16x32_bf16 v[126:129], v[158:161], v[194:197], v[126:129]
	v_mfma_f32_16x16x32_bf16 v[122:125], v[166:169], v[194:197], v[122:125]
	v_mfma_f32_16x16x32_bf16 v[114:117], v[158:161], v[202:205], v[114:117]
	v_mfma_f32_16x16x32_bf16 v[106:109], v[166:169], v[202:205], v[106:109]
	v_mfma_f32_16x16x32_bf16 v[98:101], v[158:161], v[210:213], v[98:101]
	v_mfma_f32_16x16x32_bf16 v[90:93], v[166:169], v[210:213], v[90:93]
	v_mfma_f32_16x16x32_bf16 v[82:85], v[158:161], v[218:221], v[82:85]
	v_mfma_f32_16x16x32_bf16 v[74:77], v[166:169], v[218:221], v[74:77]
	v_mfma_f32_16x16x32_bf16 v[118:121], v[170:173], v[190:193], 0
	v_mfma_f32_16x16x32_bf16 v[110:113], v[182:185], v[190:193], 0
	v_mfma_f32_16x16x32_bf16 v[102:105], v[170:173], v[198:201], 0
	v_mfma_f32_16x16x32_bf16 v[94:97], v[182:185], v[198:201], 0
	v_mfma_f32_16x16x32_bf16 v[86:89], v[170:173], v[206:209], 0
	v_mfma_f32_16x16x32_bf16 v[78:81], v[182:185], v[206:209], 0
	v_mfma_f32_16x16x32_bf16 v[70:73], v[170:173], v[214:217], 0
	v_mfma_f32_16x16x32_bf16 v[66:69], v[182:185], v[214:217], 0
	v_mfma_f32_16x16x32_bf16 v[118:121], v[178:181], v[194:197], v[118:121]
	v_mfma_f32_16x16x32_bf16 v[110:113], v[186:189], v[194:197], v[110:113]
	v_mfma_f32_16x16x32_bf16 v[102:105], v[178:181], v[202:205], v[102:105]
	v_mfma_f32_16x16x32_bf16 v[94:97], v[186:189], v[202:205], v[94:97]
	v_mfma_f32_16x16x32_bf16 v[86:89], v[178:181], v[210:213], v[86:89]
	v_mfma_f32_16x16x32_bf16 v[78:81], v[186:189], v[210:213], v[78:81]
	v_mfma_f32_16x16x32_bf16 v[70:73], v[178:181], v[218:221], v[70:73]
	v_mfma_f32_16x16x32_bf16 v[66:69], v[186:189], v[218:221], v[66:69]
	s_barrier
	s_setprio 0
	s_add_i32 s53, s44, s34
	v_lshl_add_u64 v[144:145], s[28:29], 0, v[134:135]
	s_mov_b32 m0, s53
	ds_read_b128 v[190:193], v153 offset:16384
	ds_read_b128 v[194:197], v153 offset:17408
	ds_read_b128 v[198:201], v153 offset:18432
	ds_read_b128 v[202:205], v153 offset:19456
	ds_read_b128 v[206:209], v153 offset:20480
	ds_read_b128 v[210:213], v153 offset:21504
	ds_read_b128 v[214:217], v153 offset:22528
	ds_read_b128 v[218:221], v153 offset:23552
	global_load_lds_dwordx4 v[144:145], off
	s_add_i32 m0, s53, 0x2000
	s_add_u32 s54, s28, 0x40000
	v_lshl_add_u64 v[174:175], s[28:29], 0, v[130:131]
	s_addc_u32 s55, s29, 0
	s_add_i32 s53, s45, s34
	global_load_lds_dwordx4 v[174:175], off
	v_lshl_add_u64 v[222:223], s[54:55], 0, v[134:135]
	s_mov_b32 m0, s53
	v_lshl_add_u64 v[224:225], s[2:3], 0, v[132:133]
	global_load_lds_dwordx4 v[222:223], off
	v_lshl_add_u64 v[222:223], s[54:55], 0, v[130:131]
	s_add_i32 m0, s53, 0x2000
	s_nop 0
	global_load_lds_dwordx4 v[222:223], off
	v_lshl_add_u64 v[222:223], s[2:3], 0, v[136:137]
	s_mov_b32 m0, s37
	s_nop 0
	global_load_lds_dwordx4 v[222:223], off
	s_mov_b32 m0, s25
	s_nop 0
	global_load_lds_dwordx4 v[224:225], off
	s_waitcnt vmcnt(8)
	s_waitcnt lgkmcnt(0)
	s_setprio 1
	s_barrier
	v_mfma_f32_16x16x32_bf16 v[62:65], v[154:157], v[190:193], 0
	v_mfma_f32_16x16x32_bf16 v[58:61], v[162:165], v[190:193], 0
	v_mfma_f32_16x16x32_bf16 v[50:53], v[154:157], v[198:201], 0
	v_mfma_f32_16x16x32_bf16 v[42:45], v[162:165], v[198:201], 0
	v_mfma_f32_16x16x32_bf16 v[34:37], v[154:157], v[206:209], 0
	v_mfma_f32_16x16x32_bf16 v[26:29], v[162:165], v[206:209], 0
	v_mfma_f32_16x16x32_bf16 v[18:21], v[154:157], v[214:217], 0
	v_mfma_f32_16x16x32_bf16 v[10:13], v[162:165], v[214:217], 0
	v_mfma_f32_16x16x32_bf16 v[62:65], v[158:161], v[194:197], v[62:65]
	v_mfma_f32_16x16x32_bf16 v[58:61], v[166:169], v[194:197], v[58:61]
	v_mfma_f32_16x16x32_bf16 v[50:53], v[158:161], v[202:205], v[50:53]
	v_mfma_f32_16x16x32_bf16 v[42:45], v[166:169], v[202:205], v[42:45]
	v_mfma_f32_16x16x32_bf16 v[34:37], v[158:161], v[210:213], v[34:37]
	v_mfma_f32_16x16x32_bf16 v[26:29], v[166:169], v[210:213], v[26:29]
	v_mfma_f32_16x16x32_bf16 v[18:21], v[158:161], v[218:221], v[18:21]
	v_mfma_f32_16x16x32_bf16 v[10:13], v[166:169], v[218:221], v[10:13]
	v_mfma_f32_16x16x32_bf16 v[54:57], v[170:173], v[190:193], 0
	v_mfma_f32_16x16x32_bf16 v[46:49], v[182:185], v[190:193], 0
	v_mfma_f32_16x16x32_bf16 v[38:41], v[170:173], v[198:201], 0
	v_mfma_f32_16x16x32_bf16 v[30:33], v[182:185], v[198:201], 0
	v_mfma_f32_16x16x32_bf16 v[22:25], v[170:173], v[206:209], 0
	v_mfma_f32_16x16x32_bf16 v[14:17], v[182:185], v[206:209], 0
	v_mfma_f32_16x16x32_bf16 v[6:9], v[170:173], v[214:217], 0
	v_mfma_f32_16x16x32_bf16 v[2:5], v[182:185], v[214:217], 0
	v_mfma_f32_16x16x32_bf16 v[54:57], v[178:181], v[194:197], v[54:57]
	v_mfma_f32_16x16x32_bf16 v[46:49], v[186:189], v[194:197], v[46:49]
	v_mfma_f32_16x16x32_bf16 v[38:41], v[178:181], v[202:205], v[38:41]
	v_mfma_f32_16x16x32_bf16 v[30:33], v[186:189], v[202:205], v[30:33]
	v_mfma_f32_16x16x32_bf16 v[22:25], v[178:181], v[210:213], v[22:25]
	v_mfma_f32_16x16x32_bf16 v[14:17], v[186:189], v[210:213], v[14:17]
	v_mfma_f32_16x16x32_bf16 v[6:9], v[178:181], v[218:221], v[6:9]
	v_mfma_f32_16x16x32_bf16 v[2:5], v[186:189], v[218:221], v[2:5]
	s_barrier
	s_setprio 0
	s_add_i32 s53, 0, 0x18000
	s_add_i32 s54, 0, 0x1c000
	v_add_u32_e32 v166, s53, v149
	v_add_u32_e32 v176, s54, v149
	ds_read_b128 v[154:157], v166
	ds_read_b128 v[158:161], v166 offset:1024
	ds_read_b128 v[162:165], v166 offset:2048
	ds_read_b128 v[166:169], v166 offset:3072
	ds_read_b128 v[170:173], v176
	ds_read_b128 v[178:181], v176 offset:1024
	ds_read_b128 v[182:185], v176 offset:2048
	ds_read_b128 v[186:189], v176 offset:3072
	s_add_u32 s2, s2, 0x40000
	s_addc_u32 s3, s3, 0
	s_mov_b32 m0, s38
	v_lshl_add_u64 v[226:227], s[2:3], 0, v[136:137]
	ds_read_b128 v[190:193], v153 offset:32768
	ds_read_b128 v[194:197], v153 offset:33792
	ds_read_b128 v[198:201], v153 offset:34816
	ds_read_b128 v[202:205], v153 offset:35840
	ds_read_b128 v[206:209], v153 offset:36864
	ds_read_b128 v[210:213], v153 offset:37888
	ds_read_b128 v[214:217], v153 offset:38912
	ds_read_b128 v[218:221], v153 offset:39936
	global_load_lds_dwordx4 v[226:227], off
	v_lshl_add_u64 v[226:227], s[2:3], 0, v[132:133]
	s_mov_b32 m0, s39
	s_nop 0
	global_load_lds_dwordx4 v[226:227], off
	s_waitcnt vmcnt(8)
	s_waitcnt lgkmcnt(0)
	s_setprio 1
	s_barrier
	v_mfma_f32_16x16x32_bf16 v[126:129], v[154:157], v[190:193], v[126:129]
	v_mfma_f32_16x16x32_bf16 v[122:125], v[162:165], v[190:193], v[122:125]
	v_mfma_f32_16x16x32_bf16 v[114:117], v[154:157], v[198:201], v[114:117]
	v_mfma_f32_16x16x32_bf16 v[106:109], v[162:165], v[198:201], v[106:109]
	v_mfma_f32_16x16x32_bf16 v[98:101], v[154:157], v[206:209], v[98:101]
	v_mfma_f32_16x16x32_bf16 v[90:93], v[162:165], v[206:209], v[90:93]
	v_mfma_f32_16x16x32_bf16 v[82:85], v[154:157], v[214:217], v[82:85]
	v_mfma_f32_16x16x32_bf16 v[74:77], v[162:165], v[214:217], v[74:77]
	v_mfma_f32_16x16x32_bf16 v[126:129], v[158:161], v[194:197], v[126:129]
	v_mfma_f32_16x16x32_bf16 v[122:125], v[166:169], v[194:197], v[122:125]
	v_mfma_f32_16x16x32_bf16 v[114:117], v[158:161], v[202:205], v[114:117]
	v_mfma_f32_16x16x32_bf16 v[106:109], v[166:169], v[202:205], v[106:109]
	v_mfma_f32_16x16x32_bf16 v[98:101], v[158:161], v[210:213], v[98:101]
	v_mfma_f32_16x16x32_bf16 v[90:93], v[166:169], v[210:213], v[90:93]
	v_mfma_f32_16x16x32_bf16 v[82:85], v[158:161], v[218:221], v[82:85]
	v_mfma_f32_16x16x32_bf16 v[74:77], v[166:169], v[218:221], v[74:77]
	v_mfma_f32_16x16x32_bf16 v[118:121], v[170:173], v[190:193], v[118:121]
	v_mfma_f32_16x16x32_bf16 v[110:113], v[182:185], v[190:193], v[110:113]
	v_mfma_f32_16x16x32_bf16 v[102:105], v[170:173], v[198:201], v[102:105]
	v_mfma_f32_16x16x32_bf16 v[94:97], v[182:185], v[198:201], v[94:97]
	v_mfma_f32_16x16x32_bf16 v[86:89], v[170:173], v[206:209], v[86:89]
	v_mfma_f32_16x16x32_bf16 v[78:81], v[182:185], v[206:209], v[78:81]
	v_mfma_f32_16x16x32_bf16 v[70:73], v[170:173], v[214:217], v[70:73]
	v_mfma_f32_16x16x32_bf16 v[66:69], v[182:185], v[214:217], v[66:69]
	v_mfma_f32_16x16x32_bf16 v[118:121], v[178:181], v[194:197], v[118:121]
	v_mfma_f32_16x16x32_bf16 v[110:113], v[186:189], v[194:197], v[110:113]
	v_mfma_f32_16x16x32_bf16 v[102:105], v[178:181], v[202:205], v[102:105]
	v_mfma_f32_16x16x32_bf16 v[94:97], v[186:189], v[202:205], v[94:97]
	v_mfma_f32_16x16x32_bf16 v[86:89], v[178:181], v[210:213], v[86:89]
	v_mfma_f32_16x16x32_bf16 v[78:81], v[186:189], v[210:213], v[78:81]
	v_mfma_f32_16x16x32_bf16 v[70:73], v[178:181], v[218:221], v[70:73]
	v_mfma_f32_16x16x32_bf16 v[66:69], v[186:189], v[218:221], v[66:69]
	s_barrier
	s_setprio 0
	s_add_i32 s2, s53, s34
	v_lshl_add_u64 v[144:145], v[144:145], 0, s[6:7]
	s_mov_b32 m0, s2
	ds_read_b128 v[190:193], v153 offset:49152
	ds_read_b128 v[194:197], v153 offset:50176
	ds_read_b128 v[198:201], v153 offset:51200
	ds_read_b128 v[202:205], v153 offset:52224
	ds_read_b128 v[206:209], v153 offset:53248
	ds_read_b128 v[210:213], v153 offset:54272
	ds_read_b128 v[214:217], v153 offset:55296
	ds_read_b128 v[218:221], v153 offset:56320
	global_load_lds_dwordx4 v[144:145], off
	s_add_i32 m0, s2, 0x2000
	s_add_u32 s2, s28, 0x40080
	v_lshl_add_u64 v[144:145], v[174:175], 0, s[6:7]
	s_addc_u32 s3, s29, 0
	s_add_i32 s28, s54, s34
	global_load_lds_dwordx4 v[144:145], off
	v_lshl_add_u64 v[144:145], s[2:3], 0, v[134:135]
	s_mov_b32 m0, s28
	s_nop 0
	global_load_lds_dwordx4 v[144:145], off
	v_lshl_add_u64 v[144:145], s[2:3], 0, v[130:131]
	s_add_i32 m0, s28, 0x2000
	s_nop 0
	global_load_lds_dwordx4 v[144:145], off
	v_lshl_add_u64 v[144:145], v[222:223], 0, s[6:7]
	s_mov_b32 m0, s41
	s_nop 0
	global_load_lds_dwordx4 v[144:145], off
	v_lshl_add_u64 v[144:145], v[224:225], 0, s[6:7]
	s_mov_b32 m0, s42
	s_nop 0
	global_load_lds_dwordx4 v[144:145], off
	s_waitcnt vmcnt(8)
	s_waitcnt lgkmcnt(0)
	s_setprio 1
	s_barrier
	v_mfma_f32_16x16x32_bf16 v[62:65], v[154:157], v[190:193], v[62:65]
	v_mfma_f32_16x16x32_bf16 v[58:61], v[162:165], v[190:193], v[58:61]
	v_mfma_f32_16x16x32_bf16 v[50:53], v[154:157], v[198:201], v[50:53]
	v_mfma_f32_16x16x32_bf16 v[42:45], v[162:165], v[198:201], v[42:45]
	v_mfma_f32_16x16x32_bf16 v[34:37], v[154:157], v[206:209], v[34:37]
	v_mfma_f32_16x16x32_bf16 v[26:29], v[162:165], v[206:209], v[26:29]
	v_mfma_f32_16x16x32_bf16 v[18:21], v[154:157], v[214:217], v[18:21]
	v_mfma_f32_16x16x32_bf16 v[10:13], v[162:165], v[214:217], v[10:13]
	v_mfma_f32_16x16x32_bf16 v[62:65], v[158:161], v[194:197], v[62:65]
	v_mfma_f32_16x16x32_bf16 v[58:61], v[166:169], v[194:197], v[58:61]
	v_mfma_f32_16x16x32_bf16 v[50:53], v[158:161], v[202:205], v[50:53]
	v_mfma_f32_16x16x32_bf16 v[42:45], v[166:169], v[202:205], v[42:45]
	v_mfma_f32_16x16x32_bf16 v[34:37], v[158:161], v[210:213], v[34:37]
	v_mfma_f32_16x16x32_bf16 v[26:29], v[166:169], v[210:213], v[26:29]
	v_mfma_f32_16x16x32_bf16 v[18:21], v[158:161], v[218:221], v[18:21]
	v_mfma_f32_16x16x32_bf16 v[10:13], v[166:169], v[218:221], v[10:13]
	v_mfma_f32_16x16x32_bf16 v[54:57], v[170:173], v[190:193], v[54:57]
	v_mfma_f32_16x16x32_bf16 v[46:49], v[182:185], v[190:193], v[46:49]
	v_mfma_f32_16x16x32_bf16 v[38:41], v[170:173], v[198:201], v[38:41]
	v_mfma_f32_16x16x32_bf16 v[30:33], v[182:185], v[198:201], v[30:33]
	v_mfma_f32_16x16x32_bf16 v[22:25], v[170:173], v[206:209], v[22:25]
	v_mfma_f32_16x16x32_bf16 v[14:17], v[182:185], v[206:209], v[14:17]
	v_mfma_f32_16x16x32_bf16 v[6:9], v[170:173], v[214:217], v[6:9]
	v_mfma_f32_16x16x32_bf16 v[2:5], v[182:185], v[214:217], v[2:5]
	v_mfma_f32_16x16x32_bf16 v[54:57], v[178:181], v[194:197], v[54:57]
	v_mfma_f32_16x16x32_bf16 v[46:49], v[186:189], v[194:197], v[46:49]
	v_mfma_f32_16x16x32_bf16 v[38:41], v[178:181], v[202:205], v[38:41]
	v_mfma_f32_16x16x32_bf16 v[30:33], v[186:189], v[202:205], v[30:33]
	v_mfma_f32_16x16x32_bf16 v[22:25], v[178:181], v[210:213], v[22:25]
	v_mfma_f32_16x16x32_bf16 v[14:17], v[186:189], v[210:213], v[14:17]
	v_mfma_f32_16x16x32_bf16 v[6:9], v[178:181], v[218:221], v[6:9]
	v_mfma_f32_16x16x32_bf16 v[2:5], v[186:189], v[218:221], v[2:5]
	s_barrier
	s_setprio 0
	s_add_i32 s52, s52, 2
	s_add_u32 s26, s26, 0x100
	s_addc_u32 s27, s27, 0
	s_add_u32 s50, s50, 0x100
	s_addc_u32 s51, s51, 0
	s_cmp_gt_u32 s52, 13
	s_cbranch_scc0 .LBB0_555
	s_branch .Lpk555_exit

.LBB0_558:
	v_lshl_or_b32 v144, s47, 8, v150
	v_ashrrev_i32_e32 v145, 31, v144
	v_lshl_add_u32 v158, s24, 8, v148
	v_lshl_add_u64 v[144:145], v[144:145], 1, s[62:63]
	v_mad_i64_i32 v[154:155], s[2:3], v158, s46, v[144:145]
	v_pk_add_f32 v[128:129], v[128:129], 0 op_sel_hi:[1,0]
	v_pk_add_f32 v[126:127], v[126:127], 0 op_sel_hi:[1,0]
	v_pk_add_f32 v[156:157], v[124:125], 0 op_sel_hi:[1,0]
	v_pk_add_f32 v[124:125], v[122:123], 0 op_sel_hi:[1,0]
	v_cvt_pk_bf16_f32 v122, v126, v127
	v_cvt_pk_bf16_f32 v123, v128, v129
	v_pk_add_f32 v[118:119], v[118:119], 0 op_sel_hi:[1,0]
	v_cvt_pk_bf16_f32 v124, v124, v125
	v_cvt_pk_bf16_f32 v125, v156, v157
	global_store_dwordx4 v[154:155], v[122:125], off
	v_pk_add_f32 v[120:121], v[120:121], 0 op_sel_hi:[1,0]
	v_pk_add_f32 v[114:115], v[114:115], 0 op_sel_hi:[1,0]
	v_pk_add_f32 v[122:123], v[112:113], 0 op_sel_hi:[1,0]
	v_pk_add_f32 v[112:113], v[110:111], 0 op_sel_hi:[1,0]
	v_cvt_pk_bf16_f32 v110, v118, v119
	v_cvt_pk_bf16_f32 v111, v120, v121
	v_pk_add_f32 v[102:103], v[102:103], 0 op_sel_hi:[1,0]
	v_cvt_pk_bf16_f32 v112, v112, v113
	v_cvt_pk_bf16_f32 v113, v122, v123
	global_store_dwordx4 v[154:155], v[110:113], off offset:256
	v_pk_add_f32 v[104:105], v[104:105], 0 op_sel_hi:[1,0]
	v_pk_add_f32 v[98:99], v[98:99], 0 op_sel_hi:[1,0]
	v_or_b32_e32 v110, 16, v158
	v_mad_i64_i32 v[110:111], s[2:3], v110, s46, v[144:145]
	v_pk_add_f32 v[112:113], v[116:117], 0 op_sel_hi:[1,0]
	v_pk_add_f32 v[116:117], v[108:109], 0 op_sel_hi:[1,0]
	v_pk_add_f32 v[108:109], v[106:107], 0 op_sel_hi:[1,0]
	v_cvt_pk_bf16_f32 v106, v114, v115
	v_cvt_pk_bf16_f32 v107, v112, v113
	v_pk_add_f32 v[86:87], v[86:87], 0 op_sel_hi:[1,0]
	v_cvt_pk_bf16_f32 v108, v108, v109
	v_cvt_pk_bf16_f32 v109, v116, v117
	global_store_dwordx4 v[110:111], v[106:109], off
	v_pk_add_f32 v[88:89], v[88:89], 0 op_sel_hi:[1,0]
	v_pk_add_f32 v[82:83], v[82:83], 0 op_sel_hi:[1,0]
	v_pk_add_f32 v[106:107], v[96:97], 0 op_sel_hi:[1,0]
	v_pk_add_f32 v[96:97], v[94:95], 0 op_sel_hi:[1,0]
	v_cvt_pk_bf16_f32 v94, v102, v103
	v_cvt_pk_bf16_f32 v95, v104, v105
	v_pk_add_f32 v[70:71], v[70:71], 0 op_sel_hi:[1,0]
	v_cvt_pk_bf16_f32 v96, v96, v97
	v_cvt_pk_bf16_f32 v97, v106, v107
	global_store_dwordx4 v[110:111], v[94:97], off offset:256
	v_pk_add_f32 v[72:73], v[72:73], 0 op_sel_hi:[1,0]
	v_pk_add_f32 v[64:65], v[64:65], 0 op_sel_hi:[1,0]
	v_or_b32_e32 v94, 32, v158
	v_mad_i64_i32 v[94:95], s[2:3], v94, s46, v[144:145]
	v_pk_add_f32 v[96:97], v[100:101], 0 op_sel_hi:[1,0]
	v_pk_add_f32 v[100:101], v[92:93], 0 op_sel_hi:[1,0]
	v_pk_add_f32 v[92:93], v[90:91], 0 op_sel_hi:[1,0]
	v_cvt_pk_bf16_f32 v90, v98, v99
	v_cvt_pk_bf16_f32 v91, v96, v97
	v_pk_add_f32 v[62:63], v[62:63], 0 op_sel_hi:[1,0]
	v_cvt_pk_bf16_f32 v92, v92, v93
	v_cvt_pk_bf16_f32 v93, v100, v101
	global_store_dwordx4 v[94:95], v[90:93], off
	v_pk_add_f32 v[54:55], v[54:55], 0 op_sel_hi:[1,0]
	v_pk_add_f32 v[56:57], v[56:57], 0 op_sel_hi:[1,0]
	v_pk_add_f32 v[90:91], v[80:81], 0 op_sel_hi:[1,0]
	v_pk_add_f32 v[80:81], v[78:79], 0 op_sel_hi:[1,0]
	v_cvt_pk_bf16_f32 v78, v86, v87
	v_cvt_pk_bf16_f32 v79, v88, v89
	v_pk_add_f32 v[50:51], v[50:51], 0 op_sel_hi:[1,0]
	v_cvt_pk_bf16_f32 v80, v80, v81
	v_cvt_pk_bf16_f32 v81, v90, v91
	global_store_dwordx4 v[94:95], v[78:81], off offset:256
	v_pk_add_f32 v[38:39], v[38:39], 0 op_sel_hi:[1,0]
	v_pk_add_f32 v[40:41], v[40:41], 0 op_sel_hi:[1,0]
	v_or_b32_e32 v78, 48, v158
	v_mad_i64_i32 v[78:79], s[2:3], v78, s46, v[144:145]
	v_pk_add_f32 v[80:81], v[84:85], 0 op_sel_hi:[1,0]
	v_pk_add_f32 v[84:85], v[76:77], 0 op_sel_hi:[1,0]
	v_pk_add_f32 v[76:77], v[74:75], 0 op_sel_hi:[1,0]
	v_cvt_pk_bf16_f32 v74, v82, v83
	v_cvt_pk_bf16_f32 v75, v80, v81
	v_pk_add_f32 v[34:35], v[34:35], 0 op_sel_hi:[1,0]
	v_cvt_pk_bf16_f32 v76, v76, v77
	v_cvt_pk_bf16_f32 v77, v84, v85
	global_store_dwordx4 v[78:79], v[74:77], off
	v_pk_add_f32 v[22:23], v[22:23], 0 op_sel_hi:[1,0]
	v_pk_add_f32 v[24:25], v[24:25], 0 op_sel_hi:[1,0]
	v_pk_add_f32 v[74:75], v[68:69], 0 op_sel_hi:[1,0]
	v_pk_add_f32 v[68:69], v[66:67], 0 op_sel_hi:[1,0]
	v_cvt_pk_bf16_f32 v66, v70, v71
	v_cvt_pk_bf16_f32 v67, v72, v73
	v_pk_add_f32 v[18:19], v[18:19], 0 op_sel_hi:[1,0]
	v_cvt_pk_bf16_f32 v68, v68, v69
	v_cvt_pk_bf16_f32 v69, v74, v75
	global_store_dwordx4 v[78:79], v[66:69], off offset:256
	s_andn2_b64 vcc, exec, s[18:19]
	v_pk_add_f32 v[8:9], v[8:9], 0 op_sel_hi:[1,0]
	v_add_u32_e32 v66, 0x80, v158
	v_mad_i64_i32 v[66:67], s[2:3], v66, s46, v[144:145]
	v_pk_add_f32 v[68:69], v[60:61], 0 op_sel_hi:[1,0]
	v_pk_add_f32 v[60:61], v[58:59], 0 op_sel_hi:[1,0]
	v_cvt_pk_bf16_f32 v58, v62, v63
	v_cvt_pk_bf16_f32 v59, v64, v65
	v_pk_add_f32 v[6:7], v[6:7], 0 op_sel_hi:[1,0]
	v_cvt_pk_bf16_f32 v60, v60, v61
	v_cvt_pk_bf16_f32 v61, v68, v69
	global_store_dwordx4 v[66:67], v[58:61], off
	s_nop 1
	v_pk_add_f32 v[58:59], v[48:49], 0 op_sel_hi:[1,0]
	v_pk_add_f32 v[48:49], v[46:47], 0 op_sel_hi:[1,0]
	v_cvt_pk_bf16_f32 v46, v54, v55
	v_cvt_pk_bf16_f32 v47, v56, v57
	s_nop 0
	v_cvt_pk_bf16_f32 v48, v48, v49
	v_cvt_pk_bf16_f32 v49, v58, v59
	global_store_dwordx4 v[66:67], v[46:49], off offset:256
	s_nop 1
	v_add_u32_e32 v46, 0x90, v158
	v_mad_i64_i32 v[46:47], s[2:3], v46, s46, v[144:145]
	v_pk_add_f32 v[48:49], v[52:53], 0 op_sel_hi:[1,0]
	v_pk_add_f32 v[52:53], v[44:45], 0 op_sel_hi:[1,0]
	v_pk_add_f32 v[44:45], v[42:43], 0 op_sel_hi:[1,0]
	v_cvt_pk_bf16_f32 v42, v50, v51
	v_cvt_pk_bf16_f32 v43, v48, v49
	s_nop 0
	v_cvt_pk_bf16_f32 v44, v44, v45
	v_cvt_pk_bf16_f32 v45, v52, v53
	global_store_dwordx4 v[46:47], v[42:45], off
	s_nop 1
	v_pk_add_f32 v[42:43], v[32:33], 0 op_sel_hi:[1,0]
	v_pk_add_f32 v[32:33], v[30:31], 0 op_sel_hi:[1,0]
	v_cvt_pk_bf16_f32 v30, v38, v39
	v_cvt_pk_bf16_f32 v31, v40, v41
	s_nop 0
	v_cvt_pk_bf16_f32 v32, v32, v33
	v_cvt_pk_bf16_f32 v33, v42, v43
	global_store_dwordx4 v[46:47], v[30:33], off offset:256
	s_nop 1
	v_add_u32_e32 v30, 0xa0, v158
	v_mad_i64_i32 v[30:31], s[2:3], v30, s46, v[144:145]
	v_pk_add_f32 v[32:33], v[36:37], 0 op_sel_hi:[1,0]
	v_pk_add_f32 v[36:37], v[28:29], 0 op_sel_hi:[1,0]
	v_pk_add_f32 v[28:29], v[26:27], 0 op_sel_hi:[1,0]
	v_cvt_pk_bf16_f32 v26, v34, v35
	v_cvt_pk_bf16_f32 v27, v32, v33
	s_nop 0
	v_cvt_pk_bf16_f32 v28, v28, v29
	v_cvt_pk_bf16_f32 v29, v36, v37
	global_store_dwordx4 v[30:31], v[26:29], off
	s_nop 1
	v_pk_add_f32 v[26:27], v[16:17], 0 op_sel_hi:[1,0]
	v_pk_add_f32 v[16:17], v[14:15], 0 op_sel_hi:[1,0]
	v_cvt_pk_bf16_f32 v14, v22, v23
	v_cvt_pk_bf16_f32 v15, v24, v25
	s_nop 0
	v_cvt_pk_bf16_f32 v16, v16, v17
	v_cvt_pk_bf16_f32 v17, v26, v27
	global_store_dwordx4 v[30:31], v[14:17], off offset:256
	s_nop 1
	v_add_u32_e32 v14, 0xb0, v158
	v_mad_i64_i32 v[14:15], s[2:3], v14, s46, v[144:145]
	v_pk_add_f32 v[16:17], v[20:21], 0 op_sel_hi:[1,0]
	v_pk_add_f32 v[20:21], v[12:13], 0 op_sel_hi:[1,0]
	v_pk_add_f32 v[12:13], v[10:11], 0 op_sel_hi:[1,0]
	v_cvt_pk_bf16_f32 v10, v18, v19
	v_cvt_pk_bf16_f32 v11, v16, v17
	s_mov_b64 s[2:3], -1
	v_cvt_pk_bf16_f32 v12, v12, v13
	v_cvt_pk_bf16_f32 v13, v20, v21
	global_store_dwordx4 v[14:15], v[10:13], off
	s_nop 1
	v_pk_add_f32 v[10:11], v[4:5], 0 op_sel_hi:[1,0]
	v_pk_add_f32 v[4:5], v[2:3], 0 op_sel_hi:[1,0]
	v_cvt_pk_bf16_f32 v2, v6, v7
	v_cvt_pk_bf16_f32 v3, v8, v9
	s_nop 0
	v_cvt_pk_bf16_f32 v4, v4, v5
	v_cvt_pk_bf16_f32 v5, v10, v11
	global_store_dwordx4 v[14:15], v[2:5], off offset:256
	s_cbranch_vccnz .LBB0_550
	s_andn2_b64 vcc, exec, s[0:1]
	s_cbranch_vccnz .LBB0_549
	s_branch .LBB0_549

.LBB0_1097:
	s_lshl_b64 s[2:3], s[18:19], 1
	s_add_u32 s24, s90, s2
	s_addc_u32 s25, s91, s3
	s_and_b64 s[2:3], s[22:23], exec
	s_cselect_b32 s15, s25, s31
	s_cselect_b32 s17, s24, s30
	s_lshl_b64 s[2:3], s[20:21], 1
	s_add_u32 s26, s37, s2
	s_addc_u32 s27, s38, s3
	s_and_b64 s[2:3], s[22:23], exec
	s_cselect_b32 s52, s27, s35
	s_cselect_b32 s53, s26, s34
	s_add_u32 s30, s30, 0x40080
	s_addc_u32 s31, s31, 0
	s_add_u32 s54, s34, 0x100
	s_addc_u32 s55, s35, 0
	s_mov_b32 s56, -2
	s_cmp_lt_u32 s43, 2
	s_cbranch_scc1 .Lz1s1098
	s_andn2_b64 vcc, exec, s[4:5]
	s_cbranch_vccnz .Lz1s1098
	s_barrier
.Lz1s1098:
.Lpk1098_peel:
	ds_read_b128 v[152:155], v148
	ds_read_b128 v[156:159], v148 offset:1024
	ds_read_b128 v[160:163], v148 offset:2048
	ds_read_b128 v[164:167], v148 offset:3072
	ds_read_b128 v[168:171], v149
	ds_read_b128 v[172:175], v149 offset:1024
	ds_read_b128 v[178:181], v149 offset:2048
	ds_read_b128 v[182:185], v149 offset:3072
	s_add_u32 s2, s30, 0xfffc0080
	s_addc_u32 s3, s31, -1
	s_cmp_eq_u32 s56, 12
	s_cselect_b32 s3, s15, s3
	s_cselect_b32 s2, s17, s2
	s_cselect_b32 s35, s52, s55
	s_cselect_b32 s34, s53, s54
	v_lshl_add_u64 v[144:145], s[30:31], 0, v[138:139]
	s_add_i32 m0, s40, 0xc000
	ds_read_b128 v[186:189], v150
	ds_read_b128 v[190:193], v150 offset:1024
	ds_read_b128 v[194:197], v150 offset:2048
	ds_read_b128 v[198:201], v150 offset:3072
	ds_read_b128 v[202:205], v150 offset:4096
	ds_read_b128 v[206:209], v150 offset:5120
	ds_read_b128 v[210:213], v150 offset:6144
	ds_read_b128 v[214:217], v150 offset:7168
	global_load_lds_dwordx4 v[144:145], off
	v_lshl_add_u64 v[144:145], s[30:31], 0, v[140:141]
	s_add_i32 m0, s40, 0xe000
	s_nop 0
	global_load_lds_dwordx4 v[144:145], off
	s_waitcnt vmcnt(8)
	s_waitcnt lgkmcnt(0)
	s_setprio 1
	s_barrier
	v_mfma_f32_16x16x32_bf16 v[126:129], v[152:155], v[186:189], 0
	v_mfma_f32_16x16x32_bf16 v[122:125], v[160:163], v[186:189], 0
	v_mfma_f32_16x16x32_bf16 v[114:117], v[152:155], v[194:197], 0
	v_mfma_f32_16x16x32_bf16 v[106:109], v[160:163], v[194:197], 0
	v_mfma_f32_16x16x32_bf16 v[98:101], v[152:155], v[202:205], 0
	v_mfma_f32_16x16x32_bf16 v[90:93], v[160:163], v[202:205], 0
	v_mfma_f32_16x16x32_bf16 v[82:85], v[152:155], v[210:213], 0
	v_mfma_f32_16x16x32_bf16 v[74:77], v[160:163], v[210:213], 0
	v_mfma_f32_16x16x32_bf16 v[126:129], v[156:159], v[190:193], v[126:129]
	v_mfma_f32_16x16x32_bf16 v[122:125], v[164:167], v[190:193], v[122:125]
	v_mfma_f32_16x16x32_bf16 v[114:117], v[156:159], v[198:201], v[114:117]
	v_mfma_f32_16x16x32_bf16 v[106:109], v[164:167], v[198:201], v[106:109]
	v_mfma_f32_16x16x32_bf16 v[98:101], v[156:159], v[206:209], v[98:101]
	v_mfma_f32_16x16x32_bf16 v[90:93], v[164:167], v[206:209], v[90:93]
	v_mfma_f32_16x16x32_bf16 v[82:85], v[156:159], v[214:217], v[82:85]
	v_mfma_f32_16x16x32_bf16 v[74:77], v[164:167], v[214:217], v[74:77]
	v_mfma_f32_16x16x32_bf16 v[118:121], v[168:171], v[186:189], 0
	v_mfma_f32_16x16x32_bf16 v[110:113], v[178:181], v[186:189], 0
	v_mfma_f32_16x16x32_bf16 v[102:105], v[168:171], v[194:197], 0
	v_mfma_f32_16x16x32_bf16 v[94:97], v[178:181], v[194:197], 0
	v_mfma_f32_16x16x32_bf16 v[86:89], v[168:171], v[202:205], 0
	v_mfma_f32_16x16x32_bf16 v[78:81], v[178:181], v[202:205], 0
	v_mfma_f32_16x16x32_bf16 v[70:73], v[168:171], v[210:213], 0
	v_mfma_f32_16x16x32_bf16 v[66:69], v[178:181], v[210:213], 0
	v_mfma_f32_16x16x32_bf16 v[118:121], v[172:175], v[190:193], v[118:121]
	v_mfma_f32_16x16x32_bf16 v[110:113], v[182:185], v[190:193], v[110:113]
	v_mfma_f32_16x16x32_bf16 v[102:105], v[172:175], v[198:201], v[102:105]
	v_mfma_f32_16x16x32_bf16 v[94:97], v[182:185], v[198:201], v[94:97]
	v_mfma_f32_16x16x32_bf16 v[86:89], v[172:175], v[206:209], v[86:89]
	v_mfma_f32_16x16x32_bf16 v[78:81], v[182:185], v[206:209], v[78:81]
	v_mfma_f32_16x16x32_bf16 v[70:73], v[172:175], v[214:217], v[70:73]
	v_mfma_f32_16x16x32_bf16 v[66:69], v[182:185], v[214:217], v[66:69]
	s_barrier
	s_setprio 0
	s_add_i32 s57, s47, s39
	v_lshl_add_u64 v[144:145], s[34:35], 0, v[132:133]
	s_mov_b32 m0, s57
	ds_read_b128 v[186:189], v150 offset:16384
	ds_read_b128 v[190:193], v150 offset:17408
	ds_read_b128 v[194:197], v150 offset:18432
	ds_read_b128 v[198:201], v150 offset:19456
	ds_read_b128 v[202:205], v150 offset:20480
	ds_read_b128 v[206:209], v150 offset:21504
	ds_read_b128 v[210:213], v150 offset:22528
	ds_read_b128 v[214:217], v150 offset:23552
	global_load_lds_dwordx4 v[144:145], off
	s_add_i32 m0, s57, 0x2000
	s_add_u32 s58, s34, 0x40000
	v_lshl_add_u64 v[218:219], s[34:35], 0, v[136:137]
	s_addc_u32 s59, s35, 0
	s_add_i32 s57, s48, s39
	global_load_lds_dwordx4 v[218:219], off
	v_lshl_add_u64 v[220:221], s[58:59], 0, v[132:133]
	s_mov_b32 m0, s57
	v_lshl_add_u64 v[222:223], s[2:3], 0, v[134:135]
	global_load_lds_dwordx4 v[220:221], off
	v_lshl_add_u64 v[220:221], s[58:59], 0, v[136:137]
	s_add_i32 m0, s57, 0x2000
	s_nop 0
	global_load_lds_dwordx4 v[220:221], off
	v_lshl_add_u64 v[220:221], s[2:3], 0, v[130:131]
	s_mov_b32 m0, s40
	s_nop 0
	global_load_lds_dwordx4 v[220:221], off
	s_mov_b32 m0, s29
	s_nop 0
	global_load_lds_dwordx4 v[222:223], off
	s_waitcnt vmcnt(8)
	s_waitcnt lgkmcnt(0)
	s_setprio 1
	s_barrier
	v_mfma_f32_16x16x32_bf16 v[62:65], v[152:155], v[186:189], 0
	v_mfma_f32_16x16x32_bf16 v[58:61], v[160:163], v[186:189], 0
	v_mfma_f32_16x16x32_bf16 v[50:53], v[152:155], v[194:197], 0
	v_mfma_f32_16x16x32_bf16 v[42:45], v[160:163], v[194:197], 0
	v_mfma_f32_16x16x32_bf16 v[34:37], v[152:155], v[202:205], 0
	v_mfma_f32_16x16x32_bf16 v[26:29], v[160:163], v[202:205], 0
	v_mfma_f32_16x16x32_bf16 v[18:21], v[152:155], v[210:213], 0
	v_mfma_f32_16x16x32_bf16 v[10:13], v[160:163], v[210:213], 0
	v_mfma_f32_16x16x32_bf16 v[62:65], v[156:159], v[190:193], v[62:65]
	v_mfma_f32_16x16x32_bf16 v[58:61], v[164:167], v[190:193], v[58:61]
	v_mfma_f32_16x16x32_bf16 v[50:53], v[156:159], v[198:201], v[50:53]
	v_mfma_f32_16x16x32_bf16 v[42:45], v[164:167], v[198:201], v[42:45]
	v_mfma_f32_16x16x32_bf16 v[34:37], v[156:159], v[206:209], v[34:37]
	v_mfma_f32_16x16x32_bf16 v[26:29], v[164:167], v[206:209], v[26:29]
	v_mfma_f32_16x16x32_bf16 v[18:21], v[156:159], v[214:217], v[18:21]
	v_mfma_f32_16x16x32_bf16 v[10:13], v[164:167], v[214:217], v[10:13]
	v_mfma_f32_16x16x32_bf16 v[54:57], v[168:171], v[186:189], 0
	v_mfma_f32_16x16x32_bf16 v[46:49], v[178:181], v[186:189], 0
	v_mfma_f32_16x16x32_bf16 v[38:41], v[168:171], v[194:197], 0
	v_mfma_f32_16x16x32_bf16 v[30:33], v[178:181], v[194:197], 0
	v_mfma_f32_16x16x32_bf16 v[22:25], v[168:171], v[202:205], 0
	v_mfma_f32_16x16x32_bf16 v[14:17], v[178:181], v[202:205], 0
	v_mfma_f32_16x16x32_bf16 v[6:9], v[168:171], v[210:213], 0
	v_mfma_f32_16x16x32_bf16 v[2:5], v[178:181], v[210:213], 0
	v_mfma_f32_16x16x32_bf16 v[54:57], v[172:175], v[190:193], v[54:57]
	v_mfma_f32_16x16x32_bf16 v[46:49], v[182:185], v[190:193], v[46:49]
	v_mfma_f32_16x16x32_bf16 v[38:41], v[172:175], v[198:201], v[38:41]
	v_mfma_f32_16x16x32_bf16 v[30:33], v[182:185], v[198:201], v[30:33]
	v_mfma_f32_16x16x32_bf16 v[22:25], v[172:175], v[206:209], v[22:25]
	v_mfma_f32_16x16x32_bf16 v[14:17], v[182:185], v[206:209], v[14:17]
	v_mfma_f32_16x16x32_bf16 v[6:9], v[172:175], v[214:217], v[6:9]
	v_mfma_f32_16x16x32_bf16 v[2:5], v[182:185], v[214:217], v[2:5]
	s_barrier
	s_setprio 0
	s_add_i32 s57, 0, 0x18000
	v_add_u32_e32 v151, s57, v146
	s_add_i32 s58, 0, 0x1c000
	ds_read_b128 v[152:155], v151
	ds_read_b128 v[156:159], v151 offset:1024
	ds_read_b128 v[160:163], v151 offset:2048
	ds_read_b128 v[164:167], v151 offset:3072
	v_add_u32_e32 v151, s58, v146
	ds_read_b128 v[168:171], v151
	ds_read_b128 v[172:175], v151 offset:1024
	ds_read_b128 v[178:181], v151 offset:2048
	ds_read_b128 v[182:185], v151 offset:3072
	s_add_u32 s2, s2, 0x40000
	s_addc_u32 s3, s3, 0
	s_mov_b32 m0, s41
	v_lshl_add_u64 v[224:225], s[2:3], 0, v[130:131]
	ds_read_b128 v[186:189], v150 offset:32768
	ds_read_b128 v[190:193], v150 offset:33792
	ds_read_b128 v[194:197], v150 offset:34816
	ds_read_b128 v[198:201], v150 offset:35840
	ds_read_b128 v[202:205], v150 offset:36864
	ds_read_b128 v[206:209], v150 offset:37888
	ds_read_b128 v[210:213], v150 offset:38912
	ds_read_b128 v[214:217], v150 offset:39936
	global_load_lds_dwordx4 v[224:225], off
	v_lshl_add_u64 v[224:225], s[2:3], 0, v[134:135]
	s_mov_b32 m0, s42
	s_nop 0
	global_load_lds_dwordx4 v[224:225], off
	s_waitcnt vmcnt(8)
	s_waitcnt lgkmcnt(0)
	s_setprio 1
	s_barrier
	v_mfma_f32_16x16x32_bf16 v[126:129], v[152:155], v[186:189], v[126:129]
	v_mfma_f32_16x16x32_bf16 v[122:125], v[160:163], v[186:189], v[122:125]
	v_mfma_f32_16x16x32_bf16 v[114:117], v[152:155], v[194:197], v[114:117]
	v_mfma_f32_16x16x32_bf16 v[106:109], v[160:163], v[194:197], v[106:109]
	v_mfma_f32_16x16x32_bf16 v[98:101], v[152:155], v[202:205], v[98:101]
	v_mfma_f32_16x16x32_bf16 v[90:93], v[160:163], v[202:205], v[90:93]
	v_mfma_f32_16x16x32_bf16 v[82:85], v[152:155], v[210:213], v[82:85]
	v_mfma_f32_16x16x32_bf16 v[74:77], v[160:163], v[210:213], v[74:77]
	v_mfma_f32_16x16x32_bf16 v[126:129], v[156:159], v[190:193], v[126:129]
	v_mfma_f32_16x16x32_bf16 v[122:125], v[164:167], v[190:193], v[122:125]
	v_mfma_f32_16x16x32_bf16 v[114:117], v[156:159], v[198:201], v[114:117]
	v_mfma_f32_16x16x32_bf16 v[106:109], v[164:167], v[198:201], v[106:109]
	v_mfma_f32_16x16x32_bf16 v[98:101], v[156:159], v[206:209], v[98:101]
	v_mfma_f32_16x16x32_bf16 v[90:93], v[164:167], v[206:209], v[90:93]
	v_mfma_f32_16x16x32_bf16 v[82:85], v[156:159], v[214:217], v[82:85]
	v_mfma_f32_16x16x32_bf16 v[74:77], v[164:167], v[214:217], v[74:77]
	v_mfma_f32_16x16x32_bf16 v[118:121], v[168:171], v[186:189], v[118:121]
	v_mfma_f32_16x16x32_bf16 v[110:113], v[178:181], v[186:189], v[110:113]
	v_mfma_f32_16x16x32_bf16 v[102:105], v[168:171], v[194:197], v[102:105]
	v_mfma_f32_16x16x32_bf16 v[94:97], v[178:181], v[194:197], v[94:97]
	v_mfma_f32_16x16x32_bf16 v[86:89], v[168:171], v[202:205], v[86:89]
	v_mfma_f32_16x16x32_bf16 v[78:81], v[178:181], v[202:205], v[78:81]
	v_mfma_f32_16x16x32_bf16 v[70:73], v[168:171], v[210:213], v[70:73]
	v_mfma_f32_16x16x32_bf16 v[66:69], v[178:181], v[210:213], v[66:69]
	v_mfma_f32_16x16x32_bf16 v[118:121], v[172:175], v[190:193], v[118:121]
	v_mfma_f32_16x16x32_bf16 v[110:113], v[182:185], v[190:193], v[110:113]
	v_mfma_f32_16x16x32_bf16 v[102:105], v[172:175], v[198:201], v[102:105]
	v_mfma_f32_16x16x32_bf16 v[94:97], v[182:185], v[198:201], v[94:97]
	v_mfma_f32_16x16x32_bf16 v[86:89], v[172:175], v[206:209], v[86:89]
	v_mfma_f32_16x16x32_bf16 v[78:81], v[182:185], v[206:209], v[78:81]
	v_mfma_f32_16x16x32_bf16 v[70:73], v[172:175], v[214:217], v[70:73]
	v_mfma_f32_16x16x32_bf16 v[66:69], v[182:185], v[214:217], v[66:69]
	s_barrier
	s_setprio 0
	s_add_i32 s2, s57, s39
	v_lshl_add_u64 v[144:145], v[144:145], 0, s[6:7]
	s_mov_b32 m0, s2
	ds_read_b128 v[186:189], v150 offset:49152
	ds_read_b128 v[190:193], v150 offset:50176
	ds_read_b128 v[194:197], v150 offset:51200
	ds_read_b128 v[198:201], v150 offset:52224
	ds_read_b128 v[202:205], v150 offset:53248
	ds_read_b128 v[206:209], v150 offset:54272
	ds_read_b128 v[210:213], v150 offset:55296
	ds_read_b128 v[214:217], v150 offset:56320
	global_load_lds_dwordx4 v[144:145], off
	s_add_i32 m0, s2, 0x2000
	s_add_u32 s2, s34, 0x40080
	v_lshl_add_u64 v[144:145], v[218:219], 0, s[6:7]
	s_addc_u32 s3, s35, 0
	s_add_i32 s34, s58, s39
	global_load_lds_dwordx4 v[144:145], off
	v_lshl_add_u64 v[144:145], s[2:3], 0, v[132:133]
	s_mov_b32 m0, s34
	s_nop 0
	global_load_lds_dwordx4 v[144:145], off
	v_lshl_add_u64 v[144:145], s[2:3], 0, v[136:137]
	s_add_i32 m0, s34, 0x2000
	s_nop 0
	global_load_lds_dwordx4 v[144:145], off
	v_lshl_add_u64 v[144:145], v[220:221], 0, s[6:7]
	s_mov_b32 m0, s44
	s_nop 0
	global_load_lds_dwordx4 v[144:145], off
	v_lshl_add_u64 v[144:145], v[222:223], 0, s[6:7]
	s_mov_b32 m0, s45
	s_nop 0
	global_load_lds_dwordx4 v[144:145], off
	s_waitcnt vmcnt(8)
	s_waitcnt lgkmcnt(0)
	s_setprio 1
	s_barrier
	v_mfma_f32_16x16x32_bf16 v[62:65], v[152:155], v[186:189], v[62:65]
	v_mfma_f32_16x16x32_bf16 v[58:61], v[160:163], v[186:189], v[58:61]
	v_mfma_f32_16x16x32_bf16 v[50:53], v[152:155], v[194:197], v[50:53]
	v_mfma_f32_16x16x32_bf16 v[42:45], v[160:163], v[194:197], v[42:45]
	v_mfma_f32_16x16x32_bf16 v[34:37], v[152:155], v[202:205], v[34:37]
	v_mfma_f32_16x16x32_bf16 v[26:29], v[160:163], v[202:205], v[26:29]
	v_mfma_f32_16x16x32_bf16 v[18:21], v[152:155], v[210:213], v[18:21]
	v_mfma_f32_16x16x32_bf16 v[10:13], v[160:163], v[210:213], v[10:13]
	v_mfma_f32_16x16x32_bf16 v[62:65], v[156:159], v[190:193], v[62:65]
	v_mfma_f32_16x16x32_bf16 v[58:61], v[164:167], v[190:193], v[58:61]
	v_mfma_f32_16x16x32_bf16 v[50:53], v[156:159], v[198:201], v[50:53]
	v_mfma_f32_16x16x32_bf16 v[42:45], v[164:167], v[198:201], v[42:45]
	v_mfma_f32_16x16x32_bf16 v[34:37], v[156:159], v[206:209], v[34:37]
	v_mfma_f32_16x16x32_bf16 v[26:29], v[164:167], v[206:209], v[26:29]
	v_mfma_f32_16x16x32_bf16 v[18:21], v[156:159], v[214:217], v[18:21]
	v_mfma_f32_16x16x32_bf16 v[10:13], v[164:167], v[214:217], v[10:13]
	v_mfma_f32_16x16x32_bf16 v[54:57], v[168:171], v[186:189], v[54:57]
	v_mfma_f32_16x16x32_bf16 v[46:49], v[178:181], v[186:189], v[46:49]
	v_mfma_f32_16x16x32_bf16 v[38:41], v[168:171], v[194:197], v[38:41]
	v_mfma_f32_16x16x32_bf16 v[30:33], v[178:181], v[194:197], v[30:33]
	v_mfma_f32_16x16x32_bf16 v[22:25], v[168:171], v[202:205], v[22:25]
	v_mfma_f32_16x16x32_bf16 v[14:17], v[178:181], v[202:205], v[14:17]
	v_mfma_f32_16x16x32_bf16 v[6:9], v[168:171], v[210:213], v[6:9]
	v_mfma_f32_16x16x32_bf16 v[2:5], v[178:181], v[210:213], v[2:5]
	v_mfma_f32_16x16x32_bf16 v[54:57], v[172:175], v[190:193], v[54:57]
	v_mfma_f32_16x16x32_bf16 v[46:49], v[182:185], v[190:193], v[46:49]
	v_mfma_f32_16x16x32_bf16 v[38:41], v[172:175], v[198:201], v[38:41]
	v_mfma_f32_16x16x32_bf16 v[30:33], v[182:185], v[198:201], v[30:33]
	v_mfma_f32_16x16x32_bf16 v[22:25], v[172:175], v[206:209], v[22:25]
	v_mfma_f32_16x16x32_bf16 v[14:17], v[182:185], v[206:209], v[14:17]
	v_mfma_f32_16x16x32_bf16 v[6:9], v[172:175], v[214:217], v[6:9]
	v_mfma_f32_16x16x32_bf16 v[2:5], v[182:185], v[214:217], v[2:5]
	s_barrier
	s_setprio 0
	s_add_i32 s56, s56, 2
	s_add_u32 s30, s30, 0x100
	s_addc_u32 s31, s31, 0
	s_add_u32 s54, s54, 0x100
	s_addc_u32 s55, s55, 0
	s_cmp_gt_u32 s56, 13
	s_cbranch_scc0 .LBB0_1098
	s_branch .Lpk1098_exit

.LBB0_1101:
	v_lshl_add_u32 v152, s28, 8, v1
	v_lshl_or_b32 v144, s51, 8, v147
	v_readlane_b32 s2, v252, 2
	v_ashrrev_i32_e32 v145, 31, v144
	v_readlane_b32 s3, v252, 3
	v_ashrrev_i32_e32 v153, 31, v152
	v_pk_add_f32 v[128:129], v[128:129], 0 op_sel_hi:[1,0]
	v_lshl_add_u64 v[154:155], v[144:145], 1, s[2:3]
	v_lshlrev_b64 v[144:145], 11, v[152:153]
	v_lshl_add_u64 v[144:145], v[154:155], 0, v[144:145]
	v_pk_add_f32 v[126:127], v[126:127], 0 op_sel_hi:[1,0]
	v_pk_add_f32 v[156:157], v[124:125], 0 op_sel_hi:[1,0]
	v_pk_add_f32 v[124:125], v[122:123], 0 op_sel_hi:[1,0]
	v_cvt_pk_bf16_f32 v122, v126, v127
	v_cvt_pk_bf16_f32 v123, v128, v129
	v_pk_add_f32 v[118:119], v[118:119], 0 op_sel_hi:[1,0]
	v_cvt_pk_bf16_f32 v124, v124, v125
	v_cvt_pk_bf16_f32 v125, v156, v157
	global_store_dwordx4 v[144:145], v[122:125], off
	v_pk_add_f32 v[120:121], v[120:121], 0 op_sel_hi:[1,0]
	v_pk_add_f32 v[114:115], v[114:115], 0 op_sel_hi:[1,0]
	v_pk_add_f32 v[122:123], v[112:113], 0 op_sel_hi:[1,0]
	v_pk_add_f32 v[112:113], v[110:111], 0 op_sel_hi:[1,0]
	v_cvt_pk_bf16_f32 v110, v118, v119
	v_cvt_pk_bf16_f32 v111, v120, v121
	v_pk_add_f32 v[102:103], v[102:103], 0 op_sel_hi:[1,0]
	v_cvt_pk_bf16_f32 v112, v112, v113
	v_cvt_pk_bf16_f32 v113, v122, v123
	global_store_dwordx4 v[144:145], v[110:113], off offset:256
	v_pk_add_f32 v[104:105], v[104:105], 0 op_sel_hi:[1,0]
	v_pk_add_f32 v[98:99], v[98:99], 0 op_sel_hi:[1,0]
	v_or_b32_e32 v110, 16, v152
	v_ashrrev_i32_e32 v111, 31, v110
	v_lshlrev_b64 v[110:111], 11, v[110:111]
	v_lshl_add_u64 v[110:111], v[154:155], 0, v[110:111]
	v_pk_add_f32 v[112:113], v[116:117], 0 op_sel_hi:[1,0]
	v_pk_add_f32 v[116:117], v[108:109], 0 op_sel_hi:[1,0]
	v_pk_add_f32 v[108:109], v[106:107], 0 op_sel_hi:[1,0]
	v_cvt_pk_bf16_f32 v106, v114, v115
	v_cvt_pk_bf16_f32 v107, v112, v113
	v_pk_add_f32 v[86:87], v[86:87], 0 op_sel_hi:[1,0]
	v_cvt_pk_bf16_f32 v108, v108, v109
	v_cvt_pk_bf16_f32 v109, v116, v117
	global_store_dwordx4 v[110:111], v[106:109], off
	v_pk_add_f32 v[88:89], v[88:89], 0 op_sel_hi:[1,0]
	v_pk_add_f32 v[82:83], v[82:83], 0 op_sel_hi:[1,0]
	v_pk_add_f32 v[106:107], v[96:97], 0 op_sel_hi:[1,0]
	v_pk_add_f32 v[96:97], v[94:95], 0 op_sel_hi:[1,0]
	v_cvt_pk_bf16_f32 v94, v102, v103
	v_cvt_pk_bf16_f32 v95, v104, v105
	v_pk_add_f32 v[72:73], v[72:73], 0 op_sel_hi:[1,0]
	v_cvt_pk_bf16_f32 v96, v96, v97
	v_cvt_pk_bf16_f32 v97, v106, v107
	global_store_dwordx4 v[110:111], v[94:97], off offset:256
	v_pk_add_f32 v[70:71], v[70:71], 0 op_sel_hi:[1,0]
	s_mov_b64 s[2:3], 0x40000
	v_or_b32_e32 v94, 32, v152
	v_ashrrev_i32_e32 v95, 31, v94
	v_lshlrev_b64 v[94:95], 11, v[94:95]
	v_lshl_add_u64 v[94:95], v[154:155], 0, v[94:95]
	v_pk_add_f32 v[96:97], v[100:101], 0 op_sel_hi:[1,0]
	v_pk_add_f32 v[100:101], v[92:93], 0 op_sel_hi:[1,0]
	v_pk_add_f32 v[92:93], v[90:91], 0 op_sel_hi:[1,0]
	v_cvt_pk_bf16_f32 v90, v98, v99
	v_cvt_pk_bf16_f32 v91, v96, v97
	v_pk_add_f32 v[62:63], v[62:63], 0 op_sel_hi:[1,0]
	v_cvt_pk_bf16_f32 v92, v92, v93
	v_cvt_pk_bf16_f32 v93, v100, v101
	global_store_dwordx4 v[94:95], v[90:93], off
	v_pk_add_f32 v[64:65], v[64:65], 0 op_sel_hi:[1,0]
	v_pk_add_f32 v[56:57], v[56:57], 0 op_sel_hi:[1,0]
	v_pk_add_f32 v[90:91], v[80:81], 0 op_sel_hi:[1,0]
	v_pk_add_f32 v[80:81], v[78:79], 0 op_sel_hi:[1,0]
	v_cvt_pk_bf16_f32 v78, v86, v87
	v_cvt_pk_bf16_f32 v79, v88, v89
	v_pk_add_f32 v[54:55], v[54:55], 0 op_sel_hi:[1,0]
	v_cvt_pk_bf16_f32 v80, v80, v81
	v_cvt_pk_bf16_f32 v81, v90, v91
	global_store_dwordx4 v[94:95], v[78:81], off offset:256
	v_pk_add_f32 v[50:51], v[50:51], 0 op_sel_hi:[1,0]
	v_pk_add_f32 v[40:41], v[40:41], 0 op_sel_hi:[1,0]
	v_or_b32_e32 v78, 48, v152
	v_ashrrev_i32_e32 v79, 31, v78
	v_lshlrev_b64 v[78:79], 11, v[78:79]
	v_lshl_add_u64 v[78:79], v[154:155], 0, v[78:79]
	v_pk_add_f32 v[80:81], v[84:85], 0 op_sel_hi:[1,0]
	v_pk_add_f32 v[84:85], v[76:77], 0 op_sel_hi:[1,0]
	v_pk_add_f32 v[76:77], v[74:75], 0 op_sel_hi:[1,0]
	v_cvt_pk_bf16_f32 v74, v82, v83
	v_cvt_pk_bf16_f32 v75, v80, v81
	v_pk_add_f32 v[38:39], v[38:39], 0 op_sel_hi:[1,0]
	v_cvt_pk_bf16_f32 v76, v76, v77
	v_cvt_pk_bf16_f32 v77, v84, v85
	global_store_dwordx4 v[78:79], v[74:77], off
	v_pk_add_f32 v[34:35], v[34:35], 0 op_sel_hi:[1,0]
	v_pk_add_f32 v[24:25], v[24:25], 0 op_sel_hi:[1,0]
	v_pk_add_f32 v[74:75], v[68:69], 0 op_sel_hi:[1,0]
	v_pk_add_f32 v[68:69], v[66:67], 0 op_sel_hi:[1,0]
	v_cvt_pk_bf16_f32 v66, v70, v71
	v_cvt_pk_bf16_f32 v67, v72, v73
	v_pk_add_f32 v[22:23], v[22:23], 0 op_sel_hi:[1,0]
	v_cvt_pk_bf16_f32 v68, v68, v69
	v_cvt_pk_bf16_f32 v69, v74, v75
	global_store_dwordx4 v[78:79], v[66:69], off offset:256
	v_pk_add_f32 v[18:19], v[18:19], 0 op_sel_hi:[1,0]
	v_pk_add_f32 v[8:9], v[8:9], 0 op_sel_hi:[1,0]
	v_lshl_add_u64 v[66:67], v[144:145], 0, s[2:3]
	s_mov_b32 s2, 0x40000
	v_pk_add_f32 v[68:69], v[60:61], 0 op_sel_hi:[1,0]
	v_pk_add_f32 v[60:61], v[58:59], 0 op_sel_hi:[1,0]
	v_cvt_pk_bf16_f32 v58, v62, v63
	v_add_co_u32_e32 v62, vcc, s2, v144
	v_cvt_pk_bf16_f32 v59, v64, v65
	v_cvt_pk_bf16_f32 v60, v60, v61
	v_cvt_pk_bf16_f32 v61, v68, v69
	s_mov_b64 s[2:3], 0x48000
	s_nop 0
	v_addc_co_u32_e32 v63, vcc, 0, v145, vcc
	global_store_dwordx4 v[62:63], v[58:61], off
	v_pk_add_f32 v[6:7], v[6:7], 0 op_sel_hi:[1,0]
	s_nop 0
	v_pk_add_f32 v[58:59], v[48:49], 0 op_sel_hi:[1,0]
	v_pk_add_f32 v[48:49], v[46:47], 0 op_sel_hi:[1,0]
	v_cvt_pk_bf16_f32 v46, v54, v55
	v_cvt_pk_bf16_f32 v47, v56, v57
	s_nop 0
	v_cvt_pk_bf16_f32 v48, v48, v49
	v_cvt_pk_bf16_f32 v49, v58, v59
	global_store_dwordx4 v[66:67], v[46:49], off offset:256
	s_nop 1
	v_lshl_add_u64 v[46:47], v[144:145], 0, s[2:3]
	v_pk_add_f32 v[48:49], v[52:53], 0 op_sel_hi:[1,0]
	s_mov_b32 s2, 0x48000
	v_pk_add_f32 v[52:53], v[44:45], 0 op_sel_hi:[1,0]
	v_pk_add_f32 v[44:45], v[42:43], 0 op_sel_hi:[1,0]
	v_cvt_pk_bf16_f32 v42, v50, v51
	v_cvt_pk_bf16_f32 v43, v48, v49
	v_add_co_u32_e32 v48, vcc, s2, v144
	v_cvt_pk_bf16_f32 v44, v44, v45
	v_cvt_pk_bf16_f32 v45, v52, v53
	s_mov_b64 s[2:3], -1
	s_nop 0
	v_addc_co_u32_e32 v49, vcc, 0, v145, vcc
	global_store_dwordx4 v[48:49], v[42:45], off
	s_nop 1
	v_pk_add_f32 v[42:43], v[32:33], 0 op_sel_hi:[1,0]
	v_pk_add_f32 v[32:33], v[30:31], 0 op_sel_hi:[1,0]
	v_cvt_pk_bf16_f32 v30, v38, v39
	v_cvt_pk_bf16_f32 v31, v40, v41
	s_nop 0
	v_cvt_pk_bf16_f32 v32, v32, v33
	v_cvt_pk_bf16_f32 v33, v42, v43
	global_store_dwordx4 v[46:47], v[30:33], off offset:256
	s_nop 1
	v_pk_add_f32 v[32:33], v[36:37], 0 op_sel_hi:[1,0]
	v_pk_add_f32 v[36:37], v[28:29], 0 op_sel_hi:[1,0]
	v_pk_add_f32 v[28:29], v[26:27], 0 op_sel_hi:[1,0]
	v_cvt_pk_bf16_f32 v26, v34, v35
	v_cvt_pk_bf16_f32 v27, v32, v33
	v_add_co_u32_e32 v32, vcc, s49, v144
	v_cvt_pk_bf16_f32 v28, v28, v29
	v_cvt_pk_bf16_f32 v29, v36, v37
	v_lshl_add_u64 v[30:31], v[144:145], 0, s[10:11]
	s_nop 0
	v_addc_co_u32_e32 v33, vcc, 0, v145, vcc
	global_store_dwordx4 v[32:33], v[26:29], off
	s_nop 1
	v_pk_add_f32 v[26:27], v[16:17], 0 op_sel_hi:[1,0]
	v_pk_add_f32 v[16:17], v[14:15], 0 op_sel_hi:[1,0]
	v_cvt_pk_bf16_f32 v14, v22, v23
	v_cvt_pk_bf16_f32 v15, v24, v25
	s_nop 0
	v_cvt_pk_bf16_f32 v16, v16, v17
	v_cvt_pk_bf16_f32 v17, v26, v27
	global_store_dwordx4 v[30:31], v[14:17], off offset:256
	s_nop 1
	v_pk_add_f32 v[16:17], v[20:21], 0 op_sel_hi:[1,0]
	v_pk_add_f32 v[20:21], v[12:13], 0 op_sel_hi:[1,0]
	v_pk_add_f32 v[12:13], v[10:11], 0 op_sel_hi:[1,0]
	v_cvt_pk_bf16_f32 v10, v18, v19
	v_cvt_pk_bf16_f32 v11, v16, v17
	v_add_co_u32_e32 v16, vcc, s50, v144
	v_lshl_add_u64 v[14:15], v[144:145], 0, s[12:13]
	s_nop 0
	v_addc_co_u32_e32 v17, vcc, 0, v145, vcc
	v_cvt_pk_bf16_f32 v12, v12, v13
	v_cvt_pk_bf16_f32 v13, v20, v21
	global_store_dwordx4 v[16:17], v[10:13], off
	s_andn2_b64 vcc, exec, s[22:23]
	s_nop 0
	v_pk_add_f32 v[10:11], v[4:5], 0 op_sel_hi:[1,0]
	v_pk_add_f32 v[4:5], v[2:3], 0 op_sel_hi:[1,0]
	v_cvt_pk_bf16_f32 v2, v6, v7
	v_cvt_pk_bf16_f32 v3, v8, v9
	s_nop 0
	v_cvt_pk_bf16_f32 v4, v4, v5
	v_cvt_pk_bf16_f32 v5, v10, v11
	global_store_dwordx4 v[14:15], v[2:5], off offset:256
	s_cbranch_vccnz .LBB0_1089
	s_andn2_b64 vcc, exec, s[4:5]
	s_cbranch_vccnz .LBB0_1088
	s_branch .LBB0_1088

.LBB0_1178:
	s_lshl_b64 s[2:3], s[22:23], 1
	v_readlane_b32 s28, v253, 52
	v_readlane_b32 s29, v253, 53
	s_add_u32 s28, s28, s2
	s_addc_u32 s29, s29, s3
	s_and_b64 s[2:3], s[26:27], exec
	s_cselect_b32 s19, s29, s37
	s_cselect_b32 s21, s28, s36
	s_lshl_b64 s[2:3], s[24:25], 1
	s_add_u32 s30, s35, s2
	s_addc_u32 s31, s40, s3
	s_and_b64 s[2:3], s[26:27], exec
	s_cselect_b32 s57, s31, s39
	s_cselect_b32 s58, s30, s38
	s_add_u32 s36, s36, 0x40080
	s_addc_u32 s37, s37, 0
	s_add_u32 s59, s38, 0x100
	s_addc_u32 s60, s39, 0
	s_mov_b32 s61, -2
	s_cmp_lt_u32 s46, 2
	s_cbranch_scc1 .Lz1s1179
	s_andn2_b64 vcc, exec, s[8:9]
	s_cbranch_vccnz .Lz1s1179
	s_barrier
.Lz1s1179:
.Lpk1179_peel:
	ds_read_b128 v[144:147], v158
	ds_read_b128 v[164:167], v158 offset:1024
	ds_read_b128 v[168:171], v158 offset:2048
	ds_read_b128 v[172:175], v158 offset:3072
	ds_read_b128 v[178:181], v159
	ds_read_b128 v[182:185], v159 offset:1024
	ds_read_b128 v[186:189], v159 offset:2048
	ds_read_b128 v[190:193], v159 offset:3072
	s_add_u32 s2, s36, 0xfffc0080
	s_addc_u32 s3, s37, -1
	s_cmp_eq_u32 s61, 12
	s_cselect_b32 s3, s19, s3
	s_cselect_b32 s2, s21, s2
	s_cselect_b32 s39, s57, s60
	s_cselect_b32 s38, s58, s59
	v_lshl_add_u64 v[226:227], s[36:37], 0, v[138:139]
	s_add_i32 m0, s42, 0xc000
	ds_read_b128 v[194:197], v160
	ds_read_b128 v[198:201], v160 offset:1024
	ds_read_b128 v[202:205], v160 offset:2048
	ds_read_b128 v[206:209], v160 offset:3072
	ds_read_b128 v[210:213], v160 offset:4096
	ds_read_b128 v[214:217], v160 offset:5120
	ds_read_b128 v[218:221], v160 offset:6144
	ds_read_b128 v[222:225], v160 offset:7168
	global_load_lds_dwordx4 v[226:227], off
	v_lshl_add_u64 v[226:227], s[36:37], 0, v[140:141]
	s_add_i32 m0, s42, 0xe000
	s_nop 0
	global_load_lds_dwordx4 v[226:227], off
	s_waitcnt vmcnt(8)
	s_waitcnt lgkmcnt(0)
	s_setprio 1
	s_barrier
	v_mfma_f32_16x16x32_bf16 v[126:129], v[144:147], v[194:197], 0
	v_mfma_f32_16x16x32_bf16 v[122:125], v[168:171], v[194:197], 0
	v_mfma_f32_16x16x32_bf16 v[114:117], v[144:147], v[202:205], 0
	v_mfma_f32_16x16x32_bf16 v[106:109], v[168:171], v[202:205], 0
	v_mfma_f32_16x16x32_bf16 v[98:101], v[144:147], v[210:213], 0
	v_mfma_f32_16x16x32_bf16 v[90:93], v[168:171], v[210:213], 0
	v_mfma_f32_16x16x32_bf16 v[82:85], v[144:147], v[218:221], 0
	v_mfma_f32_16x16x32_bf16 v[74:77], v[168:171], v[218:221], 0
	v_mfma_f32_16x16x32_bf16 v[126:129], v[164:167], v[198:201], v[126:129]
	v_mfma_f32_16x16x32_bf16 v[122:125], v[172:175], v[198:201], v[122:125]
	v_mfma_f32_16x16x32_bf16 v[114:117], v[164:167], v[206:209], v[114:117]
	v_mfma_f32_16x16x32_bf16 v[106:109], v[172:175], v[206:209], v[106:109]
	v_mfma_f32_16x16x32_bf16 v[98:101], v[164:167], v[214:217], v[98:101]
	v_mfma_f32_16x16x32_bf16 v[90:93], v[172:175], v[214:217], v[90:93]
	v_mfma_f32_16x16x32_bf16 v[82:85], v[164:167], v[222:225], v[82:85]
	v_mfma_f32_16x16x32_bf16 v[74:77], v[172:175], v[222:225], v[74:77]
	v_mfma_f32_16x16x32_bf16 v[118:121], v[178:181], v[194:197], 0
	v_mfma_f32_16x16x32_bf16 v[110:113], v[186:189], v[194:197], 0
	v_mfma_f32_16x16x32_bf16 v[102:105], v[178:181], v[202:205], 0
	v_mfma_f32_16x16x32_bf16 v[94:97], v[186:189], v[202:205], 0
	v_mfma_f32_16x16x32_bf16 v[86:89], v[178:181], v[210:213], 0
	v_mfma_f32_16x16x32_bf16 v[78:81], v[186:189], v[210:213], 0
	v_mfma_f32_16x16x32_bf16 v[70:73], v[178:181], v[218:221], 0
	v_mfma_f32_16x16x32_bf16 v[66:69], v[186:189], v[218:221], 0
	v_mfma_f32_16x16x32_bf16 v[118:121], v[182:185], v[198:201], v[118:121]
	v_mfma_f32_16x16x32_bf16 v[110:113], v[190:193], v[198:201], v[110:113]
	v_mfma_f32_16x16x32_bf16 v[102:105], v[182:185], v[206:209], v[102:105]
	v_mfma_f32_16x16x32_bf16 v[94:97], v[190:193], v[206:209], v[94:97]
	v_mfma_f32_16x16x32_bf16 v[86:89], v[182:185], v[214:217], v[86:89]
	v_mfma_f32_16x16x32_bf16 v[78:81], v[190:193], v[214:217], v[78:81]
	v_mfma_f32_16x16x32_bf16 v[70:73], v[182:185], v[222:225], v[70:73]
	v_mfma_f32_16x16x32_bf16 v[66:69], v[190:193], v[222:225], v[66:69]
	s_barrier
	s_setprio 0
	s_add_i32 s62, s51, s41
	v_lshl_add_u64 v[226:227], s[38:39], 0, v[132:133]
	s_mov_b32 m0, s62
	ds_read_b128 v[194:197], v160 offset:16384
	ds_read_b128 v[198:201], v160 offset:17408
	ds_read_b128 v[202:205], v160 offset:18432
	ds_read_b128 v[206:209], v160 offset:19456
	ds_read_b128 v[210:213], v160 offset:20480
	ds_read_b128 v[214:217], v160 offset:21504
	ds_read_b128 v[218:221], v160 offset:22528
	ds_read_b128 v[222:225], v160 offset:23552
	global_load_lds_dwordx4 v[226:227], off
	s_add_i32 m0, s62, 0x2000
	s_add_u32 s62, s38, 0x40000
	v_lshl_add_u64 v[228:229], s[38:39], 0, v[136:137]
	s_addc_u32 s63, s39, 0
	s_add_i32 s64, s52, s41
	global_load_lds_dwordx4 v[228:229], off
	v_lshl_add_u64 v[230:231], s[62:63], 0, v[132:133]
	s_mov_b32 m0, s64
	v_lshl_add_u64 v[232:233], s[2:3], 0, v[134:135]
	global_load_lds_dwordx4 v[230:231], off
	v_lshl_add_u64 v[230:231], s[62:63], 0, v[136:137]
	s_add_i32 m0, s64, 0x2000
	s_nop 0
	global_load_lds_dwordx4 v[230:231], off
	v_lshl_add_u64 v[230:231], s[2:3], 0, v[130:131]
	s_mov_b32 m0, s42
	s_nop 0
	global_load_lds_dwordx4 v[230:231], off
	s_mov_b32 m0, s43
	s_nop 0
	global_load_lds_dwordx4 v[232:233], off
	s_waitcnt vmcnt(8)
	s_waitcnt lgkmcnt(0)
	s_setprio 1
	s_barrier
	v_mfma_f32_16x16x32_bf16 v[62:65], v[144:147], v[194:197], 0
	v_mfma_f32_16x16x32_bf16 v[58:61], v[168:171], v[194:197], 0
	v_mfma_f32_16x16x32_bf16 v[50:53], v[144:147], v[202:205], 0
	v_mfma_f32_16x16x32_bf16 v[42:45], v[168:171], v[202:205], 0
	v_mfma_f32_16x16x32_bf16 v[34:37], v[144:147], v[210:213], 0
	v_mfma_f32_16x16x32_bf16 v[26:29], v[168:171], v[210:213], 0
	v_mfma_f32_16x16x32_bf16 v[18:21], v[144:147], v[218:221], 0
	v_mfma_f32_16x16x32_bf16 v[10:13], v[168:171], v[218:221], 0
	v_mfma_f32_16x16x32_bf16 v[62:65], v[164:167], v[198:201], v[62:65]
	v_mfma_f32_16x16x32_bf16 v[58:61], v[172:175], v[198:201], v[58:61]
	v_mfma_f32_16x16x32_bf16 v[50:53], v[164:167], v[206:209], v[50:53]
	v_mfma_f32_16x16x32_bf16 v[42:45], v[172:175], v[206:209], v[42:45]
	v_mfma_f32_16x16x32_bf16 v[34:37], v[164:167], v[214:217], v[34:37]
	v_mfma_f32_16x16x32_bf16 v[26:29], v[172:175], v[214:217], v[26:29]
	v_mfma_f32_16x16x32_bf16 v[18:21], v[164:167], v[222:225], v[18:21]
	v_mfma_f32_16x16x32_bf16 v[10:13], v[172:175], v[222:225], v[10:13]
	v_mfma_f32_16x16x32_bf16 v[54:57], v[178:181], v[194:197], 0
	v_mfma_f32_16x16x32_bf16 v[46:49], v[186:189], v[194:197], 0
	v_mfma_f32_16x16x32_bf16 v[38:41], v[178:181], v[202:205], 0
	v_mfma_f32_16x16x32_bf16 v[30:33], v[186:189], v[202:205], 0
	v_mfma_f32_16x16x32_bf16 v[22:25], v[178:181], v[210:213], 0
	v_mfma_f32_16x16x32_bf16 v[14:17], v[186:189], v[210:213], 0
	v_mfma_f32_16x16x32_bf16 v[6:9], v[178:181], v[218:221], 0
	v_mfma_f32_16x16x32_bf16 v[2:5], v[186:189], v[218:221], 0
	v_mfma_f32_16x16x32_bf16 v[54:57], v[182:185], v[198:201], v[54:57]
	v_mfma_f32_16x16x32_bf16 v[46:49], v[190:193], v[198:201], v[46:49]
	v_mfma_f32_16x16x32_bf16 v[38:41], v[182:185], v[206:209], v[38:41]
	v_mfma_f32_16x16x32_bf16 v[30:33], v[190:193], v[206:209], v[30:33]
	v_mfma_f32_16x16x32_bf16 v[22:25], v[182:185], v[214:217], v[22:25]
	v_mfma_f32_16x16x32_bf16 v[14:17], v[190:193], v[214:217], v[14:17]
	v_mfma_f32_16x16x32_bf16 v[6:9], v[182:185], v[222:225], v[6:9]
	v_mfma_f32_16x16x32_bf16 v[2:5], v[190:193], v[222:225], v[2:5]
	s_barrier
	s_setprio 0
	s_add_i32 s62, 0, 0x18000
	v_add_u32_e32 v163, s62, v148
	s_add_i32 s63, 0, 0x1c000
	ds_read_b128 v[144:147], v163
	ds_read_b128 v[164:167], v163 offset:1024
	ds_read_b128 v[168:171], v163 offset:2048
	ds_read_b128 v[172:175], v163 offset:3072
	v_add_u32_e32 v163, s63, v148
	ds_read_b128 v[178:181], v163
	ds_read_b128 v[182:185], v163 offset:1024
	ds_read_b128 v[186:189], v163 offset:2048
	ds_read_b128 v[190:193], v163 offset:3072
	s_add_u32 s2, s2, 0x40000
	s_addc_u32 s3, s3, 0
	s_mov_b32 m0, s44
	v_lshl_add_u64 v[234:235], s[2:3], 0, v[130:131]
	ds_read_b128 v[194:197], v160 offset:32768
	ds_read_b128 v[198:201], v160 offset:33792
	ds_read_b128 v[202:205], v160 offset:34816
	ds_read_b128 v[206:209], v160 offset:35840
	ds_read_b128 v[210:213], v160 offset:36864
	ds_read_b128 v[214:217], v160 offset:37888
	ds_read_b128 v[218:221], v160 offset:38912
	ds_read_b128 v[222:225], v160 offset:39936
	global_load_lds_dwordx4 v[234:235], off
	v_lshl_add_u64 v[234:235], s[2:3], 0, v[134:135]
	s_mov_b32 m0, s45
	s_nop 0
	global_load_lds_dwordx4 v[234:235], off
	s_waitcnt vmcnt(8)
	s_waitcnt lgkmcnt(0)
	s_setprio 1
	s_barrier
	v_mfma_f32_16x16x32_bf16 v[126:129], v[144:147], v[194:197], v[126:129]
	v_mfma_f32_16x16x32_bf16 v[122:125], v[168:171], v[194:197], v[122:125]
	v_mfma_f32_16x16x32_bf16 v[114:117], v[144:147], v[202:205], v[114:117]
	v_mfma_f32_16x16x32_bf16 v[106:109], v[168:171], v[202:205], v[106:109]
	v_mfma_f32_16x16x32_bf16 v[98:101], v[144:147], v[210:213], v[98:101]
	v_mfma_f32_16x16x32_bf16 v[90:93], v[168:171], v[210:213], v[90:93]
	v_mfma_f32_16x16x32_bf16 v[82:85], v[144:147], v[218:221], v[82:85]
	v_mfma_f32_16x16x32_bf16 v[74:77], v[168:171], v[218:221], v[74:77]
	v_mfma_f32_16x16x32_bf16 v[126:129], v[164:167], v[198:201], v[126:129]
	v_mfma_f32_16x16x32_bf16 v[122:125], v[172:175], v[198:201], v[122:125]
	v_mfma_f32_16x16x32_bf16 v[114:117], v[164:167], v[206:209], v[114:117]
	v_mfma_f32_16x16x32_bf16 v[106:109], v[172:175], v[206:209], v[106:109]
	v_mfma_f32_16x16x32_bf16 v[98:101], v[164:167], v[214:217], v[98:101]
	v_mfma_f32_16x16x32_bf16 v[90:93], v[172:175], v[214:217], v[90:93]
	v_mfma_f32_16x16x32_bf16 v[82:85], v[164:167], v[222:225], v[82:85]
	v_mfma_f32_16x16x32_bf16 v[74:77], v[172:175], v[222:225], v[74:77]
	v_mfma_f32_16x16x32_bf16 v[118:121], v[178:181], v[194:197], v[118:121]
	v_mfma_f32_16x16x32_bf16 v[110:113], v[186:189], v[194:197], v[110:113]
	v_mfma_f32_16x16x32_bf16 v[102:105], v[178:181], v[202:205], v[102:105]
	v_mfma_f32_16x16x32_bf16 v[94:97], v[186:189], v[202:205], v[94:97]
	v_mfma_f32_16x16x32_bf16 v[86:89], v[178:181], v[210:213], v[86:89]
	v_mfma_f32_16x16x32_bf16 v[78:81], v[186:189], v[210:213], v[78:81]
	v_mfma_f32_16x16x32_bf16 v[70:73], v[178:181], v[218:221], v[70:73]
	v_mfma_f32_16x16x32_bf16 v[66:69], v[186:189], v[218:221], v[66:69]
	v_mfma_f32_16x16x32_bf16 v[118:121], v[182:185], v[198:201], v[118:121]
	v_mfma_f32_16x16x32_bf16 v[110:113], v[190:193], v[198:201], v[110:113]
	v_mfma_f32_16x16x32_bf16 v[102:105], v[182:185], v[206:209], v[102:105]
	v_mfma_f32_16x16x32_bf16 v[94:97], v[190:193], v[206:209], v[94:97]
	v_mfma_f32_16x16x32_bf16 v[86:89], v[182:185], v[214:217], v[86:89]
	v_mfma_f32_16x16x32_bf16 v[78:81], v[190:193], v[214:217], v[78:81]
	v_mfma_f32_16x16x32_bf16 v[70:73], v[182:185], v[222:225], v[70:73]
	v_mfma_f32_16x16x32_bf16 v[66:69], v[190:193], v[222:225], v[66:69]
	s_barrier
	s_setprio 0
	s_add_i32 s2, s62, s41
	v_lshl_add_u64 v[226:227], v[226:227], 0, s[10:11]
	s_mov_b32 m0, s2
	ds_read_b128 v[194:197], v160 offset:49152
	ds_read_b128 v[198:201], v160 offset:50176
	ds_read_b128 v[202:205], v160 offset:51200
	ds_read_b128 v[206:209], v160 offset:52224
	ds_read_b128 v[210:213], v160 offset:53248
	ds_read_b128 v[214:217], v160 offset:54272
	ds_read_b128 v[218:221], v160 offset:55296
	ds_read_b128 v[222:225], v160 offset:56320
	global_load_lds_dwordx4 v[226:227], off
	s_add_i32 m0, s2, 0x2000
	s_add_u32 s2, s38, 0x40080
	v_lshl_add_u64 v[226:227], v[228:229], 0, s[10:11]
	s_addc_u32 s3, s39, 0
	s_add_i32 s38, s63, s41
	global_load_lds_dwordx4 v[226:227], off
	v_lshl_add_u64 v[226:227], s[2:3], 0, v[132:133]
	s_mov_b32 m0, s38
	s_nop 0
	global_load_lds_dwordx4 v[226:227], off
	v_lshl_add_u64 v[226:227], s[2:3], 0, v[136:137]
	s_add_i32 m0, s38, 0x2000
	s_nop 0
	global_load_lds_dwordx4 v[226:227], off
	v_lshl_add_u64 v[226:227], v[230:231], 0, s[10:11]
	s_mov_b32 m0, s47
	s_nop 0
	global_load_lds_dwordx4 v[226:227], off
	v_lshl_add_u64 v[226:227], v[232:233], 0, s[10:11]
	s_mov_b32 m0, s48
	s_nop 0
	global_load_lds_dwordx4 v[226:227], off
	s_waitcnt vmcnt(8)
	s_waitcnt lgkmcnt(0)
	s_setprio 1
	s_barrier
	v_mfma_f32_16x16x32_bf16 v[62:65], v[144:147], v[194:197], v[62:65]
	v_mfma_f32_16x16x32_bf16 v[58:61], v[168:171], v[194:197], v[58:61]
	v_mfma_f32_16x16x32_bf16 v[50:53], v[144:147], v[202:205], v[50:53]
	v_mfma_f32_16x16x32_bf16 v[42:45], v[168:171], v[202:205], v[42:45]
	v_mfma_f32_16x16x32_bf16 v[34:37], v[144:147], v[210:213], v[34:37]
	v_mfma_f32_16x16x32_bf16 v[26:29], v[168:171], v[210:213], v[26:29]
	v_mfma_f32_16x16x32_bf16 v[18:21], v[144:147], v[218:221], v[18:21]
	v_mfma_f32_16x16x32_bf16 v[10:13], v[168:171], v[218:221], v[10:13]
	v_mfma_f32_16x16x32_bf16 v[62:65], v[164:167], v[198:201], v[62:65]
	v_mfma_f32_16x16x32_bf16 v[58:61], v[172:175], v[198:201], v[58:61]
	v_mfma_f32_16x16x32_bf16 v[50:53], v[164:167], v[206:209], v[50:53]
	v_mfma_f32_16x16x32_bf16 v[42:45], v[172:175], v[206:209], v[42:45]
	v_mfma_f32_16x16x32_bf16 v[34:37], v[164:167], v[214:217], v[34:37]
	v_mfma_f32_16x16x32_bf16 v[26:29], v[172:175], v[214:217], v[26:29]
	v_mfma_f32_16x16x32_bf16 v[18:21], v[164:167], v[222:225], v[18:21]
	v_mfma_f32_16x16x32_bf16 v[10:13], v[172:175], v[222:225], v[10:13]
	v_mfma_f32_16x16x32_bf16 v[54:57], v[178:181], v[194:197], v[54:57]
	v_mfma_f32_16x16x32_bf16 v[46:49], v[186:189], v[194:197], v[46:49]
	v_mfma_f32_16x16x32_bf16 v[38:41], v[178:181], v[202:205], v[38:41]
	v_mfma_f32_16x16x32_bf16 v[30:33], v[186:189], v[202:205], v[30:33]
	v_mfma_f32_16x16x32_bf16 v[22:25], v[178:181], v[210:213], v[22:25]
	v_mfma_f32_16x16x32_bf16 v[14:17], v[186:189], v[210:213], v[14:17]
	v_mfma_f32_16x16x32_bf16 v[6:9], v[178:181], v[218:221], v[6:9]
	v_mfma_f32_16x16x32_bf16 v[2:5], v[186:189], v[218:221], v[2:5]
	v_mfma_f32_16x16x32_bf16 v[54:57], v[182:185], v[198:201], v[54:57]
	v_mfma_f32_16x16x32_bf16 v[46:49], v[190:193], v[198:201], v[46:49]
	v_mfma_f32_16x16x32_bf16 v[38:41], v[182:185], v[206:209], v[38:41]
	v_mfma_f32_16x16x32_bf16 v[30:33], v[190:193], v[206:209], v[30:33]
	v_mfma_f32_16x16x32_bf16 v[22:25], v[182:185], v[214:217], v[22:25]
	v_mfma_f32_16x16x32_bf16 v[14:17], v[190:193], v[214:217], v[14:17]
	v_mfma_f32_16x16x32_bf16 v[6:9], v[182:185], v[222:225], v[6:9]
	v_mfma_f32_16x16x32_bf16 v[2:5], v[190:193], v[222:225], v[2:5]
	s_barrier
	s_setprio 0
	s_add_i32 s61, s61, 2
	s_add_u32 s36, s36, 0x100
	s_addc_u32 s37, s37, 0
	s_add_u32 s59, s59, 0x100
	s_addc_u32 s60, s60, 0
	s_cmp_gt_u32 s61, 13
	s_cbranch_scc0 .LBB0_1179
	s_branch .Lpk1179_exit

.LBB0_1198:
	s_or_b64 exec, exec, s[2:3]
	s_waitcnt lgkmcnt(0)
	s_barrier
	s_waitcnt lgkmcnt(0)
	ds_read_b128 v[18:21], v162
	v_lshl_add_u32 v164, s34, 8, v1
	v_lshl_or_b32 v166, s56, 8, v149
	v_ashrrev_i32_e32 v165, 31, v164
	v_ashrrev_i32_e32 v167, 31, v166
	s_waitcnt lgkmcnt(0)
	v_mov_b32_e32 v168, v19
	v_mov_b32_e32 v169, v20
	v_mov_b32_e32 v19, v21
	v_pk_add_f32 v[18:19], v[168:169], v[18:19]
	v_lshlrev_b64 v[166:167], 1, v[166:167]
	v_add_f32_e32 v18, v18, v19
	v_rcp_f32_e32 v20, v18
	v_lshlrev_b64 v[18:19], 11, v[164:165]
	v_lshl_add_u64 v[18:19], s[4:5], 0, v[18:19]
	v_lshl_add_u64 v[18:19], v[18:19], 0, v[166:167]
	v_pk_mul_f32 v[126:127], v[126:127], v[20:21] op_sel_hi:[1,0]
	v_pk_mul_f32 v[128:129], v[128:129], v[20:21] op_sel_hi:[1,0]
	v_pk_mul_f32 v[122:123], v[122:123], v[20:21] op_sel_hi:[1,0]
	v_pk_mul_f32 v[118:119], v[118:119], v[20:21] op_sel_hi:[1,0]
	v_pk_mul_f32 v[124:125], v[124:125], v[20:21] op_sel_hi:[1,0]
	v_pk_mul_f32 v[144:145], v[144:145], v[20:21] op_sel_hi:[1,0]
	v_pk_mul_f32 v[146:147], v[146:147], v[20:21] op_sel_hi:[1,0]
	v_cvt_pk_bf16_f32 v126, v126, v127
	v_cvt_pk_bf16_f32 v127, v144, v145
	v_cvt_pk_bf16_f32 v128, v128, v129
	v_pk_mul_f32 v[20:21], v[120:121], v[20:21] op_sel_hi:[1,0]
	v_cvt_pk_bf16_f32 v129, v146, v147
	global_store_dwordx4 v[18:19], v[126:129], off
	v_cvt_pk_bf16_f32 v118, v118, v119
	v_cvt_pk_bf16_f32 v119, v122, v123
	v_cvt_pk_bf16_f32 v120, v20, v21
	v_cvt_pk_bf16_f32 v121, v124, v125
	ds_read_b128 v[122:125], v162 offset:256
	global_store_dwordx4 v[18:19], v[118:121], off offset:256
	s_mov_b32 s2, 0x40000
	s_waitcnt lgkmcnt(0)
	v_mov_b32_e32 v20, v123
	v_mov_b32_e32 v21, v124
	v_mov_b32_e32 v123, v125
	v_pk_add_f32 v[20:21], v[20:21], v[122:123]
	v_or_b32_e32 v118, 16, v164
	v_add_f32_e32 v20, v20, v21
	v_rcp_f32_e32 v20, v20
	v_ashrrev_i32_e32 v119, 31, v118
	v_lshlrev_b64 v[118:119], 11, v[118:119]
	v_lshl_add_u64 v[118:119], s[4:5], 0, v[118:119]
	v_lshl_add_u64 v[118:119], v[118:119], 0, v[166:167]
	v_pk_mul_f32 v[110:111], v[110:111], v[20:21] op_sel_hi:[1,0]
	v_pk_mul_f32 v[112:113], v[112:113], v[20:21] op_sel_hi:[1,0]
	v_pk_mul_f32 v[106:107], v[106:107], v[20:21] op_sel_hi:[1,0]
	v_pk_mul_f32 v[102:103], v[102:103], v[20:21] op_sel_hi:[1,0]
	v_pk_mul_f32 v[108:109], v[108:109], v[20:21] op_sel_hi:[1,0]
	v_pk_mul_f32 v[114:115], v[114:115], v[20:21] op_sel_hi:[1,0]
	v_pk_mul_f32 v[116:117], v[116:117], v[20:21] op_sel_hi:[1,0]
	v_cvt_pk_bf16_f32 v110, v110, v111
	v_cvt_pk_bf16_f32 v111, v114, v115
	v_cvt_pk_bf16_f32 v112, v112, v113
	v_pk_mul_f32 v[20:21], v[104:105], v[20:21] op_sel_hi:[1,0]
	v_cvt_pk_bf16_f32 v113, v116, v117
	global_store_dwordx4 v[118:119], v[110:113], off
	v_cvt_pk_bf16_f32 v102, v102, v103
	v_cvt_pk_bf16_f32 v103, v106, v107
	v_cvt_pk_bf16_f32 v104, v20, v21
	v_cvt_pk_bf16_f32 v105, v108, v109
	ds_read_b128 v[106:109], v162 offset:512
	global_store_dwordx4 v[118:119], v[102:105], off offset:256
	s_waitcnt lgkmcnt(0)
	v_mov_b32_e32 v20, v107
	v_mov_b32_e32 v21, v108
	v_mov_b32_e32 v107, v109
	v_pk_add_f32 v[20:21], v[20:21], v[106:107]
	v_or_b32_e32 v102, 32, v164
	v_add_f32_e32 v20, v20, v21
	v_rcp_f32_e32 v20, v20
	v_ashrrev_i32_e32 v103, 31, v102
	v_lshlrev_b64 v[102:103], 11, v[102:103]
	v_lshl_add_u64 v[102:103], s[4:5], 0, v[102:103]
	v_lshl_add_u64 v[102:103], v[102:103], 0, v[166:167]
	v_pk_mul_f32 v[94:95], v[94:95], v[20:21] op_sel_hi:[1,0]
	v_pk_mul_f32 v[96:97], v[96:97], v[20:21] op_sel_hi:[1,0]
	v_pk_mul_f32 v[90:91], v[90:91], v[20:21] op_sel_hi:[1,0]
	v_pk_mul_f32 v[86:87], v[86:87], v[20:21] op_sel_hi:[1,0]
	v_pk_mul_f32 v[92:93], v[92:93], v[20:21] op_sel_hi:[1,0]
	v_pk_mul_f32 v[98:99], v[98:99], v[20:21] op_sel_hi:[1,0]
	v_pk_mul_f32 v[100:101], v[100:101], v[20:21] op_sel_hi:[1,0]
	v_cvt_pk_bf16_f32 v94, v94, v95
	v_cvt_pk_bf16_f32 v95, v98, v99
	v_cvt_pk_bf16_f32 v96, v96, v97
	v_pk_mul_f32 v[20:21], v[88:89], v[20:21] op_sel_hi:[1,0]
	v_cvt_pk_bf16_f32 v97, v100, v101
	global_store_dwordx4 v[102:103], v[94:97], off
	v_cvt_pk_bf16_f32 v86, v86, v87
	v_cvt_pk_bf16_f32 v87, v90, v91
	v_cvt_pk_bf16_f32 v88, v20, v21
	v_cvt_pk_bf16_f32 v89, v92, v93
	ds_read_b128 v[90:93], v162 offset:768
	global_store_dwordx4 v[102:103], v[86:89], off offset:256
	s_waitcnt lgkmcnt(0)
	v_mov_b32_e32 v20, v91
	v_mov_b32_e32 v21, v92
	v_mov_b32_e32 v91, v93
	v_pk_add_f32 v[20:21], v[20:21], v[90:91]
	v_or_b32_e32 v86, 48, v164
	v_add_f32_e32 v20, v20, v21
	v_rcp_f32_e32 v20, v20
	v_ashrrev_i32_e32 v87, 31, v86
	v_lshlrev_b64 v[86:87], 11, v[86:87]
	v_lshl_add_u64 v[86:87], s[4:5], 0, v[86:87]
	v_lshl_add_u64 v[86:87], v[86:87], 0, v[166:167]
	v_pk_mul_f32 v[78:79], v[78:79], v[20:21] op_sel_hi:[1,0]
	v_pk_mul_f32 v[80:81], v[80:81], v[20:21] op_sel_hi:[1,0]
	v_pk_mul_f32 v[74:75], v[74:75], v[20:21] op_sel_hi:[1,0]
	v_pk_mul_f32 v[70:71], v[70:71], v[20:21] op_sel_hi:[1,0]
	v_pk_mul_f32 v[76:77], v[76:77], v[20:21] op_sel_hi:[1,0]
	v_pk_mul_f32 v[82:83], v[82:83], v[20:21] op_sel_hi:[1,0]
	v_pk_mul_f32 v[84:85], v[84:85], v[20:21] op_sel_hi:[1,0]
	v_cvt_pk_bf16_f32 v78, v78, v79
	v_cvt_pk_bf16_f32 v79, v82, v83
	v_cvt_pk_bf16_f32 v80, v80, v81
	v_pk_mul_f32 v[20:21], v[72:73], v[20:21] op_sel_hi:[1,0]
	v_cvt_pk_bf16_f32 v81, v84, v85
	global_store_dwordx4 v[86:87], v[78:81], off
	v_cvt_pk_bf16_f32 v70, v70, v71
	v_cvt_pk_bf16_f32 v71, v74, v75
	v_cvt_pk_bf16_f32 v72, v20, v21
	v_cvt_pk_bf16_f32 v73, v76, v77
	ds_read_b128 v[74:77], v162 offset:2048
	global_store_dwordx4 v[86:87], v[70:73], off offset:256
	s_waitcnt lgkmcnt(0)
	v_mov_b32_e32 v20, v75
	v_mov_b32_e32 v21, v76
	v_mov_b32_e32 v75, v77
	v_pk_add_f32 v[20:21], v[20:21], v[74:75]
	s_nop 0
	v_add_f32_e32 v20, v20, v21
	v_rcp_f32_e32 v20, v20
	s_nop 0
	v_pk_mul_f32 v[66:67], v[66:67], v[20:21] op_sel_hi:[1,0]
	v_pk_mul_f32 v[62:63], v[62:63], v[20:21] op_sel_hi:[1,0]
	v_pk_mul_f32 v[64:65], v[64:65], v[20:21] op_sel_hi:[1,0]
	v_cvt_pk_bf16_f32 v62, v62, v63
	v_cvt_pk_bf16_f32 v63, v66, v67
	v_add_co_u32_e32 v66, vcc, s2, v18
	v_pk_mul_f32 v[58:59], v[58:59], v[20:21] op_sel_hi:[1,0]
	s_nop 0
	v_addc_co_u32_e32 v67, vcc, 0, v19, vcc
	v_pk_mul_f32 v[54:55], v[54:55], v[20:21] op_sel_hi:[1,0]
	v_pk_mul_f32 v[60:61], v[60:61], v[20:21] op_sel_hi:[1,0]
	v_pk_mul_f32 v[68:69], v[68:69], v[20:21] op_sel_hi:[1,0]
	v_cvt_pk_bf16_f32 v64, v64, v65
	v_pk_mul_f32 v[20:21], v[56:57], v[20:21] op_sel_hi:[1,0]
	v_cvt_pk_bf16_f32 v65, v68, v69
	global_store_dwordx4 v[66:67], v[62:65], off
	v_cvt_pk_bf16_f32 v54, v54, v55
	v_cvt_pk_bf16_f32 v55, v58, v59
	v_cvt_pk_bf16_f32 v56, v20, v21
	v_cvt_pk_bf16_f32 v57, v60, v61
	ds_read_b128 v[58:61], v162 offset:2304
	s_mov_b64 s[2:3], 0x40000
	s_waitcnt lgkmcnt(0)
	v_mov_b32_e32 v20, v59
	v_mov_b32_e32 v21, v60
	v_mov_b32_e32 v59, v61
	v_pk_add_f32 v[20:21], v[20:21], v[58:59]
	v_lshl_add_u64 v[58:59], v[18:19], 0, s[2:3]
	v_add_f32_e32 v20, v20, v21
	v_rcp_f32_e32 v20, v20
	global_store_dwordx4 v[58:59], v[54:57], off offset:256
	s_mov_b64 s[2:3], 0x48000
	v_pk_mul_f32 v[50:51], v[50:51], v[20:21] op_sel_hi:[1,0]
	v_pk_mul_f32 v[46:47], v[46:47], v[20:21] op_sel_hi:[1,0]
	v_pk_mul_f32 v[48:49], v[48:49], v[20:21] op_sel_hi:[1,0]
	v_cvt_pk_bf16_f32 v46, v46, v47
	v_cvt_pk_bf16_f32 v47, v50, v51
	v_add_co_u32_e32 v50, vcc, s53, v18
	v_pk_mul_f32 v[42:43], v[42:43], v[20:21] op_sel_hi:[1,0]
	s_nop 0
	v_addc_co_u32_e32 v51, vcc, 0, v19, vcc
	v_pk_mul_f32 v[38:39], v[38:39], v[20:21] op_sel_hi:[1,0]
	v_pk_mul_f32 v[44:45], v[44:45], v[20:21] op_sel_hi:[1,0]
	v_pk_mul_f32 v[52:53], v[52:53], v[20:21] op_sel_hi:[1,0]
	v_cvt_pk_bf16_f32 v48, v48, v49
	v_pk_mul_f32 v[20:21], v[40:41], v[20:21] op_sel_hi:[1,0]
	v_cvt_pk_bf16_f32 v49, v52, v53
	global_store_dwordx4 v[50:51], v[46:49], off
	v_cvt_pk_bf16_f32 v38, v38, v39
	v_cvt_pk_bf16_f32 v39, v42, v43
	v_cvt_pk_bf16_f32 v40, v20, v21
	v_cvt_pk_bf16_f32 v41, v44, v45
	ds_read_b128 v[42:45], v162 offset:2560
	s_waitcnt lgkmcnt(0)
	v_mov_b32_e32 v20, v43
	v_mov_b32_e32 v21, v44
	v_mov_b32_e32 v43, v45
	v_pk_add_f32 v[20:21], v[20:21], v[42:43]
	v_lshl_add_u64 v[42:43], v[18:19], 0, s[2:3]
	v_add_f32_e32 v20, v20, v21
	v_rcp_f32_e32 v20, v20
	global_store_dwordx4 v[42:43], v[38:41], off offset:256
	s_mov_b64 s[2:3], -1
	v_pk_mul_f32 v[34:35], v[34:35], v[20:21] op_sel_hi:[1,0]
	v_pk_mul_f32 v[30:31], v[30:31], v[20:21] op_sel_hi:[1,0]
	v_pk_mul_f32 v[32:33], v[32:33], v[20:21] op_sel_hi:[1,0]
	v_cvt_pk_bf16_f32 v30, v30, v31
	v_cvt_pk_bf16_f32 v31, v34, v35
	v_add_co_u32_e32 v34, vcc, s54, v18
	v_pk_mul_f32 v[26:27], v[26:27], v[20:21] op_sel_hi:[1,0]
	s_nop 0
	v_addc_co_u32_e32 v35, vcc, 0, v19, vcc
	v_pk_mul_f32 v[22:23], v[22:23], v[20:21] op_sel_hi:[1,0]
	v_pk_mul_f32 v[24:25], v[24:25], v[20:21] op_sel_hi:[1,0]
	v_pk_mul_f32 v[36:37], v[36:37], v[20:21] op_sel_hi:[1,0]
	v_cvt_pk_bf16_f32 v32, v32, v33
	v_pk_mul_f32 v[28:29], v[28:29], v[20:21] op_sel_hi:[1,0]
	v_cvt_pk_bf16_f32 v33, v36, v37
	global_store_dwordx4 v[34:35], v[30:33], off
	v_cvt_pk_bf16_f32 v20, v22, v23
	v_cvt_pk_bf16_f32 v21, v26, v27
	v_cvt_pk_bf16_f32 v22, v24, v25
	v_cvt_pk_bf16_f32 v23, v28, v29
	ds_read_b128 v[24:27], v162 offset:2816
	s_waitcnt lgkmcnt(0)
	v_mov_b32_e32 v28, v25
	v_mov_b32_e32 v29, v26
	v_mov_b32_e32 v25, v27
	v_pk_add_f32 v[24:25], v[28:29], v[24:25]
	v_lshl_add_u64 v[26:27], v[18:19], 0, s[14:15]
	v_add_f32_e32 v24, v24, v25
	v_rcp_f32_e32 v24, v24
	global_store_dwordx4 v[26:27], v[20:23], off offset:256
	v_pk_mul_f32 v[14:15], v[14:15], v[24:25] op_sel_hi:[1,0]
	s_nop 0
	v_pk_mul_f32 v[22:23], v[12:13], v[24:25] op_sel_hi:[1,0]
	v_pk_mul_f32 v[12:13], v[10:11], v[24:25] op_sel_hi:[1,0]
	v_cvt_pk_bf16_f32 v10, v14, v15
	v_add_co_u32_e32 v14, vcc, s55, v18
	v_pk_mul_f32 v[16:17], v[16:17], v[24:25] op_sel_hi:[1,0]
	s_nop 0
	v_addc_co_u32_e32 v15, vcc, 0, v19, vcc
	v_cvt_pk_bf16_f32 v11, v16, v17
	v_lshl_add_u64 v[20:21], v[18:19], 0, s[16:17]
	v_cvt_pk_bf16_f32 v12, v12, v13
	v_cvt_pk_bf16_f32 v13, v22, v23
	global_store_dwordx4 v[14:15], v[10:13], off
	v_pk_mul_f32 v[8:9], v[8:9], v[24:25] op_sel_hi:[1,0]
	v_pk_mul_f32 v[6:7], v[6:7], v[24:25] op_sel_hi:[1,0]
	v_pk_mul_f32 v[10:11], v[4:5], v[24:25] op_sel_hi:[1,0]
	v_pk_mul_f32 v[4:5], v[2:3], v[24:25] op_sel_hi:[1,0]
	v_cvt_pk_bf16_f32 v2, v6, v7
	v_cvt_pk_bf16_f32 v3, v8, v9
	s_andn2_b64 vcc, exec, s[26:27]
	v_cvt_pk_bf16_f32 v4, v4, v5
	v_cvt_pk_bf16_f32 v5, v10, v11
	global_store_dwordx4 v[20:21], v[2:5], off offset:256
	s_waitcnt lgkmcnt(0)
	s_barrier
	s_cbranch_vccnz .LBB0_1170
	s_andn2_b64 vcc, exec, s[8:9]
	s_cbranch_vccnz .LBB0_1169
	s_branch .LBB0_1169

.LBB0_1238:
	s_lshl_b64 s[2:3], s[22:23], 1
	s_add_u32 s28, s4, s2
	s_addc_u32 s29, s5, s3
	s_and_b64 s[2:3], s[26:27], exec
	s_cselect_b32 s19, s29, s37
	s_cselect_b32 s21, s28, s36
	s_lshl_b64 s[2:3], s[24:25], 1
	s_add_u32 s30, s41, s2
	s_addc_u32 s31, s42, s3
	s_and_b64 s[2:3], s[26:27], exec
	s_cselect_b32 s58, s31, s39
	s_cselect_b32 s59, s30, s38
	s_add_u32 s36, s36, 0x40080
	s_addc_u32 s37, s37, 0
	s_add_u32 s60, s38, 0x100
	s_addc_u32 s61, s39, 0
	s_mov_b32 s62, -2
	s_cmp_lt_u32 s47, 2
	s_cbranch_scc1 .Lz1s1239
	s_andn2_b64 vcc, exec, s[6:7]
	s_cbranch_vccnz .Lz1s1239
	s_barrier
.Lz1s1239:
.Lpk1239_peel:
	ds_read_b128 v[152:155], v148
	ds_read_b128 v[156:159], v148 offset:1024
	ds_read_b128 v[160:163], v148 offset:2048
	ds_read_b128 v[164:167], v148 offset:3072
	ds_read_b128 v[168:171], v149
	ds_read_b128 v[172:175], v149 offset:1024
	ds_read_b128 v[178:181], v149 offset:2048
	ds_read_b128 v[182:185], v149 offset:3072
	s_add_u32 s2, s36, 0xfffc0080
	s_addc_u32 s3, s37, -1
	s_cmp_eq_u32 s62, 12
	s_cselect_b32 s3, s19, s3
	s_cselect_b32 s2, s21, s2
	s_cselect_b32 s39, s58, s61
	s_cselect_b32 s38, s59, s60
	v_lshl_add_u64 v[144:145], s[36:37], 0, v[138:139]
	s_add_i32 m0, s44, 0xc000
	ds_read_b128 v[186:189], v150
	ds_read_b128 v[190:193], v150 offset:1024
	ds_read_b128 v[194:197], v150 offset:2048
	ds_read_b128 v[198:201], v150 offset:3072
	ds_read_b128 v[202:205], v150 offset:4096
	ds_read_b128 v[206:209], v150 offset:5120
	ds_read_b128 v[210:213], v150 offset:6144
	ds_read_b128 v[214:217], v150 offset:7168
	global_load_lds_dwordx4 v[144:145], off
	v_lshl_add_u64 v[144:145], s[36:37], 0, v[140:141]
	s_add_i32 m0, s44, 0xe000
	s_nop 0
	global_load_lds_dwordx4 v[144:145], off
	s_waitcnt vmcnt(8)
	s_waitcnt lgkmcnt(0)
	s_setprio 1
	s_barrier
	v_mfma_f32_16x16x32_bf16 v[126:129], v[152:155], v[186:189], 0
	v_mfma_f32_16x16x32_bf16 v[122:125], v[160:163], v[186:189], 0
	v_mfma_f32_16x16x32_bf16 v[114:117], v[152:155], v[194:197], 0
	v_mfma_f32_16x16x32_bf16 v[106:109], v[160:163], v[194:197], 0
	v_mfma_f32_16x16x32_bf16 v[98:101], v[152:155], v[202:205], 0
	v_mfma_f32_16x16x32_bf16 v[90:93], v[160:163], v[202:205], 0
	v_mfma_f32_16x16x32_bf16 v[82:85], v[152:155], v[210:213], 0
	v_mfma_f32_16x16x32_bf16 v[74:77], v[160:163], v[210:213], 0
	v_mfma_f32_16x16x32_bf16 v[126:129], v[156:159], v[190:193], v[126:129]
	v_mfma_f32_16x16x32_bf16 v[122:125], v[164:167], v[190:193], v[122:125]
	v_mfma_f32_16x16x32_bf16 v[114:117], v[156:159], v[198:201], v[114:117]
	v_mfma_f32_16x16x32_bf16 v[106:109], v[164:167], v[198:201], v[106:109]
	v_mfma_f32_16x16x32_bf16 v[98:101], v[156:159], v[206:209], v[98:101]
	v_mfma_f32_16x16x32_bf16 v[90:93], v[164:167], v[206:209], v[90:93]
	v_mfma_f32_16x16x32_bf16 v[82:85], v[156:159], v[214:217], v[82:85]
	v_mfma_f32_16x16x32_bf16 v[74:77], v[164:167], v[214:217], v[74:77]
	v_mfma_f32_16x16x32_bf16 v[118:121], v[168:171], v[186:189], 0
	v_mfma_f32_16x16x32_bf16 v[110:113], v[178:181], v[186:189], 0
	v_mfma_f32_16x16x32_bf16 v[102:105], v[168:171], v[194:197], 0
	v_mfma_f32_16x16x32_bf16 v[94:97], v[178:181], v[194:197], 0
	v_mfma_f32_16x16x32_bf16 v[86:89], v[168:171], v[202:205], 0
	v_mfma_f32_16x16x32_bf16 v[78:81], v[178:181], v[202:205], 0
	v_mfma_f32_16x16x32_bf16 v[70:73], v[168:171], v[210:213], 0
	v_mfma_f32_16x16x32_bf16 v[66:69], v[178:181], v[210:213], 0
	v_mfma_f32_16x16x32_bf16 v[118:121], v[172:175], v[190:193], v[118:121]
	v_mfma_f32_16x16x32_bf16 v[110:113], v[182:185], v[190:193], v[110:113]
	v_mfma_f32_16x16x32_bf16 v[102:105], v[172:175], v[198:201], v[102:105]
	v_mfma_f32_16x16x32_bf16 v[94:97], v[182:185], v[198:201], v[94:97]
	v_mfma_f32_16x16x32_bf16 v[86:89], v[172:175], v[206:209], v[86:89]
	v_mfma_f32_16x16x32_bf16 v[78:81], v[182:185], v[206:209], v[78:81]
	v_mfma_f32_16x16x32_bf16 v[70:73], v[172:175], v[214:217], v[70:73]
	v_mfma_f32_16x16x32_bf16 v[66:69], v[182:185], v[214:217], v[66:69]
	s_barrier
	s_setprio 0
	s_add_i32 s63, s51, s43
	v_lshl_add_u64 v[144:145], s[38:39], 0, v[132:133]
	s_mov_b32 m0, s63
	ds_read_b128 v[186:189], v150 offset:16384
	ds_read_b128 v[190:193], v150 offset:17408
	ds_read_b128 v[194:197], v150 offset:18432
	ds_read_b128 v[198:201], v150 offset:19456
	ds_read_b128 v[202:205], v150 offset:20480
	ds_read_b128 v[206:209], v150 offset:21504
	ds_read_b128 v[210:213], v150 offset:22528
	ds_read_b128 v[214:217], v150 offset:23552
	global_load_lds_dwordx4 v[144:145], off
	s_add_i32 m0, s63, 0x2000
	s_add_u32 s64, s38, 0x40000
	v_lshl_add_u64 v[218:219], s[38:39], 0, v[136:137]
	s_addc_u32 s65, s39, 0
	s_add_i32 s63, s52, s43
	global_load_lds_dwordx4 v[218:219], off
	v_lshl_add_u64 v[220:221], s[64:65], 0, v[132:133]
	s_mov_b32 m0, s63
	v_lshl_add_u64 v[222:223], s[2:3], 0, v[134:135]
	global_load_lds_dwordx4 v[220:221], off
	v_lshl_add_u64 v[220:221], s[64:65], 0, v[136:137]
	s_add_i32 m0, s63, 0x2000
	s_nop 0
	global_load_lds_dwordx4 v[220:221], off
	v_lshl_add_u64 v[220:221], s[2:3], 0, v[130:131]
	s_mov_b32 m0, s44
	s_nop 0
	global_load_lds_dwordx4 v[220:221], off
	s_mov_b32 m0, s35
	s_nop 0
	global_load_lds_dwordx4 v[222:223], off
	s_waitcnt vmcnt(8)
	s_waitcnt lgkmcnt(0)
	s_setprio 1
	s_barrier
	v_mfma_f32_16x16x32_bf16 v[62:65], v[152:155], v[186:189], 0
	v_mfma_f32_16x16x32_bf16 v[58:61], v[160:163], v[186:189], 0
	v_mfma_f32_16x16x32_bf16 v[50:53], v[152:155], v[194:197], 0
	v_mfma_f32_16x16x32_bf16 v[42:45], v[160:163], v[194:197], 0
	v_mfma_f32_16x16x32_bf16 v[34:37], v[152:155], v[202:205], 0
	v_mfma_f32_16x16x32_bf16 v[26:29], v[160:163], v[202:205], 0
	v_mfma_f32_16x16x32_bf16 v[18:21], v[152:155], v[210:213], 0
	v_mfma_f32_16x16x32_bf16 v[10:13], v[160:163], v[210:213], 0
	v_mfma_f32_16x16x32_bf16 v[62:65], v[156:159], v[190:193], v[62:65]
	v_mfma_f32_16x16x32_bf16 v[58:61], v[164:167], v[190:193], v[58:61]
	v_mfma_f32_16x16x32_bf16 v[50:53], v[156:159], v[198:201], v[50:53]
	v_mfma_f32_16x16x32_bf16 v[42:45], v[164:167], v[198:201], v[42:45]
	v_mfma_f32_16x16x32_bf16 v[34:37], v[156:159], v[206:209], v[34:37]
	v_mfma_f32_16x16x32_bf16 v[26:29], v[164:167], v[206:209], v[26:29]
	v_mfma_f32_16x16x32_bf16 v[18:21], v[156:159], v[214:217], v[18:21]
	v_mfma_f32_16x16x32_bf16 v[10:13], v[164:167], v[214:217], v[10:13]
	v_mfma_f32_16x16x32_bf16 v[54:57], v[168:171], v[186:189], 0
	v_mfma_f32_16x16x32_bf16 v[46:49], v[178:181], v[186:189], 0
	v_mfma_f32_16x16x32_bf16 v[38:41], v[168:171], v[194:197], 0
	v_mfma_f32_16x16x32_bf16 v[30:33], v[178:181], v[194:197], 0
	v_mfma_f32_16x16x32_bf16 v[22:25], v[168:171], v[202:205], 0
	v_mfma_f32_16x16x32_bf16 v[14:17], v[178:181], v[202:205], 0
	v_mfma_f32_16x16x32_bf16 v[6:9], v[168:171], v[210:213], 0
	v_mfma_f32_16x16x32_bf16 v[2:5], v[178:181], v[210:213], 0
	v_mfma_f32_16x16x32_bf16 v[54:57], v[172:175], v[190:193], v[54:57]
	v_mfma_f32_16x16x32_bf16 v[46:49], v[182:185], v[190:193], v[46:49]
	v_mfma_f32_16x16x32_bf16 v[38:41], v[172:175], v[198:201], v[38:41]
	v_mfma_f32_16x16x32_bf16 v[30:33], v[182:185], v[198:201], v[30:33]
	v_mfma_f32_16x16x32_bf16 v[22:25], v[172:175], v[206:209], v[22:25]
	v_mfma_f32_16x16x32_bf16 v[14:17], v[182:185], v[206:209], v[14:17]
	v_mfma_f32_16x16x32_bf16 v[6:9], v[172:175], v[214:217], v[6:9]
	v_mfma_f32_16x16x32_bf16 v[2:5], v[182:185], v[214:217], v[2:5]
	s_barrier
	s_setprio 0
	s_add_i32 s63, 0, 0x18000
	v_add_u32_e32 v151, s63, v146
	s_add_i32 s64, 0, 0x1c000
	ds_read_b128 v[152:155], v151
	ds_read_b128 v[156:159], v151 offset:1024
	ds_read_b128 v[160:163], v151 offset:2048
	ds_read_b128 v[164:167], v151 offset:3072
	v_add_u32_e32 v151, s64, v146
	ds_read_b128 v[168:171], v151
	ds_read_b128 v[172:175], v151 offset:1024
	ds_read_b128 v[178:181], v151 offset:2048
	ds_read_b128 v[182:185], v151 offset:3072
	s_add_u32 s2, s2, 0x40000
	s_addc_u32 s3, s3, 0
	s_mov_b32 m0, s45
	v_lshl_add_u64 v[224:225], s[2:3], 0, v[130:131]
	ds_read_b128 v[186:189], v150 offset:32768
	ds_read_b128 v[190:193], v150 offset:33792
	ds_read_b128 v[194:197], v150 offset:34816
	ds_read_b128 v[198:201], v150 offset:35840
	ds_read_b128 v[202:205], v150 offset:36864
	ds_read_b128 v[206:209], v150 offset:37888
	ds_read_b128 v[210:213], v150 offset:38912
	ds_read_b128 v[214:217], v150 offset:39936
	global_load_lds_dwordx4 v[224:225], off
	v_lshl_add_u64 v[224:225], s[2:3], 0, v[134:135]
	s_mov_b32 m0, s46
	s_nop 0
	global_load_lds_dwordx4 v[224:225], off
	s_waitcnt vmcnt(8)
	s_waitcnt lgkmcnt(0)
	s_setprio 1
	s_barrier
	v_mfma_f32_16x16x32_bf16 v[126:129], v[152:155], v[186:189], v[126:129]
	v_mfma_f32_16x16x32_bf16 v[122:125], v[160:163], v[186:189], v[122:125]
	v_mfma_f32_16x16x32_bf16 v[114:117], v[152:155], v[194:197], v[114:117]
	v_mfma_f32_16x16x32_bf16 v[106:109], v[160:163], v[194:197], v[106:109]
	v_mfma_f32_16x16x32_bf16 v[98:101], v[152:155], v[202:205], v[98:101]
	v_mfma_f32_16x16x32_bf16 v[90:93], v[160:163], v[202:205], v[90:93]
	v_mfma_f32_16x16x32_bf16 v[82:85], v[152:155], v[210:213], v[82:85]
	v_mfma_f32_16x16x32_bf16 v[74:77], v[160:163], v[210:213], v[74:77]
	v_mfma_f32_16x16x32_bf16 v[126:129], v[156:159], v[190:193], v[126:129]
	v_mfma_f32_16x16x32_bf16 v[122:125], v[164:167], v[190:193], v[122:125]
	v_mfma_f32_16x16x32_bf16 v[114:117], v[156:159], v[198:201], v[114:117]
	v_mfma_f32_16x16x32_bf16 v[106:109], v[164:167], v[198:201], v[106:109]
	v_mfma_f32_16x16x32_bf16 v[98:101], v[156:159], v[206:209], v[98:101]
	v_mfma_f32_16x16x32_bf16 v[90:93], v[164:167], v[206:209], v[90:93]
	v_mfma_f32_16x16x32_bf16 v[82:85], v[156:159], v[214:217], v[82:85]
	v_mfma_f32_16x16x32_bf16 v[74:77], v[164:167], v[214:217], v[74:77]
	v_mfma_f32_16x16x32_bf16 v[118:121], v[168:171], v[186:189], v[118:121]
	v_mfma_f32_16x16x32_bf16 v[110:113], v[178:181], v[186:189], v[110:113]
	v_mfma_f32_16x16x32_bf16 v[102:105], v[168:171], v[194:197], v[102:105]
	v_mfma_f32_16x16x32_bf16 v[94:97], v[178:181], v[194:197], v[94:97]
	v_mfma_f32_16x16x32_bf16 v[86:89], v[168:171], v[202:205], v[86:89]
	v_mfma_f32_16x16x32_bf16 v[78:81], v[178:181], v[202:205], v[78:81]
	v_mfma_f32_16x16x32_bf16 v[70:73], v[168:171], v[210:213], v[70:73]
	v_mfma_f32_16x16x32_bf16 v[66:69], v[178:181], v[210:213], v[66:69]
	v_mfma_f32_16x16x32_bf16 v[118:121], v[172:175], v[190:193], v[118:121]
	v_mfma_f32_16x16x32_bf16 v[110:113], v[182:185], v[190:193], v[110:113]
	v_mfma_f32_16x16x32_bf16 v[102:105], v[172:175], v[198:201], v[102:105]
	v_mfma_f32_16x16x32_bf16 v[94:97], v[182:185], v[198:201], v[94:97]
	v_mfma_f32_16x16x32_bf16 v[86:89], v[172:175], v[206:209], v[86:89]
	v_mfma_f32_16x16x32_bf16 v[78:81], v[182:185], v[206:209], v[78:81]
	v_mfma_f32_16x16x32_bf16 v[70:73], v[172:175], v[214:217], v[70:73]
	v_mfma_f32_16x16x32_bf16 v[66:69], v[182:185], v[214:217], v[66:69]
	s_barrier
	s_setprio 0
	s_add_i32 s2, s63, s43
	v_lshl_add_u64 v[144:145], v[144:145], 0, s[8:9]
	s_mov_b32 m0, s2
	ds_read_b128 v[186:189], v150 offset:49152
	ds_read_b128 v[190:193], v150 offset:50176
	ds_read_b128 v[194:197], v150 offset:51200
	ds_read_b128 v[198:201], v150 offset:52224
	ds_read_b128 v[202:205], v150 offset:53248
	ds_read_b128 v[206:209], v150 offset:54272
	ds_read_b128 v[210:213], v150 offset:55296
	ds_read_b128 v[214:217], v150 offset:56320
	global_load_lds_dwordx4 v[144:145], off
	s_add_i32 m0, s2, 0x2000
	s_add_u32 s2, s38, 0x40080
	v_lshl_add_u64 v[144:145], v[218:219], 0, s[8:9]
	s_addc_u32 s3, s39, 0
	s_add_i32 s38, s64, s43
	global_load_lds_dwordx4 v[144:145], off
	v_lshl_add_u64 v[144:145], s[2:3], 0, v[132:133]
	s_mov_b32 m0, s38
	s_nop 0
	global_load_lds_dwordx4 v[144:145], off
	v_lshl_add_u64 v[144:145], s[2:3], 0, v[136:137]
	s_add_i32 m0, s38, 0x2000
	s_nop 0
	global_load_lds_dwordx4 v[144:145], off
	v_lshl_add_u64 v[144:145], v[220:221], 0, s[8:9]
	s_mov_b32 m0, s48
	s_nop 0
	global_load_lds_dwordx4 v[144:145], off
	v_lshl_add_u64 v[144:145], v[222:223], 0, s[8:9]
	s_mov_b32 m0, s49
	s_nop 0
	global_load_lds_dwordx4 v[144:145], off
	s_waitcnt vmcnt(8)
	s_waitcnt lgkmcnt(0)
	s_setprio 1
	s_barrier
	v_mfma_f32_16x16x32_bf16 v[62:65], v[152:155], v[186:189], v[62:65]
	v_mfma_f32_16x16x32_bf16 v[58:61], v[160:163], v[186:189], v[58:61]
	v_mfma_f32_16x16x32_bf16 v[50:53], v[152:155], v[194:197], v[50:53]
	v_mfma_f32_16x16x32_bf16 v[42:45], v[160:163], v[194:197], v[42:45]
	v_mfma_f32_16x16x32_bf16 v[34:37], v[152:155], v[202:205], v[34:37]
	v_mfma_f32_16x16x32_bf16 v[26:29], v[160:163], v[202:205], v[26:29]
	v_mfma_f32_16x16x32_bf16 v[18:21], v[152:155], v[210:213], v[18:21]
	v_mfma_f32_16x16x32_bf16 v[10:13], v[160:163], v[210:213], v[10:13]
	v_mfma_f32_16x16x32_bf16 v[62:65], v[156:159], v[190:193], v[62:65]
	v_mfma_f32_16x16x32_bf16 v[58:61], v[164:167], v[190:193], v[58:61]
	v_mfma_f32_16x16x32_bf16 v[50:53], v[156:159], v[198:201], v[50:53]
	v_mfma_f32_16x16x32_bf16 v[42:45], v[164:167], v[198:201], v[42:45]
	v_mfma_f32_16x16x32_bf16 v[34:37], v[156:159], v[206:209], v[34:37]
	v_mfma_f32_16x16x32_bf16 v[26:29], v[164:167], v[206:209], v[26:29]
	v_mfma_f32_16x16x32_bf16 v[18:21], v[156:159], v[214:217], v[18:21]
	v_mfma_f32_16x16x32_bf16 v[10:13], v[164:167], v[214:217], v[10:13]
	v_mfma_f32_16x16x32_bf16 v[54:57], v[168:171], v[186:189], v[54:57]
	v_mfma_f32_16x16x32_bf16 v[46:49], v[178:181], v[186:189], v[46:49]
	v_mfma_f32_16x16x32_bf16 v[38:41], v[168:171], v[194:197], v[38:41]
	v_mfma_f32_16x16x32_bf16 v[30:33], v[178:181], v[194:197], v[30:33]
	v_mfma_f32_16x16x32_bf16 v[22:25], v[168:171], v[202:205], v[22:25]
	v_mfma_f32_16x16x32_bf16 v[14:17], v[178:181], v[202:205], v[14:17]
	v_mfma_f32_16x16x32_bf16 v[6:9], v[168:171], v[210:213], v[6:9]
	v_mfma_f32_16x16x32_bf16 v[2:5], v[178:181], v[210:213], v[2:5]
	v_mfma_f32_16x16x32_bf16 v[54:57], v[172:175], v[190:193], v[54:57]
	v_mfma_f32_16x16x32_bf16 v[46:49], v[182:185], v[190:193], v[46:49]
	v_mfma_f32_16x16x32_bf16 v[38:41], v[172:175], v[198:201], v[38:41]
	v_mfma_f32_16x16x32_bf16 v[30:33], v[182:185], v[198:201], v[30:33]
	v_mfma_f32_16x16x32_bf16 v[22:25], v[172:175], v[206:209], v[22:25]
	v_mfma_f32_16x16x32_bf16 v[14:17], v[182:185], v[206:209], v[14:17]
	v_mfma_f32_16x16x32_bf16 v[6:9], v[172:175], v[214:217], v[6:9]
	v_mfma_f32_16x16x32_bf16 v[2:5], v[182:185], v[214:217], v[2:5]
	s_barrier
	s_setprio 0
	s_add_i32 s62, s62, 2
	s_add_u32 s36, s36, 0x100
	s_addc_u32 s37, s37, 0
	s_add_u32 s60, s60, 0x100
	s_addc_u32 s61, s61, 0
	s_cmp_gt_u32 s62, 13
	s_cbranch_scc0 .LBB0_1239
	s_branch .Lpk1239_exit

.LBB0_1242:
	v_lshl_add_u32 v152, s34, 8, v1
	v_lshl_or_b32 v144, s57, 8, v147
	v_readlane_b32 s2, v252, 2
	v_ashrrev_i32_e32 v145, 31, v144
	v_readlane_b32 s3, v252, 3
	v_ashrrev_i32_e32 v153, 31, v152
	v_pk_add_f32 v[128:129], v[128:129], 0 op_sel_hi:[1,0]
	v_lshl_add_u64 v[154:155], v[144:145], 1, s[2:3]
	v_lshlrev_b64 v[144:145], 11, v[152:153]
	v_lshl_add_u64 v[144:145], v[154:155], 0, v[144:145]
	v_pk_add_f32 v[126:127], v[126:127], 0 op_sel_hi:[1,0]
	v_pk_add_f32 v[156:157], v[124:125], 0 op_sel_hi:[1,0]
	v_pk_add_f32 v[124:125], v[122:123], 0 op_sel_hi:[1,0]
	v_cvt_pk_bf16_f32 v122, v126, v127
	v_cvt_pk_bf16_f32 v123, v128, v129
	v_pk_add_f32 v[118:119], v[118:119], 0 op_sel_hi:[1,0]
	v_cvt_pk_bf16_f32 v124, v124, v125
	v_cvt_pk_bf16_f32 v125, v156, v157
	global_store_dwordx4 v[144:145], v[122:125], off
	v_pk_add_f32 v[120:121], v[120:121], 0 op_sel_hi:[1,0]
	v_pk_add_f32 v[114:115], v[114:115], 0 op_sel_hi:[1,0]
	v_pk_add_f32 v[122:123], v[112:113], 0 op_sel_hi:[1,0]
	v_pk_add_f32 v[112:113], v[110:111], 0 op_sel_hi:[1,0]
	v_cvt_pk_bf16_f32 v110, v118, v119
	v_cvt_pk_bf16_f32 v111, v120, v121
	v_pk_add_f32 v[102:103], v[102:103], 0 op_sel_hi:[1,0]
	v_cvt_pk_bf16_f32 v112, v112, v113
	v_cvt_pk_bf16_f32 v113, v122, v123
	global_store_dwordx4 v[144:145], v[110:113], off offset:256
	v_pk_add_f32 v[104:105], v[104:105], 0 op_sel_hi:[1,0]
	v_pk_add_f32 v[98:99], v[98:99], 0 op_sel_hi:[1,0]
	v_or_b32_e32 v110, 16, v152
	v_ashrrev_i32_e32 v111, 31, v110
	v_lshlrev_b64 v[110:111], 11, v[110:111]
	v_lshl_add_u64 v[110:111], v[154:155], 0, v[110:111]
	v_pk_add_f32 v[112:113], v[116:117], 0 op_sel_hi:[1,0]
	v_pk_add_f32 v[116:117], v[108:109], 0 op_sel_hi:[1,0]
	v_pk_add_f32 v[108:109], v[106:107], 0 op_sel_hi:[1,0]
	v_cvt_pk_bf16_f32 v106, v114, v115
	v_cvt_pk_bf16_f32 v107, v112, v113
	v_pk_add_f32 v[86:87], v[86:87], 0 op_sel_hi:[1,0]
	v_cvt_pk_bf16_f32 v108, v108, v109
	v_cvt_pk_bf16_f32 v109, v116, v117
	global_store_dwordx4 v[110:111], v[106:109], off
	v_pk_add_f32 v[88:89], v[88:89], 0 op_sel_hi:[1,0]
	v_pk_add_f32 v[82:83], v[82:83], 0 op_sel_hi:[1,0]
	v_pk_add_f32 v[106:107], v[96:97], 0 op_sel_hi:[1,0]
	v_pk_add_f32 v[96:97], v[94:95], 0 op_sel_hi:[1,0]
	v_cvt_pk_bf16_f32 v94, v102, v103
	v_cvt_pk_bf16_f32 v95, v104, v105
	v_pk_add_f32 v[72:73], v[72:73], 0 op_sel_hi:[1,0]
	v_cvt_pk_bf16_f32 v96, v96, v97
	v_cvt_pk_bf16_f32 v97, v106, v107
	global_store_dwordx4 v[110:111], v[94:97], off offset:256
	v_pk_add_f32 v[70:71], v[70:71], 0 op_sel_hi:[1,0]
	v_pk_add_f32 v[62:63], v[62:63], 0 op_sel_hi:[1,0]
	v_or_b32_e32 v94, 32, v152
	v_ashrrev_i32_e32 v95, 31, v94
	v_lshlrev_b64 v[94:95], 11, v[94:95]
	v_lshl_add_u64 v[94:95], v[154:155], 0, v[94:95]
	v_pk_add_f32 v[96:97], v[100:101], 0 op_sel_hi:[1,0]
	v_pk_add_f32 v[100:101], v[92:93], 0 op_sel_hi:[1,0]
	v_pk_add_f32 v[92:93], v[90:91], 0 op_sel_hi:[1,0]
	v_cvt_pk_bf16_f32 v90, v98, v99
	v_cvt_pk_bf16_f32 v91, v96, v97
	v_pk_add_f32 v[64:65], v[64:65], 0 op_sel_hi:[1,0]
	v_cvt_pk_bf16_f32 v92, v92, v93
	v_cvt_pk_bf16_f32 v93, v100, v101
	global_store_dwordx4 v[94:95], v[90:93], off
	s_mov_b64 s[2:3], 0x40000
	v_pk_add_f32 v[56:57], v[56:57], 0 op_sel_hi:[1,0]
	v_pk_add_f32 v[90:91], v[80:81], 0 op_sel_hi:[1,0]
	v_pk_add_f32 v[80:81], v[78:79], 0 op_sel_hi:[1,0]
	v_cvt_pk_bf16_f32 v78, v86, v87
	v_cvt_pk_bf16_f32 v79, v88, v89
	v_pk_add_f32 v[54:55], v[54:55], 0 op_sel_hi:[1,0]
	v_cvt_pk_bf16_f32 v80, v80, v81
	v_cvt_pk_bf16_f32 v81, v90, v91
	global_store_dwordx4 v[94:95], v[78:81], off offset:256
	v_pk_add_f32 v[50:51], v[50:51], 0 op_sel_hi:[1,0]
	v_pk_add_f32 v[40:41], v[40:41], 0 op_sel_hi:[1,0]
	v_or_b32_e32 v78, 48, v152
	v_ashrrev_i32_e32 v79, 31, v78
	v_lshlrev_b64 v[78:79], 11, v[78:79]
	v_lshl_add_u64 v[78:79], v[154:155], 0, v[78:79]
	v_pk_add_f32 v[80:81], v[84:85], 0 op_sel_hi:[1,0]
	v_pk_add_f32 v[84:85], v[76:77], 0 op_sel_hi:[1,0]
	v_pk_add_f32 v[76:77], v[74:75], 0 op_sel_hi:[1,0]
	v_cvt_pk_bf16_f32 v74, v82, v83
	v_cvt_pk_bf16_f32 v75, v80, v81
	v_pk_add_f32 v[38:39], v[38:39], 0 op_sel_hi:[1,0]
	v_cvt_pk_bf16_f32 v76, v76, v77
	v_cvt_pk_bf16_f32 v77, v84, v85
	global_store_dwordx4 v[78:79], v[74:77], off
	v_pk_add_f32 v[34:35], v[34:35], 0 op_sel_hi:[1,0]
	v_pk_add_f32 v[24:25], v[24:25], 0 op_sel_hi:[1,0]
	v_pk_add_f32 v[74:75], v[68:69], 0 op_sel_hi:[1,0]
	v_pk_add_f32 v[68:69], v[66:67], 0 op_sel_hi:[1,0]
	v_cvt_pk_bf16_f32 v66, v70, v71
	v_cvt_pk_bf16_f32 v67, v72, v73
	v_pk_add_f32 v[22:23], v[22:23], 0 op_sel_hi:[1,0]
	v_cvt_pk_bf16_f32 v68, v68, v69
	v_cvt_pk_bf16_f32 v69, v74, v75
	global_store_dwordx4 v[78:79], v[66:69], off offset:256
	v_pk_add_f32 v[18:19], v[18:19], 0 op_sel_hi:[1,0]
	v_pk_add_f32 v[8:9], v[8:9], 0 op_sel_hi:[1,0]
	v_pk_add_f32 v[68:69], v[60:61], 0 op_sel_hi:[1,0]
	v_pk_add_f32 v[60:61], v[58:59], 0 op_sel_hi:[1,0]
	v_cvt_pk_bf16_f32 v58, v62, v63
	v_add_co_u32_e32 v62, vcc, s53, v144
	v_cvt_pk_bf16_f32 v59, v64, v65
	v_cvt_pk_bf16_f32 v60, v60, v61
	v_cvt_pk_bf16_f32 v61, v68, v69
	v_lshl_add_u64 v[66:67], v[144:145], 0, s[2:3]
	s_nop 0
	v_addc_co_u32_e32 v63, vcc, 0, v145, vcc
	global_store_dwordx4 v[62:63], v[58:61], off
	s_mov_b64 s[2:3], -1
	v_pk_add_f32 v[6:7], v[6:7], 0 op_sel_hi:[1,0]
	v_pk_add_f32 v[58:59], v[48:49], 0 op_sel_hi:[1,0]
	v_pk_add_f32 v[48:49], v[46:47], 0 op_sel_hi:[1,0]
	v_cvt_pk_bf16_f32 v46, v54, v55
	v_cvt_pk_bf16_f32 v47, v56, v57
	s_nop 0
	v_cvt_pk_bf16_f32 v48, v48, v49
	v_cvt_pk_bf16_f32 v49, v58, v59
	global_store_dwordx4 v[66:67], v[46:49], off offset:256
	s_nop 1
	v_pk_add_f32 v[48:49], v[52:53], 0 op_sel_hi:[1,0]
	v_pk_add_f32 v[52:53], v[44:45], 0 op_sel_hi:[1,0]
	v_pk_add_f32 v[44:45], v[42:43], 0 op_sel_hi:[1,0]
	v_cvt_pk_bf16_f32 v42, v50, v51
	v_cvt_pk_bf16_f32 v43, v48, v49
	v_add_co_u32_e32 v48, vcc, s54, v144
	v_cvt_pk_bf16_f32 v44, v44, v45
	v_cvt_pk_bf16_f32 v45, v52, v53
	v_lshl_add_u64 v[46:47], v[144:145], 0, s[12:13]
	s_nop 0
	v_addc_co_u32_e32 v49, vcc, 0, v145, vcc
	global_store_dwordx4 v[48:49], v[42:45], off
	s_nop 1
	v_pk_add_f32 v[42:43], v[32:33], 0 op_sel_hi:[1,0]
	v_pk_add_f32 v[32:33], v[30:31], 0 op_sel_hi:[1,0]
	v_cvt_pk_bf16_f32 v30, v38, v39
	v_cvt_pk_bf16_f32 v31, v40, v41
	s_nop 0
	v_cvt_pk_bf16_f32 v32, v32, v33
	v_cvt_pk_bf16_f32 v33, v42, v43
	global_store_dwordx4 v[46:47], v[30:33], off offset:256
	s_nop 1
	v_pk_add_f32 v[32:33], v[36:37], 0 op_sel_hi:[1,0]
	v_pk_add_f32 v[36:37], v[28:29], 0 op_sel_hi:[1,0]
	v_pk_add_f32 v[28:29], v[26:27], 0 op_sel_hi:[1,0]
	v_cvt_pk_bf16_f32 v26, v34, v35
	v_cvt_pk_bf16_f32 v27, v32, v33
	v_add_co_u32_e32 v32, vcc, s55, v144
	v_cvt_pk_bf16_f32 v28, v28, v29
	v_cvt_pk_bf16_f32 v29, v36, v37
	v_lshl_add_u64 v[30:31], v[144:145], 0, s[14:15]
	s_nop 0
	v_addc_co_u32_e32 v33, vcc, 0, v145, vcc
	global_store_dwordx4 v[32:33], v[26:29], off
	s_nop 1
	v_pk_add_f32 v[26:27], v[16:17], 0 op_sel_hi:[1,0]
	v_pk_add_f32 v[16:17], v[14:15], 0 op_sel_hi:[1,0]
	v_cvt_pk_bf16_f32 v14, v22, v23
	v_cvt_pk_bf16_f32 v15, v24, v25
	s_nop 0
	v_cvt_pk_bf16_f32 v16, v16, v17
	v_cvt_pk_bf16_f32 v17, v26, v27
	global_store_dwordx4 v[30:31], v[14:17], off offset:256
	s_nop 1
	v_pk_add_f32 v[16:17], v[20:21], 0 op_sel_hi:[1,0]
	v_pk_add_f32 v[20:21], v[12:13], 0 op_sel_hi:[1,0]
	v_pk_add_f32 v[12:13], v[10:11], 0 op_sel_hi:[1,0]
	v_cvt_pk_bf16_f32 v10, v18, v19
	v_cvt_pk_bf16_f32 v11, v16, v17
	v_add_co_u32_e32 v16, vcc, s56, v144
	v_lshl_add_u64 v[14:15], v[144:145], 0, s[16:17]
	s_nop 0
	v_addc_co_u32_e32 v17, vcc, 0, v145, vcc
	v_cvt_pk_bf16_f32 v12, v12, v13
	v_cvt_pk_bf16_f32 v13, v20, v21
	global_store_dwordx4 v[16:17], v[10:13], off
	s_andn2_b64 vcc, exec, s[26:27]
	s_nop 0
	v_pk_add_f32 v[10:11], v[4:5], 0 op_sel_hi:[1,0]
	v_pk_add_f32 v[4:5], v[2:3], 0 op_sel_hi:[1,0]
	v_cvt_pk_bf16_f32 v2, v6, v7
	v_cvt_pk_bf16_f32 v3, v8, v9
	s_nop 0
	v_cvt_pk_bf16_f32 v4, v4, v5
	v_cvt_pk_bf16_f32 v5, v10, v11
	global_store_dwordx4 v[14:15], v[2:5], off offset:256
	s_cbranch_vccnz .LBB0_1230
	s_andn2_b64 vcc, exec, s[6:7]
	s_cbranch_vccnz .LBB0_1229
	s_branch .LBB0_1229

.LBB0_1302:
	s_lshl_b64 s[2:3], s[14:15], 1
	v_readlane_b32 s20, v253, 52
	v_readlane_b32 s21, v253, 53
	s_add_u32 s20, s20, s2
	s_addc_u32 s21, s21, s3
	s_and_b64 s[2:3], s[18:19], exec
	s_cselect_b32 s11, s21, s27
	s_cselect_b32 s13, s20, s26
	s_lshl_b64 s[2:3], s[16:17], 1
	s_add_u32 s22, s48, s2
	s_addc_u32 s23, s49, s3
	s_and_b64 s[2:3], s[18:19], exec
	s_cselect_b32 s47, s23, s29
	s_cselect_b32 s52, s22, s28
	s_add_u32 s26, s26, 0x40080
	s_addc_u32 s27, s27, 0
	s_add_u32 s53, s28, 0x100
	s_addc_u32 s54, s29, 0
	s_mov_b32 s55, -2
	s_cmp_lt_u32 s37, 2
	s_cbranch_scc1 .Lz1s1303
	s_andn2_b64 vcc, exec, s[0:1]
	s_cbranch_vccnz .Lz1s1303
	s_barrier
.Lz1s1303:
.Lpk1303_peel:
	ds_read_b128 v[166:169], v139
	ds_read_b128 v[170:173], v139 offset:1024
	ds_read_b128 v[178:181], v139 offset:2048
	ds_read_b128 v[182:185], v139 offset:3072
	ds_read_b128 v[186:189], v163
	ds_read_b128 v[190:193], v163 offset:1024
	ds_read_b128 v[194:197], v163 offset:2048
	ds_read_b128 v[198:201], v163 offset:3072
	s_add_u32 s2, s26, 0xfffc0080
	s_addc_u32 s3, s27, -1
	s_cmp_eq_u32 s55, 12
	s_cselect_b32 s3, s11, s3
	s_cselect_b32 s2, s13, s2
	s_cselect_b32 s29, s47, s54
	s_cselect_b32 s28, s52, s53
	v_lshl_add_u64 v[148:149], s[26:27], 0, v[142:143]
	s_add_i32 m0, s34, 0xc000
	ds_read_b128 v[202:205], v164
	ds_read_b128 v[206:209], v164 offset:1024
	ds_read_b128 v[210:213], v164 offset:2048
	ds_read_b128 v[214:217], v164 offset:3072
	ds_read_b128 v[218:221], v164 offset:4096
	ds_read_b128 v[222:225], v164 offset:5120
	ds_read_b128 v[226:229], v164 offset:6144
	ds_read_b128 v[230:233], v164 offset:7168
	global_load_lds_dwordx4 v[148:149], off
	v_lshl_add_u64 v[148:149], s[26:27], 0, v[144:145]
	s_add_i32 m0, s34, 0xe000
	s_nop 0
	global_load_lds_dwordx4 v[148:149], off
	s_waitcnt vmcnt(8)
	s_waitcnt lgkmcnt(0)
	s_setprio 1
	s_barrier
	v_mfma_f32_16x16x32_bf16 v[126:129], v[166:169], v[202:205], 0
	v_mfma_f32_16x16x32_bf16 v[122:125], v[178:181], v[202:205], 0
	v_mfma_f32_16x16x32_bf16 v[110:113], v[166:169], v[210:213], 0
	v_mfma_f32_16x16x32_bf16 v[106:109], v[178:181], v[210:213], 0
	v_mfma_f32_16x16x32_bf16 v[94:97], v[166:169], v[218:221], 0
	v_mfma_f32_16x16x32_bf16 v[90:93], v[178:181], v[218:221], 0
	v_mfma_f32_16x16x32_bf16 v[78:81], v[166:169], v[226:229], 0
	v_mfma_f32_16x16x32_bf16 v[74:77], v[178:181], v[226:229], 0
	v_mfma_f32_16x16x32_bf16 v[126:129], v[170:173], v[206:209], v[126:129]
	v_mfma_f32_16x16x32_bf16 v[122:125], v[182:185], v[206:209], v[122:125]
	v_mfma_f32_16x16x32_bf16 v[110:113], v[170:173], v[214:217], v[110:113]
	v_mfma_f32_16x16x32_bf16 v[106:109], v[182:185], v[214:217], v[106:109]
	v_mfma_f32_16x16x32_bf16 v[94:97], v[170:173], v[222:225], v[94:97]
	v_mfma_f32_16x16x32_bf16 v[90:93], v[182:185], v[222:225], v[90:93]
	v_mfma_f32_16x16x32_bf16 v[78:81], v[170:173], v[230:233], v[78:81]
	v_mfma_f32_16x16x32_bf16 v[74:77], v[182:185], v[230:233], v[74:77]
	v_mfma_f32_16x16x32_bf16 v[118:121], v[186:189], v[202:205], 0
	v_mfma_f32_16x16x32_bf16 v[114:117], v[194:197], v[202:205], 0
	v_mfma_f32_16x16x32_bf16 v[102:105], v[186:189], v[210:213], 0
	v_mfma_f32_16x16x32_bf16 v[98:101], v[194:197], v[210:213], 0
	v_mfma_f32_16x16x32_bf16 v[86:89], v[186:189], v[218:221], 0
	v_mfma_f32_16x16x32_bf16 v[82:85], v[194:197], v[218:221], 0
	v_mfma_f32_16x16x32_bf16 v[70:73], v[186:189], v[226:229], 0
	v_mfma_f32_16x16x32_bf16 v[66:69], v[194:197], v[226:229], 0
	v_mfma_f32_16x16x32_bf16 v[118:121], v[190:193], v[206:209], v[118:121]
	v_mfma_f32_16x16x32_bf16 v[114:117], v[198:201], v[206:209], v[114:117]
	v_mfma_f32_16x16x32_bf16 v[102:105], v[190:193], v[214:217], v[102:105]
	v_mfma_f32_16x16x32_bf16 v[98:101], v[198:201], v[214:217], v[98:101]
	v_mfma_f32_16x16x32_bf16 v[86:89], v[190:193], v[222:225], v[86:89]
	v_mfma_f32_16x16x32_bf16 v[82:85], v[198:201], v[222:225], v[82:85]
	v_mfma_f32_16x16x32_bf16 v[70:73], v[190:193], v[230:233], v[70:73]
	v_mfma_f32_16x16x32_bf16 v[66:69], v[198:201], v[230:233], v[66:69]
	s_barrier
	s_setprio 0
	s_add_i32 s56, s42, s30
	v_lshl_add_u64 v[148:149], s[28:29], 0, v[132:133]
	s_mov_b32 m0, s56
	ds_read_b128 v[202:205], v164 offset:16384
	ds_read_b128 v[206:209], v164 offset:17408
	ds_read_b128 v[210:213], v164 offset:18432
	ds_read_b128 v[214:217], v164 offset:19456
	ds_read_b128 v[218:221], v164 offset:20480
	ds_read_b128 v[222:225], v164 offset:21504
	ds_read_b128 v[226:229], v164 offset:22528
	ds_read_b128 v[230:233], v164 offset:23552
	global_load_lds_dwordx4 v[148:149], off
	s_add_i32 m0, s56, 0x2000
	s_add_u32 s56, s28, 0x40000
	v_lshl_add_u64 v[174:175], s[28:29], 0, v[136:137]
	s_addc_u32 s57, s29, 0
	s_add_i32 s58, s43, s30
	global_load_lds_dwordx4 v[174:175], off
	v_lshl_add_u64 v[234:235], s[56:57], 0, v[132:133]
	s_mov_b32 m0, s58
	v_lshl_add_u64 v[236:237], s[2:3], 0, v[134:135]
	global_load_lds_dwordx4 v[234:235], off
	v_lshl_add_u64 v[234:235], s[56:57], 0, v[136:137]
	s_add_i32 m0, s58, 0x2000
	s_nop 0
	global_load_lds_dwordx4 v[234:235], off
	v_lshl_add_u64 v[234:235], s[2:3], 0, v[130:131]
	s_mov_b32 m0, s34
	s_nop 0
	global_load_lds_dwordx4 v[234:235], off
	s_mov_b32 m0, s25
	s_nop 0
	global_load_lds_dwordx4 v[236:237], off
	s_waitcnt vmcnt(8)
	s_waitcnt lgkmcnt(0)
	s_setprio 1
	s_barrier
	v_mfma_f32_16x16x32_bf16 v[62:65], v[166:169], v[202:205], 0
	v_mfma_f32_16x16x32_bf16 v[58:61], v[178:181], v[202:205], 0
	v_mfma_f32_16x16x32_bf16 v[46:49], v[166:169], v[210:213], 0
	v_mfma_f32_16x16x32_bf16 v[42:45], v[178:181], v[210:213], 0
	v_mfma_f32_16x16x32_bf16 v[30:33], v[166:169], v[218:221], 0
	v_mfma_f32_16x16x32_bf16 v[26:29], v[178:181], v[218:221], 0
	v_mfma_f32_16x16x32_bf16 v[14:17], v[166:169], v[226:229], 0
	v_mfma_f32_16x16x32_bf16 v[10:13], v[178:181], v[226:229], 0
	v_mfma_f32_16x16x32_bf16 v[62:65], v[170:173], v[206:209], v[62:65]
	v_mfma_f32_16x16x32_bf16 v[58:61], v[182:185], v[206:209], v[58:61]
	v_mfma_f32_16x16x32_bf16 v[46:49], v[170:173], v[214:217], v[46:49]
	v_mfma_f32_16x16x32_bf16 v[42:45], v[182:185], v[214:217], v[42:45]
	v_mfma_f32_16x16x32_bf16 v[30:33], v[170:173], v[222:225], v[30:33]
	v_mfma_f32_16x16x32_bf16 v[26:29], v[182:185], v[222:225], v[26:29]
	v_mfma_f32_16x16x32_bf16 v[14:17], v[170:173], v[230:233], v[14:17]
	v_mfma_f32_16x16x32_bf16 v[10:13], v[182:185], v[230:233], v[10:13]
	v_mfma_f32_16x16x32_bf16 v[54:57], v[186:189], v[202:205], 0
	v_mfma_f32_16x16x32_bf16 v[50:53], v[194:197], v[202:205], 0
	v_mfma_f32_16x16x32_bf16 v[38:41], v[186:189], v[210:213], 0
	v_mfma_f32_16x16x32_bf16 v[34:37], v[194:197], v[210:213], 0
	v_mfma_f32_16x16x32_bf16 v[22:25], v[186:189], v[218:221], 0
	v_mfma_f32_16x16x32_bf16 v[18:21], v[194:197], v[218:221], 0
	v_mfma_f32_16x16x32_bf16 v[6:9], v[186:189], v[226:229], 0
	v_mfma_f32_16x16x32_bf16 v[2:5], v[194:197], v[226:229], 0
	v_mfma_f32_16x16x32_bf16 v[54:57], v[190:193], v[206:209], v[54:57]
	v_mfma_f32_16x16x32_bf16 v[50:53], v[198:201], v[206:209], v[50:53]
	v_mfma_f32_16x16x32_bf16 v[38:41], v[190:193], v[214:217], v[38:41]
	v_mfma_f32_16x16x32_bf16 v[34:37], v[198:201], v[214:217], v[34:37]
	v_mfma_f32_16x16x32_bf16 v[22:25], v[190:193], v[222:225], v[22:25]
	v_mfma_f32_16x16x32_bf16 v[18:21], v[198:201], v[222:225], v[18:21]
	v_mfma_f32_16x16x32_bf16 v[6:9], v[190:193], v[230:233], v[6:9]
	v_mfma_f32_16x16x32_bf16 v[2:5], v[198:201], v[230:233], v[2:5]
	s_barrier
	s_setprio 0
	s_add_i32 s56, 0, 0x18000
	v_add_u32_e32 v165, s56, v162
	s_add_i32 s57, 0, 0x1c000
	ds_read_b128 v[166:169], v165
	ds_read_b128 v[170:173], v165 offset:1024
	ds_read_b128 v[178:181], v165 offset:2048
	ds_read_b128 v[182:185], v165 offset:3072
	v_add_u32_e32 v165, s57, v162
	ds_read_b128 v[186:189], v165
	ds_read_b128 v[190:193], v165 offset:1024
	ds_read_b128 v[194:197], v165 offset:2048
	ds_read_b128 v[198:201], v165 offset:3072
	s_add_u32 s2, s2, 0x40000
	s_addc_u32 s3, s3, 0
	s_mov_b32 m0, s35
	v_lshl_add_u64 v[238:239], s[2:3], 0, v[130:131]
	ds_read_b128 v[202:205], v164 offset:32768
	ds_read_b128 v[206:209], v164 offset:33792
	ds_read_b128 v[210:213], v164 offset:34816
	ds_read_b128 v[214:217], v164 offset:35840
	ds_read_b128 v[218:221], v164 offset:36864
	ds_read_b128 v[222:225], v164 offset:37888
	ds_read_b128 v[226:229], v164 offset:38912
	ds_read_b128 v[230:233], v164 offset:39936
	global_load_lds_dwordx4 v[238:239], off
	v_lshl_add_u64 v[238:239], s[2:3], 0, v[134:135]
	s_mov_b32 m0, s36
	s_nop 0
	global_load_lds_dwordx4 v[238:239], off
	s_waitcnt vmcnt(8)
	s_waitcnt lgkmcnt(0)
	s_setprio 1
	s_barrier
	v_mfma_f32_16x16x32_bf16 v[126:129], v[166:169], v[202:205], v[126:129]
	v_mfma_f32_16x16x32_bf16 v[122:125], v[178:181], v[202:205], v[122:125]
	v_mfma_f32_16x16x32_bf16 v[110:113], v[166:169], v[210:213], v[110:113]
	v_mfma_f32_16x16x32_bf16 v[106:109], v[178:181], v[210:213], v[106:109]
	v_mfma_f32_16x16x32_bf16 v[94:97], v[166:169], v[218:221], v[94:97]
	v_mfma_f32_16x16x32_bf16 v[90:93], v[178:181], v[218:221], v[90:93]
	v_mfma_f32_16x16x32_bf16 v[78:81], v[166:169], v[226:229], v[78:81]
	v_mfma_f32_16x16x32_bf16 v[74:77], v[178:181], v[226:229], v[74:77]
	v_mfma_f32_16x16x32_bf16 v[126:129], v[170:173], v[206:209], v[126:129]
	v_mfma_f32_16x16x32_bf16 v[122:125], v[182:185], v[206:209], v[122:125]
	v_mfma_f32_16x16x32_bf16 v[110:113], v[170:173], v[214:217], v[110:113]
	v_mfma_f32_16x16x32_bf16 v[106:109], v[182:185], v[214:217], v[106:109]
	v_mfma_f32_16x16x32_bf16 v[94:97], v[170:173], v[222:225], v[94:97]
	v_mfma_f32_16x16x32_bf16 v[90:93], v[182:185], v[222:225], v[90:93]
	v_mfma_f32_16x16x32_bf16 v[78:81], v[170:173], v[230:233], v[78:81]
	v_mfma_f32_16x16x32_bf16 v[74:77], v[182:185], v[230:233], v[74:77]
	v_mfma_f32_16x16x32_bf16 v[118:121], v[186:189], v[202:205], v[118:121]
	v_mfma_f32_16x16x32_bf16 v[114:117], v[194:197], v[202:205], v[114:117]
	v_mfma_f32_16x16x32_bf16 v[102:105], v[186:189], v[210:213], v[102:105]
	v_mfma_f32_16x16x32_bf16 v[98:101], v[194:197], v[210:213], v[98:101]
	v_mfma_f32_16x16x32_bf16 v[86:89], v[186:189], v[218:221], v[86:89]
	v_mfma_f32_16x16x32_bf16 v[82:85], v[194:197], v[218:221], v[82:85]
	v_mfma_f32_16x16x32_bf16 v[70:73], v[186:189], v[226:229], v[70:73]
	v_mfma_f32_16x16x32_bf16 v[66:69], v[194:197], v[226:229], v[66:69]
	v_mfma_f32_16x16x32_bf16 v[118:121], v[190:193], v[206:209], v[118:121]
	v_mfma_f32_16x16x32_bf16 v[114:117], v[198:201], v[206:209], v[114:117]
	v_mfma_f32_16x16x32_bf16 v[102:105], v[190:193], v[214:217], v[102:105]
	v_mfma_f32_16x16x32_bf16 v[98:101], v[198:201], v[214:217], v[98:101]
	v_mfma_f32_16x16x32_bf16 v[86:89], v[190:193], v[222:225], v[86:89]
	v_mfma_f32_16x16x32_bf16 v[82:85], v[198:201], v[222:225], v[82:85]
	v_mfma_f32_16x16x32_bf16 v[70:73], v[190:193], v[230:233], v[70:73]
	v_mfma_f32_16x16x32_bf16 v[66:69], v[198:201], v[230:233], v[66:69]
	s_barrier
	s_setprio 0
	s_add_i32 s2, s56, s30
	v_lshl_add_u64 v[148:149], v[148:149], 0, s[6:7]
	s_mov_b32 m0, s2
	ds_read_b128 v[202:205], v164 offset:49152
	ds_read_b128 v[206:209], v164 offset:50176
	ds_read_b128 v[210:213], v164 offset:51200
	ds_read_b128 v[214:217], v164 offset:52224
	ds_read_b128 v[218:221], v164 offset:53248
	ds_read_b128 v[222:225], v164 offset:54272
	ds_read_b128 v[226:229], v164 offset:55296
	ds_read_b128 v[230:233], v164 offset:56320
	global_load_lds_dwordx4 v[148:149], off
	s_add_i32 m0, s2, 0x2000
	s_add_u32 s2, s28, 0x40080
	v_lshl_add_u64 v[148:149], v[174:175], 0, s[6:7]
	s_addc_u32 s3, s29, 0
	s_add_i32 s28, s57, s30
	global_load_lds_dwordx4 v[148:149], off
	v_lshl_add_u64 v[148:149], s[2:3], 0, v[132:133]
	s_mov_b32 m0, s28
	s_nop 0
	global_load_lds_dwordx4 v[148:149], off
	v_lshl_add_u64 v[148:149], s[2:3], 0, v[136:137]
	s_add_i32 m0, s28, 0x2000
	s_nop 0
	global_load_lds_dwordx4 v[148:149], off
	v_lshl_add_u64 v[148:149], v[234:235], 0, s[6:7]
	s_mov_b32 m0, s39
	s_nop 0
	global_load_lds_dwordx4 v[148:149], off
	v_lshl_add_u64 v[148:149], v[236:237], 0, s[6:7]
	s_mov_b32 m0, s40
	s_nop 0
	global_load_lds_dwordx4 v[148:149], off
	s_waitcnt vmcnt(8)
	s_waitcnt lgkmcnt(0)
	s_setprio 1
	s_barrier
	v_mfma_f32_16x16x32_bf16 v[62:65], v[166:169], v[202:205], v[62:65]
	v_mfma_f32_16x16x32_bf16 v[58:61], v[178:181], v[202:205], v[58:61]
	v_mfma_f32_16x16x32_bf16 v[46:49], v[166:169], v[210:213], v[46:49]
	v_mfma_f32_16x16x32_bf16 v[42:45], v[178:181], v[210:213], v[42:45]
	v_mfma_f32_16x16x32_bf16 v[30:33], v[166:169], v[218:221], v[30:33]
	v_mfma_f32_16x16x32_bf16 v[26:29], v[178:181], v[218:221], v[26:29]
	v_mfma_f32_16x16x32_bf16 v[14:17], v[166:169], v[226:229], v[14:17]
	v_mfma_f32_16x16x32_bf16 v[10:13], v[178:181], v[226:229], v[10:13]
	v_mfma_f32_16x16x32_bf16 v[62:65], v[170:173], v[206:209], v[62:65]
	v_mfma_f32_16x16x32_bf16 v[58:61], v[182:185], v[206:209], v[58:61]
	v_mfma_f32_16x16x32_bf16 v[46:49], v[170:173], v[214:217], v[46:49]
	v_mfma_f32_16x16x32_bf16 v[42:45], v[182:185], v[214:217], v[42:45]
	v_mfma_f32_16x16x32_bf16 v[30:33], v[170:173], v[222:225], v[30:33]
	v_mfma_f32_16x16x32_bf16 v[26:29], v[182:185], v[222:225], v[26:29]
	v_mfma_f32_16x16x32_bf16 v[14:17], v[170:173], v[230:233], v[14:17]
	v_mfma_f32_16x16x32_bf16 v[10:13], v[182:185], v[230:233], v[10:13]
	v_mfma_f32_16x16x32_bf16 v[54:57], v[186:189], v[202:205], v[54:57]
	v_mfma_f32_16x16x32_bf16 v[50:53], v[194:197], v[202:205], v[50:53]
	v_mfma_f32_16x16x32_bf16 v[38:41], v[186:189], v[210:213], v[38:41]
	v_mfma_f32_16x16x32_bf16 v[34:37], v[194:197], v[210:213], v[34:37]
	v_mfma_f32_16x16x32_bf16 v[22:25], v[186:189], v[218:221], v[22:25]
	v_mfma_f32_16x16x32_bf16 v[18:21], v[194:197], v[218:221], v[18:21]
	v_mfma_f32_16x16x32_bf16 v[6:9], v[186:189], v[226:229], v[6:9]
	v_mfma_f32_16x16x32_bf16 v[2:5], v[194:197], v[226:229], v[2:5]
	v_mfma_f32_16x16x32_bf16 v[54:57], v[190:193], v[206:209], v[54:57]
	v_mfma_f32_16x16x32_bf16 v[50:53], v[198:201], v[206:209], v[50:53]
	v_mfma_f32_16x16x32_bf16 v[38:41], v[190:193], v[214:217], v[38:41]
	v_mfma_f32_16x16x32_bf16 v[34:37], v[198:201], v[214:217], v[34:37]
	v_mfma_f32_16x16x32_bf16 v[22:25], v[190:193], v[222:225], v[22:25]
	v_mfma_f32_16x16x32_bf16 v[18:21], v[198:201], v[222:225], v[18:21]
	v_mfma_f32_16x16x32_bf16 v[6:9], v[190:193], v[230:233], v[6:9]
	v_mfma_f32_16x16x32_bf16 v[2:5], v[198:201], v[230:233], v[2:5]
	s_barrier
	s_setprio 0
	s_add_i32 s55, s55, 2
	s_add_u32 s26, s26, 0x100
	s_addc_u32 s27, s27, 0
	s_add_u32 s53, s53, 0x100
	s_addc_u32 s54, s54, 0
	s_cmp_gt_u32 s55, 13
	s_cbranch_scc0 .LBB0_1303
	s_branch .Lpk1303_exit

.LBB0_1306:
	s_mov_b32 s100, 0xbfb8aa3b
	v_pk_mul_f32 v[166:167], v[126:127], s[100:101] op_sel_hi:[1,0]
	v_pk_mul_f32 v[168:169], v[128:129], s[100:101] op_sel_hi:[1,0]
	v_pk_mul_f32 v[170:171], v[122:123], s[100:101] op_sel_hi:[1,0]
	v_pk_mul_f32 v[172:173], v[124:125], s[100:101] op_sel_hi:[1,0]
	v_exp_f32_e32 v166, v166
	v_exp_f32_e32 v167, v167
	v_exp_f32_e32 v168, v168
	v_exp_f32_e32 v169, v169
	v_exp_f32_e32 v170, v170
	v_exp_f32_e32 v171, v171
	v_exp_f32_e32 v172, v172
	v_exp_f32_e32 v173, v173
	v_pk_add_f32 v[166:167], v[166:167], 1.0 op_sel_hi:[1,0]
	v_pk_add_f32 v[168:169], v[168:169], 1.0 op_sel_hi:[1,0]
	v_pk_add_f32 v[170:171], v[170:171], 1.0 op_sel_hi:[1,0]
	v_pk_add_f32 v[172:173], v[172:173], 1.0 op_sel_hi:[1,0]
	v_rcp_f32_e32 v166, v166
	v_rcp_f32_e32 v167, v167
	v_rcp_f32_e32 v168, v168
	v_rcp_f32_e32 v169, v169
	v_rcp_f32_e32 v170, v170
	v_rcp_f32_e32 v171, v171
	v_rcp_f32_e32 v172, v172
	v_rcp_f32_e32 v173, v173
	v_pk_mul_f32 v[166:167], v[126:127], v[166:167]
	v_pk_mul_f32 v[168:169], v[128:129], v[168:169]
	v_pk_mul_f32 v[170:171], v[122:123], v[170:171]
	v_pk_mul_f32 v[172:173], v[124:125], v[172:173]
	v_pk_mul_f32 v[166:167], v[166:167], v[118:119]
	v_pk_mul_f32 v[168:169], v[168:169], v[120:121]
	v_pk_mul_f32 v[170:171], v[170:171], v[114:115]
	v_pk_mul_f32 v[172:173], v[172:173], v[116:117]
	s_lshl_b32 s3, s46, 1
	s_mul_i32 s2, s24, 44
	s_or_b32 s3, s3, s41
	s_add_i32 s2, s3, s2
	s_ashr_i32 s3, s2, 31
	s_lshl_b64 s[2:3], s[2:3], 15
	v_lshl_add_u64 v[148:149], v[140:141], 0, s[2:3]
	v_cvt_pk_bf16_f32 v114, v166, v167
	v_cvt_pk_bf16_f32 v115, v168, v169
	v_cvt_pk_bf16_f32 v116, v170, v171
	v_cvt_pk_bf16_f32 v117, v172, v173
	global_store_dwordx4 v[148:149], v[114:117], off
	v_pk_mul_f32 v[166:167], v[110:111], s[100:101] op_sel_hi:[1,0]
	v_pk_mul_f32 v[168:169], v[112:113], s[100:101] op_sel_hi:[1,0]
	v_pk_mul_f32 v[170:171], v[106:107], s[100:101] op_sel_hi:[1,0]
	v_pk_mul_f32 v[172:173], v[108:109], s[100:101] op_sel_hi:[1,0]
	v_exp_f32_e32 v166, v166
	v_exp_f32_e32 v167, v167
	v_exp_f32_e32 v168, v168
	v_exp_f32_e32 v169, v169
	v_exp_f32_e32 v170, v170
	v_exp_f32_e32 v171, v171
	v_exp_f32_e32 v172, v172
	v_exp_f32_e32 v173, v173
	v_pk_add_f32 v[166:167], v[166:167], 1.0 op_sel_hi:[1,0]
	v_pk_add_f32 v[168:169], v[168:169], 1.0 op_sel_hi:[1,0]
	v_pk_add_f32 v[170:171], v[170:171], 1.0 op_sel_hi:[1,0]
	v_pk_add_f32 v[172:173], v[172:173], 1.0 op_sel_hi:[1,0]
	v_rcp_f32_e32 v166, v166
	v_rcp_f32_e32 v167, v167
	v_rcp_f32_e32 v168, v168
	v_rcp_f32_e32 v169, v169
	v_rcp_f32_e32 v170, v170
	v_rcp_f32_e32 v171, v171
	v_rcp_f32_e32 v172, v172
	v_rcp_f32_e32 v173, v173
	v_pk_mul_f32 v[166:167], v[110:111], v[166:167]
	v_pk_mul_f32 v[168:169], v[112:113], v[168:169]
	v_pk_mul_f32 v[170:171], v[106:107], v[170:171]
	v_pk_mul_f32 v[172:173], v[108:109], v[172:173]
	v_pk_mul_f32 v[166:167], v[166:167], v[102:103]
	v_pk_mul_f32 v[168:169], v[168:169], v[104:105]
	v_pk_mul_f32 v[170:171], v[170:171], v[98:99]
	v_pk_mul_f32 v[172:173], v[172:173], v[100:101]
	s_mov_b64 s[2:3], -1
	v_cvt_pk_bf16_f32 v98, v166, v167
	v_cvt_pk_bf16_f32 v99, v168, v169
	v_cvt_pk_bf16_f32 v100, v170, v171
	v_cvt_pk_bf16_f32 v101, v172, v173
	global_store_dwordx4 v[148:149], v[98:101], off offset:2048
	v_pk_mul_f32 v[166:167], v[94:95], s[100:101] op_sel_hi:[1,0]
	v_pk_mul_f32 v[168:169], v[96:97], s[100:101] op_sel_hi:[1,0]
	v_pk_mul_f32 v[170:171], v[90:91], s[100:101] op_sel_hi:[1,0]
	v_pk_mul_f32 v[172:173], v[92:93], s[100:101] op_sel_hi:[1,0]
	v_exp_f32_e32 v166, v166
	v_exp_f32_e32 v167, v167
	v_exp_f32_e32 v168, v168
	v_exp_f32_e32 v169, v169
	v_exp_f32_e32 v170, v170
	v_exp_f32_e32 v171, v171
	v_exp_f32_e32 v172, v172
	v_exp_f32_e32 v173, v173
	v_pk_add_f32 v[166:167], v[166:167], 1.0 op_sel_hi:[1,0]
	v_pk_add_f32 v[168:169], v[168:169], 1.0 op_sel_hi:[1,0]
	v_pk_add_f32 v[170:171], v[170:171], 1.0 op_sel_hi:[1,0]
	v_pk_add_f32 v[172:173], v[172:173], 1.0 op_sel_hi:[1,0]
	v_rcp_f32_e32 v166, v166
	v_rcp_f32_e32 v167, v167
	v_rcp_f32_e32 v168, v168
	v_rcp_f32_e32 v169, v169
	v_rcp_f32_e32 v170, v170
	v_rcp_f32_e32 v171, v171
	v_rcp_f32_e32 v172, v172
	v_rcp_f32_e32 v173, v173
	v_pk_mul_f32 v[166:167], v[94:95], v[166:167]
	v_pk_mul_f32 v[168:169], v[96:97], v[168:169]
	v_pk_mul_f32 v[170:171], v[90:91], v[170:171]
	v_pk_mul_f32 v[172:173], v[92:93], v[172:173]
	v_pk_mul_f32 v[166:167], v[166:167], v[86:87]
	v_pk_mul_f32 v[168:169], v[168:169], v[88:89]
	v_pk_mul_f32 v[170:171], v[170:171], v[82:83]
	v_pk_mul_f32 v[172:173], v[172:173], v[84:85]
	v_add_co_u32_e32 v86, vcc, s44, v148
	s_nop 1
	v_addc_co_u32_e32 v87, vcc, 0, v149, vcc
	v_cvt_pk_bf16_f32 v82, v166, v167
	v_cvt_pk_bf16_f32 v83, v168, v169
	v_cvt_pk_bf16_f32 v84, v170, v171
	v_cvt_pk_bf16_f32 v85, v172, v173
	global_store_dwordx4 v[86:87], v[82:85], off
	v_pk_mul_f32 v[166:167], v[78:79], s[100:101] op_sel_hi:[1,0]
	v_pk_mul_f32 v[168:169], v[80:81], s[100:101] op_sel_hi:[1,0]
	v_pk_mul_f32 v[170:171], v[74:75], s[100:101] op_sel_hi:[1,0]
	v_pk_mul_f32 v[172:173], v[76:77], s[100:101] op_sel_hi:[1,0]
	v_exp_f32_e32 v166, v166
	v_exp_f32_e32 v167, v167
	v_exp_f32_e32 v168, v168
	v_exp_f32_e32 v169, v169
	v_exp_f32_e32 v170, v170
	v_exp_f32_e32 v171, v171
	v_exp_f32_e32 v172, v172
	v_exp_f32_e32 v173, v173
	v_pk_add_f32 v[166:167], v[166:167], 1.0 op_sel_hi:[1,0]
	v_pk_add_f32 v[168:169], v[168:169], 1.0 op_sel_hi:[1,0]
	v_pk_add_f32 v[170:171], v[170:171], 1.0 op_sel_hi:[1,0]
	v_pk_add_f32 v[172:173], v[172:173], 1.0 op_sel_hi:[1,0]
	v_rcp_f32_e32 v166, v166
	v_rcp_f32_e32 v167, v167
	v_rcp_f32_e32 v168, v168
	v_rcp_f32_e32 v169, v169
	v_rcp_f32_e32 v170, v170
	v_rcp_f32_e32 v171, v171
	v_rcp_f32_e32 v172, v172
	v_rcp_f32_e32 v173, v173
	v_pk_mul_f32 v[166:167], v[78:79], v[166:167]
	v_pk_mul_f32 v[168:169], v[80:81], v[168:169]
	v_pk_mul_f32 v[170:171], v[74:75], v[170:171]
	v_pk_mul_f32 v[172:173], v[76:77], v[172:173]
	v_pk_mul_f32 v[166:167], v[166:167], v[70:71]
	v_pk_mul_f32 v[168:169], v[168:169], v[72:73]
	v_pk_mul_f32 v[170:171], v[170:171], v[66:67]
	v_pk_mul_f32 v[172:173], v[172:173], v[68:69]
	v_cvt_pk_bf16_f32 v66, v166, v167
	v_cvt_pk_bf16_f32 v67, v168, v169
	v_cvt_pk_bf16_f32 v68, v170, v171
	v_cvt_pk_bf16_f32 v69, v172, v173
	global_store_dwordx4 v[86:87], v[66:69], off offset:2048
	v_pk_mul_f32 v[166:167], v[62:63], s[100:101] op_sel_hi:[1,0]
	v_pk_mul_f32 v[168:169], v[64:65], s[100:101] op_sel_hi:[1,0]
	v_pk_mul_f32 v[170:171], v[58:59], s[100:101] op_sel_hi:[1,0]
	v_pk_mul_f32 v[172:173], v[60:61], s[100:101] op_sel_hi:[1,0]
	v_exp_f32_e32 v166, v166
	v_exp_f32_e32 v167, v167
	v_exp_f32_e32 v168, v168
	v_exp_f32_e32 v169, v169
	v_exp_f32_e32 v170, v170
	v_exp_f32_e32 v171, v171
	v_exp_f32_e32 v172, v172
	v_exp_f32_e32 v173, v173
	v_pk_add_f32 v[166:167], v[166:167], 1.0 op_sel_hi:[1,0]
	v_pk_add_f32 v[168:169], v[168:169], 1.0 op_sel_hi:[1,0]
	v_pk_add_f32 v[170:171], v[170:171], 1.0 op_sel_hi:[1,0]
	v_pk_add_f32 v[172:173], v[172:173], 1.0 op_sel_hi:[1,0]
	v_rcp_f32_e32 v166, v166
	v_rcp_f32_e32 v167, v167
	v_rcp_f32_e32 v168, v168
	v_rcp_f32_e32 v169, v169
	v_rcp_f32_e32 v170, v170
	v_rcp_f32_e32 v171, v171
	v_rcp_f32_e32 v172, v172
	v_rcp_f32_e32 v173, v173
	v_pk_mul_f32 v[166:167], v[62:63], v[166:167]
	v_pk_mul_f32 v[168:169], v[64:65], v[168:169]
	v_pk_mul_f32 v[170:171], v[58:59], v[170:171]
	v_pk_mul_f32 v[172:173], v[60:61], v[172:173]
	v_pk_mul_f32 v[166:167], v[166:167], v[54:55]
	v_pk_mul_f32 v[168:169], v[168:169], v[56:57]
	v_pk_mul_f32 v[170:171], v[170:171], v[50:51]
	v_pk_mul_f32 v[172:173], v[172:173], v[52:53]
	v_add_co_u32_e32 v54, vcc, s38, v148
	s_nop 1
	v_addc_co_u32_e32 v55, vcc, 0, v149, vcc
	v_add_co_u32_e32 v56, vcc, s45, v148
	s_nop 0
	s_nop 1
	v_addc_co_u32_e32 v57, vcc, 0, v149, vcc
	v_cvt_pk_bf16_f32 v50, v166, v167
	v_cvt_pk_bf16_f32 v51, v168, v169
	v_cvt_pk_bf16_f32 v52, v170, v171
	v_cvt_pk_bf16_f32 v53, v172, v173
	global_store_dwordx4 v[56:57], v[50:53], off offset:-4096
	v_pk_mul_f32 v[166:167], v[46:47], s[100:101] op_sel_hi:[1,0]
	v_pk_mul_f32 v[168:169], v[48:49], s[100:101] op_sel_hi:[1,0]
	v_pk_mul_f32 v[170:171], v[42:43], s[100:101] op_sel_hi:[1,0]
	v_pk_mul_f32 v[172:173], v[44:45], s[100:101] op_sel_hi:[1,0]
	v_exp_f32_e32 v166, v166
	v_exp_f32_e32 v167, v167
	v_exp_f32_e32 v168, v168
	v_exp_f32_e32 v169, v169
	v_exp_f32_e32 v170, v170
	v_exp_f32_e32 v171, v171
	v_exp_f32_e32 v172, v172
	v_exp_f32_e32 v173, v173
	v_pk_add_f32 v[166:167], v[166:167], 1.0 op_sel_hi:[1,0]
	v_pk_add_f32 v[168:169], v[168:169], 1.0 op_sel_hi:[1,0]
	v_pk_add_f32 v[170:171], v[170:171], 1.0 op_sel_hi:[1,0]
	v_pk_add_f32 v[172:173], v[172:173], 1.0 op_sel_hi:[1,0]
	v_rcp_f32_e32 v166, v166
	v_rcp_f32_e32 v167, v167
	v_rcp_f32_e32 v168, v168
	v_rcp_f32_e32 v169, v169
	v_rcp_f32_e32 v170, v170
	v_rcp_f32_e32 v171, v171
	v_rcp_f32_e32 v172, v172
	v_rcp_f32_e32 v173, v173
	v_pk_mul_f32 v[166:167], v[46:47], v[166:167]
	v_pk_mul_f32 v[168:169], v[48:49], v[168:169]
	v_pk_mul_f32 v[170:171], v[42:43], v[170:171]
	v_pk_mul_f32 v[172:173], v[44:45], v[172:173]
	v_pk_mul_f32 v[166:167], v[166:167], v[38:39]
	v_pk_mul_f32 v[168:169], v[168:169], v[40:41]
	v_pk_mul_f32 v[170:171], v[170:171], v[34:35]
	v_pk_mul_f32 v[172:173], v[172:173], v[36:37]
	s_andn2_b64 vcc, exec, s[18:19]
	v_cvt_pk_bf16_f32 v34, v166, v167
	v_cvt_pk_bf16_f32 v35, v168, v169
	v_cvt_pk_bf16_f32 v36, v170, v171
	v_cvt_pk_bf16_f32 v37, v172, v173
	global_store_dwordx4 v[54:55], v[34:37], off offset:2048
	v_pk_mul_f32 v[166:167], v[30:31], s[100:101] op_sel_hi:[1,0]
	v_pk_mul_f32 v[168:169], v[32:33], s[100:101] op_sel_hi:[1,0]
	v_pk_mul_f32 v[170:171], v[26:27], s[100:101] op_sel_hi:[1,0]
	v_pk_mul_f32 v[172:173], v[28:29], s[100:101] op_sel_hi:[1,0]
	v_exp_f32_e32 v166, v166
	v_exp_f32_e32 v167, v167
	v_exp_f32_e32 v168, v168
	v_exp_f32_e32 v169, v169
	v_exp_f32_e32 v170, v170
	v_exp_f32_e32 v171, v171
	v_exp_f32_e32 v172, v172
	v_exp_f32_e32 v173, v173
	v_pk_add_f32 v[166:167], v[166:167], 1.0 op_sel_hi:[1,0]
	v_pk_add_f32 v[168:169], v[168:169], 1.0 op_sel_hi:[1,0]
	v_pk_add_f32 v[170:171], v[170:171], 1.0 op_sel_hi:[1,0]
	v_pk_add_f32 v[172:173], v[172:173], 1.0 op_sel_hi:[1,0]
	v_rcp_f32_e32 v166, v166
	v_rcp_f32_e32 v167, v167
	v_rcp_f32_e32 v168, v168
	v_rcp_f32_e32 v169, v169
	v_rcp_f32_e32 v170, v170
	v_rcp_f32_e32 v171, v171
	v_rcp_f32_e32 v172, v172
	v_rcp_f32_e32 v173, v173
	v_pk_mul_f32 v[166:167], v[30:31], v[166:167]
	v_pk_mul_f32 v[168:169], v[32:33], v[168:169]
	v_pk_mul_f32 v[170:171], v[26:27], v[170:171]
	v_pk_mul_f32 v[172:173], v[28:29], v[172:173]
	v_pk_mul_f32 v[166:167], v[166:167], v[22:23]
	v_pk_mul_f32 v[168:169], v[168:169], v[24:25]
	v_pk_mul_f32 v[170:171], v[170:171], v[18:19]
	v_pk_mul_f32 v[172:173], v[172:173], v[20:21]
	v_cvt_pk_bf16_f32 v18, v166, v167
	v_cvt_pk_bf16_f32 v19, v168, v169
	v_cvt_pk_bf16_f32 v20, v170, v171
	v_cvt_pk_bf16_f32 v21, v172, v173
	global_store_dwordx4 v[56:57], v[18:21], off
	v_pk_mul_f32 v[166:167], v[14:15], s[100:101] op_sel_hi:[1,0]
	v_pk_mul_f32 v[168:169], v[16:17], s[100:101] op_sel_hi:[1,0]
	v_pk_mul_f32 v[170:171], v[10:11], s[100:101] op_sel_hi:[1,0]
	v_pk_mul_f32 v[172:173], v[12:13], s[100:101] op_sel_hi:[1,0]
	v_exp_f32_e32 v166, v166
	v_exp_f32_e32 v167, v167
	v_exp_f32_e32 v168, v168
	v_exp_f32_e32 v169, v169
	v_exp_f32_e32 v170, v170
	v_exp_f32_e32 v171, v171
	v_exp_f32_e32 v172, v172
	v_exp_f32_e32 v173, v173
	v_pk_add_f32 v[166:167], v[166:167], 1.0 op_sel_hi:[1,0]
	v_pk_add_f32 v[168:169], v[168:169], 1.0 op_sel_hi:[1,0]
	v_pk_add_f32 v[170:171], v[170:171], 1.0 op_sel_hi:[1,0]
	v_pk_add_f32 v[172:173], v[172:173], 1.0 op_sel_hi:[1,0]
	v_rcp_f32_e32 v166, v166
	v_rcp_f32_e32 v167, v167
	v_rcp_f32_e32 v168, v168
	v_rcp_f32_e32 v169, v169
	v_rcp_f32_e32 v170, v170
	v_rcp_f32_e32 v171, v171
	v_rcp_f32_e32 v172, v172
	v_rcp_f32_e32 v173, v173
	v_pk_mul_f32 v[166:167], v[14:15], v[166:167]
	v_pk_mul_f32 v[168:169], v[16:17], v[168:169]
	v_pk_mul_f32 v[170:171], v[10:11], v[170:171]
	v_pk_mul_f32 v[172:173], v[12:13], v[172:173]
	v_pk_mul_f32 v[166:167], v[166:167], v[6:7]
	v_pk_mul_f32 v[168:169], v[168:169], v[8:9]
	v_pk_mul_f32 v[170:171], v[170:171], v[2:3]
	v_pk_mul_f32 v[172:173], v[172:173], v[4:5]
	v_cvt_pk_bf16_f32 v2, v166, v167
	v_cvt_pk_bf16_f32 v3, v168, v169
	v_cvt_pk_bf16_f32 v4, v170, v171
	v_cvt_pk_bf16_f32 v5, v172, v173
	global_store_dwordx4 v[56:57], v[2:5], off offset:2048
	s_cbranch_vccnz .LBB0_1298
	s_andn2_b64 vcc, exec, s[0:1]
	s_cbranch_vccnz .LBB0_1297
	s_branch .LBB0_1297
